# v31 + MFMA-segment slot trimming in all 8-phase loops: duplicate lgkmcnt(0) after s_setprio 1 deleted, s_setprio 0 moved after the segment-closing s_barrier; bit-identical
# speedup vs baseline: 1.0248x; 1.0101x over previous
; #define PG8_WAIT_L(n) asm volatile("s_waitcnt lgkmcnt(" #n ")" ::: "memory")
; #define PG8_BAR __builtin_amdgcn_s_barrier()
; #define PG8_SCHED __builtin_amdgcn_sched_barrier(0)
; template <class Epi, class AddrA, class AddrB>
; __device__ __forceinline__ void gemm_phase(const Sched S, const int lda, const int ldb, const int K, const AddrA addrA,
;                                            const AddrB addrB, const Epi E) {
;     ...
;     const bool has_next = S.next(ui + 1, nxt);
;     const char* nA = has_next ? addrA(nxt) : cA;
;     const char* nB = has_next ? addrB(nxt) : cB;
;     for (int t = 0; t < nt; t += 2) {
;       const bool last = (t == nt - 2);
;       const char* a1 = cA + (size_t)(t + 1) * kstep;
;       const char* a2 = last ? nA : cA + (size_t)(t + 2) * kstep;
;       const char* b2 = last ? nB : cB + (size_t)(t + 2) * kstep;
;       const char* a3 = a2 + kstep;
;       const char* b3 = b2 + kstep;
;       PG8_LDB(B0, 0, 0); PG8_SCHED; PG8_LDA(At, 0, 0); PG8_STAGE(PG8_SA(1, 1), a1 + hstepA, voffA);
;       PG8_WAIT_L(8); PG8_BAR; PG8_WAIT_L(0); PG8_MMA(0, 0, At, B0); PG8_BAR; PG8_SCHED;
;       PG8_LDB(B1, 0, 1); PG8_STAGE(PG8_SB(0, 0), b2, voffB);
;       PG8_BAR; PG8_WAIT_L(0); PG8_MMA(0, 1, At, B1); PG8_BAR;
;       PG8_LDA(At, 0, 1); PG8_STAGE(PG8_SA(0, 0), a2, voffA);
;       PG8_BAR; PG8_WAIT_L(0); PG8_MMA(1, 0, At, B0); PG8_BAR; PG8_SCHED;
.LBB0_108:
	s_ashr_i32 s1, s0, 31
	s_lshl_b64 s[6:7], s[0:1], 20
	s_add_u32 s6, s20, s6
	s_addc_u32 s7, s21, s7
	s_and_b64 s[8:9], s[16:17], exec
	s_cselect_b32 s1, s7, s15
	s_cselect_b32 s11, s6, s14
	s_ashr_i32 s3, s2, 31
	s_lshl_b64 s[8:9], s[2:3], 20
	s_add_u32 s8, s22, s8
	s_addc_u32 s9, s23, s9
	s_and_b64 s[16:17], s[16:17], exec
	s_cselect_b32 s3, s9, s13
	s_cselect_b32 s36, s8, s12
	s_add_u32 s37, s12, 0x100
	s_addc_u32 s38, s13, 0
	s_add_u32 s12, s14, 0x80080
	s_addc_u32 s13, s15, 0
	s_mov_b32 s39, -2
	s_add_u32 s14, s12, 0xfff80080
	s_addc_u32 s15, s13, -1
	s_add_i32 s40, 0, 0x10000
	v_add_u32_e32 v142, s40, v145
	ds_read_b128 v[148:151], v142
	ds_read_b128 v[152:155], v142 offset:1024
	ds_read_b128 v[156:159], v142 offset:2048
	ds_read_b128 v[160:163], v142 offset:3072
	s_cmp_eq_u32 s39, 28
	s_cselect_b32 s17, s1, s15
	s_cselect_b32 s16, s11, s14
	s_cselect_b32 s15, s3, s38
	s_cselect_b32 s14, s36, s37
	v_lshl_add_u64 v[142:143], s[12:13], 0, v[140:141]
	s_add_i32 m0, s24, 0xc000
	ds_read_b128 v[168:171], v146
	ds_read_b128 v[172:175], v146 offset:1024
	ds_read_b128 v[176:179], v146 offset:2048
	ds_read_b128 v[180:183], v146 offset:3072
	ds_read_b128 v[184:187], v146 offset:4096
	ds_read_b128 v[188:191], v146 offset:5120
	ds_read_b128 v[192:195], v146 offset:6144
	ds_read_b128 v[212:215], v146 offset:7168
	global_load_lds_dwordx4 v[142:143], off
	v_lshl_add_u64 v[142:143], s[12:13], 0, v[138:139]
	s_add_i32 m0, s24, 0xe000
	s_nop 0
	global_load_lds_dwordx4 v[142:143], off
	s_waitcnt lgkmcnt(8)
	s_barrier
	s_waitcnt lgkmcnt(0)
	s_setprio 1
	v_mfma_f32_16x16x32_bf16 v[128:131], v[148:151], v[168:171], 0
	v_mfma_f32_16x16x32_bf16 v[128:131], v[152:155], v[172:175], v[128:131]
	v_mfma_f32_16x16x32_bf16 v[120:123], v[148:151], v[176:179], 0
	v_mfma_f32_16x16x32_bf16 v[120:123], v[152:155], v[180:183], v[120:123]
	v_mfma_f32_16x16x32_bf16 v[104:107], v[148:151], v[184:187], 0
	v_mfma_f32_16x16x32_bf16 v[104:107], v[152:155], v[188:191], v[104:107]
	v_mfma_f32_16x16x32_bf16 v[88:91], v[148:151], v[192:195], 0
	v_mfma_f32_16x16x32_bf16 v[88:91], v[152:155], v[212:215], v[88:91]
	v_mfma_f32_16x16x32_bf16 v[124:127], v[156:159], v[168:171], 0
	v_mfma_f32_16x16x32_bf16 v[124:127], v[160:163], v[172:175], v[124:127]
	v_mfma_f32_16x16x32_bf16 v[112:115], v[156:159], v[176:179], 0
	v_mfma_f32_16x16x32_bf16 v[112:115], v[160:163], v[180:183], v[112:115]
	v_mfma_f32_16x16x32_bf16 v[96:99], v[156:159], v[184:187], 0
	v_mfma_f32_16x16x32_bf16 v[96:99], v[160:163], v[188:191], v[96:99]
	v_mfma_f32_16x16x32_bf16 v[80:83], v[156:159], v[192:195], 0
	v_mfma_f32_16x16x32_bf16 v[80:83], v[160:163], v[212:215], v[80:83]
	s_barrier
	s_setprio 0
	s_add_i32 s42, 0, 0x14000
	v_add_u32_e32 v142, s42, v145
	s_add_i32 s40, s40, s19
	ds_read_b128 v[216:219], v142
	ds_read_b128 v[220:223], v142 offset:1024
	ds_read_b128 v[224:227], v142 offset:2048
	ds_read_b128 v[228:231], v142 offset:3072
	v_lshl_add_u64 v[142:143], s[14:15], 0, v[134:135]
	s_mov_b32 m0, s40
	v_lshl_add_u64 v[196:197], s[14:15], 0, v[0:1]
	global_load_lds_dwordx4 v[142:143], off
	s_add_i32 m0, s40, 0x2000
	s_nop 0
	global_load_lds_dwordx4 v[196:197], off
	s_barrier
	s_waitcnt lgkmcnt(0)
	s_setprio 1
	v_mfma_f32_16x16x32_bf16 v[116:119], v[216:219], v[168:171], 0
	v_mfma_f32_16x16x32_bf16 v[116:119], v[220:223], v[172:175], v[116:119]
	v_mfma_f32_16x16x32_bf16 v[100:103], v[216:219], v[176:179], 0
	v_mfma_f32_16x16x32_bf16 v[100:103], v[220:223], v[180:183], v[100:103]
	v_mfma_f32_16x16x32_bf16 v[84:87], v[216:219], v[184:187], 0
	v_mfma_f32_16x16x32_bf16 v[84:87], v[220:223], v[188:191], v[84:87]
	v_mfma_f32_16x16x32_bf16 v[72:75], v[216:219], v[192:195], 0
	v_mfma_f32_16x16x32_bf16 v[72:75], v[220:223], v[212:215], v[72:75]
	v_mfma_f32_16x16x32_bf16 v[108:111], v[224:227], v[168:171], 0
	v_mfma_f32_16x16x32_bf16 v[108:111], v[228:231], v[172:175], v[108:111]
	v_mfma_f32_16x16x32_bf16 v[92:95], v[224:227], v[176:179], 0
	v_mfma_f32_16x16x32_bf16 v[92:95], v[228:231], v[180:183], v[92:95]
	v_mfma_f32_16x16x32_bf16 v[76:79], v[224:227], v[184:187], 0
	v_mfma_f32_16x16x32_bf16 v[76:79], v[228:231], v[188:191], v[76:79]
	v_mfma_f32_16x16x32_bf16 v[68:71], v[224:227], v[192:195], 0
	v_mfma_f32_16x16x32_bf16 v[68:71], v[228:231], v[212:215], v[68:71]
	s_mov_b32 m0, s24
	v_lshl_add_u64 v[232:233], s[16:17], 0, v[136:137]
	s_barrier
	s_setprio 0
	ds_read_b128 v[168:171], v146 offset:16384
	ds_read_b128 v[172:175], v146 offset:17408
	ds_read_b128 v[176:179], v146 offset:18432
	ds_read_b128 v[180:183], v146 offset:19456
	ds_read_b128 v[184:187], v146 offset:20480
	ds_read_b128 v[188:191], v146 offset:21504
	ds_read_b128 v[192:195], v146 offset:22528
	ds_read_b128 v[212:215], v146 offset:23552
	global_load_lds_dwordx4 v[232:233], off
	v_lshl_add_u64 v[234:235], s[16:17], 0, v[132:133]
	s_mov_b32 m0, s25
	s_nop 0
	global_load_lds_dwordx4 v[234:235], off
	s_barrier
	s_waitcnt lgkmcnt(0)
	s_setprio 1
	v_mfma_f32_16x16x32_bf16 v[64:67], v[148:151], v[168:171], 0
	v_mfma_f32_16x16x32_bf16 v[64:67], v[152:155], v[172:175], v[64:67]
	v_mfma_f32_16x16x32_bf16 v[56:59], v[148:151], v[176:179], 0
	v_mfma_f32_16x16x32_bf16 v[56:59], v[152:155], v[180:183], v[56:59]
	v_mfma_f32_16x16x32_bf16 v[40:43], v[148:151], v[184:187], 0
	v_mfma_f32_16x16x32_bf16 v[40:43], v[152:155], v[188:191], v[40:43]
	v_mfma_f32_16x16x32_bf16 v[24:27], v[148:151], v[192:195], 0
	v_mfma_f32_16x16x32_bf16 v[24:27], v[152:155], v[212:215], v[24:27]
	v_mfma_f32_16x16x32_bf16 v[60:63], v[156:159], v[168:171], 0
	v_mfma_f32_16x16x32_bf16 v[60:63], v[160:163], v[172:175], v[60:63]
	v_mfma_f32_16x16x32_bf16 v[48:51], v[156:159], v[176:179], 0
	v_mfma_f32_16x16x32_bf16 v[48:51], v[160:163], v[180:183], v[48:51]
	v_mfma_f32_16x16x32_bf16 v[32:35], v[156:159], v[184:187], 0
	v_mfma_f32_16x16x32_bf16 v[32:35], v[160:163], v[188:191], v[32:35]
	v_mfma_f32_16x16x32_bf16 v[16:19], v[156:159], v[192:195], 0
	v_mfma_f32_16x16x32_bf16 v[16:19], v[160:163], v[212:215], v[16:19]
	s_barrier
; #define PG8_WAIT_V(n) asm volatile("s_waitcnt vmcnt(" #n ")" ::: "memory")
; #define PG8_WAIT_L(n) asm volatile("s_waitcnt lgkmcnt(" #n ")" ::: "memory")
; #define PG8_BAR __builtin_amdgcn_s_barrier()
; #define PG8_SCHED __builtin_amdgcn_sched_barrier(0)
; template <class Epi, class AddrA, class AddrB>
; __device__ __forceinline__ void gemm_phase(const Sched S, const int lda, const int ldb, const int K, const AddrA addrA,
;                                            const AddrB addrB, const Epi E) {
;     ...
;       PG8_STAGE(PG8_SB(0, 1), b2 + hstepB, voffB);
;       PG8_WAIT_V(6); PG8_BAR; PG8_MMA(1, 1, At, B1); PG8_BAR;
;       PG8_LDB(B0, 1, 0); PG8_SCHED; PG8_LDA(At, 1, 0); PG8_STAGE(PG8_SA(0, 1), a2 + hstepA, voffA);
;       PG8_WAIT_L(8); PG8_BAR; PG8_WAIT_L(0); PG8_MMA(0, 0, At, B0); PG8_BAR; PG8_SCHED;
;       PG8_LDB(B1, 1, 1); PG8_STAGE(PG8_SB(1, 0), b3, voffB);
;       PG8_BAR; PG8_WAIT_L(0); PG8_MMA(0, 1, At, B1); PG8_BAR;
;       PG8_LDA(At, 1, 1); PG8_STAGE(PG8_SA(1, 0), a3, voffA);
;       PG8_BAR; PG8_WAIT_L(0); PG8_MMA(1, 0, At, B0); PG8_BAR; PG8_SCHED;
	s_setprio 0
	s_add_u32 s40, s14, 0x80000
	s_addc_u32 s41, s15, 0
	s_add_i32 s42, s42, s19
	v_lshl_add_u64 v[148:149], s[40:41], 0, v[134:135]
	s_mov_b32 m0, s42
	s_nop 0
	global_load_lds_dwordx4 v[148:149], off
	v_lshl_add_u64 v[148:149], s[40:41], 0, v[0:1]
	s_add_i32 m0, s42, 0x2000
	s_nop 0
	global_load_lds_dwordx4 v[148:149], off
	s_waitcnt vmcnt(6)
	s_barrier
	s_setprio 1
	v_mfma_f32_16x16x32_bf16 v[52:55], v[216:219], v[168:171], 0
	v_mfma_f32_16x16x32_bf16 v[52:55], v[220:223], v[172:175], v[52:55]
	v_mfma_f32_16x16x32_bf16 v[36:39], v[216:219], v[176:179], 0
	v_mfma_f32_16x16x32_bf16 v[36:39], v[220:223], v[180:183], v[36:39]
	v_mfma_f32_16x16x32_bf16 v[20:23], v[216:219], v[184:187], 0
	v_mfma_f32_16x16x32_bf16 v[20:23], v[220:223], v[188:191], v[20:23]
	v_mfma_f32_16x16x32_bf16 v[8:11], v[216:219], v[192:195], 0
	v_mfma_f32_16x16x32_bf16 v[8:11], v[220:223], v[212:215], v[8:11]
	v_mfma_f32_16x16x32_bf16 v[44:47], v[224:227], v[168:171], 0
	v_mfma_f32_16x16x32_bf16 v[44:47], v[228:231], v[172:175], v[44:47]
	v_mfma_f32_16x16x32_bf16 v[28:31], v[224:227], v[176:179], 0
	v_mfma_f32_16x16x32_bf16 v[28:31], v[228:231], v[180:183], v[28:31]
	v_mfma_f32_16x16x32_bf16 v[12:15], v[224:227], v[184:187], 0
	v_mfma_f32_16x16x32_bf16 v[12:15], v[228:231], v[188:191], v[12:15]
	v_mfma_f32_16x16x32_bf16 v[4:7], v[224:227], v[192:195], 0
	v_mfma_f32_16x16x32_bf16 v[4:7], v[228:231], v[212:215], v[4:7]
	s_add_i32 s40, 0, 0x18000
	v_add_u32_e32 v147, s40, v145
	s_barrier
	s_setprio 0
	ds_read_b128 v[148:151], v147
	ds_read_b128 v[152:155], v147 offset:1024
	ds_read_b128 v[156:159], v147 offset:2048
	ds_read_b128 v[160:163], v147 offset:3072
	s_add_u32 s16, s16, 0x80000
	s_addc_u32 s17, s17, 0
	s_mov_b32 m0, s26
	v_lshl_add_u64 v[216:217], s[16:17], 0, v[136:137]
	ds_read_b128 v[168:171], v146 offset:32768
	ds_read_b128 v[172:175], v146 offset:33792
	ds_read_b128 v[176:179], v146 offset:34816
	ds_read_b128 v[180:183], v146 offset:35840
	ds_read_b128 v[184:187], v146 offset:36864
	ds_read_b128 v[188:191], v146 offset:37888
	ds_read_b128 v[192:195], v146 offset:38912
	ds_read_b128 v[212:215], v146 offset:39936
	global_load_lds_dwordx4 v[216:217], off
	v_lshl_add_u64 v[216:217], s[16:17], 0, v[132:133]
	s_mov_b32 m0, s27
	s_nop 0
	global_load_lds_dwordx4 v[216:217], off
	s_waitcnt lgkmcnt(8)
	s_barrier
	s_waitcnt lgkmcnt(0)
	s_setprio 1
	v_mfma_f32_16x16x32_bf16 v[128:131], v[148:151], v[168:171], v[128:131]
	v_mfma_f32_16x16x32_bf16 v[128:131], v[152:155], v[172:175], v[128:131]
	v_mfma_f32_16x16x32_bf16 v[120:123], v[148:151], v[176:179], v[120:123]
	v_mfma_f32_16x16x32_bf16 v[120:123], v[152:155], v[180:183], v[120:123]
	v_mfma_f32_16x16x32_bf16 v[104:107], v[148:151], v[184:187], v[104:107]
	v_mfma_f32_16x16x32_bf16 v[104:107], v[152:155], v[188:191], v[104:107]
	v_mfma_f32_16x16x32_bf16 v[88:91], v[148:151], v[192:195], v[88:91]
	v_mfma_f32_16x16x32_bf16 v[88:91], v[152:155], v[212:215], v[88:91]
	v_mfma_f32_16x16x32_bf16 v[124:127], v[156:159], v[168:171], v[124:127]
	v_mfma_f32_16x16x32_bf16 v[124:127], v[160:163], v[172:175], v[124:127]
	v_mfma_f32_16x16x32_bf16 v[112:115], v[156:159], v[176:179], v[112:115]
	v_mfma_f32_16x16x32_bf16 v[112:115], v[160:163], v[180:183], v[112:115]
	v_mfma_f32_16x16x32_bf16 v[96:99], v[156:159], v[184:187], v[96:99]
	v_mfma_f32_16x16x32_bf16 v[96:99], v[160:163], v[188:191], v[96:99]
	v_mfma_f32_16x16x32_bf16 v[80:83], v[156:159], v[192:195], v[80:83]
	v_mfma_f32_16x16x32_bf16 v[80:83], v[160:163], v[212:215], v[80:83]
	s_barrier
	s_setprio 0
	s_add_i32 s16, 0, 0x1c000
	s_add_i32 s17, s40, s19
	v_add_u32_e32 v147, s16, v145
	v_lshl_add_u64 v[142:143], v[142:143], 0, s[52:53]
	s_mov_b32 m0, s17
	ds_read_b128 v[216:219], v147
	ds_read_b128 v[220:223], v147 offset:1024
	ds_read_b128 v[224:227], v147 offset:2048
	ds_read_b128 v[228:231], v147 offset:3072
	global_load_lds_dwordx4 v[142:143], off
	v_lshl_add_u64 v[142:143], v[196:197], 0, s[52:53]
	s_add_i32 m0, s17, 0x2000
	s_nop 0
	global_load_lds_dwordx4 v[142:143], off
	s_barrier
	s_waitcnt lgkmcnt(0)
	s_setprio 1
	v_mfma_f32_16x16x32_bf16 v[116:119], v[216:219], v[168:171], v[116:119]
	v_mfma_f32_16x16x32_bf16 v[116:119], v[220:223], v[172:175], v[116:119]
	v_mfma_f32_16x16x32_bf16 v[100:103], v[216:219], v[176:179], v[100:103]
	v_mfma_f32_16x16x32_bf16 v[100:103], v[220:223], v[180:183], v[100:103]
	v_mfma_f32_16x16x32_bf16 v[84:87], v[216:219], v[184:187], v[84:87]
	v_mfma_f32_16x16x32_bf16 v[84:87], v[220:223], v[188:191], v[84:87]
	v_mfma_f32_16x16x32_bf16 v[72:75], v[216:219], v[192:195], v[72:75]
	v_mfma_f32_16x16x32_bf16 v[72:75], v[220:223], v[212:215], v[72:75]
	v_mfma_f32_16x16x32_bf16 v[108:111], v[224:227], v[168:171], v[108:111]
	v_mfma_f32_16x16x32_bf16 v[108:111], v[228:231], v[172:175], v[108:111]
	v_mfma_f32_16x16x32_bf16 v[92:95], v[224:227], v[176:179], v[92:95]
	v_mfma_f32_16x16x32_bf16 v[92:95], v[228:231], v[180:183], v[92:95]
	v_mfma_f32_16x16x32_bf16 v[76:79], v[224:227], v[184:187], v[76:79]
	v_mfma_f32_16x16x32_bf16 v[76:79], v[228:231], v[188:191], v[76:79]
	v_mfma_f32_16x16x32_bf16 v[68:71], v[224:227], v[192:195], v[68:71]
	v_mfma_f32_16x16x32_bf16 v[68:71], v[228:231], v[212:215], v[68:71]
	s_mov_b32 m0, s30
	v_lshl_add_u64 v[142:143], v[232:233], 0, s[52:53]
	s_barrier
	s_setprio 0
	ds_read_b128 v[168:171], v146 offset:49152
	ds_read_b128 v[172:175], v146 offset:50176
	ds_read_b128 v[176:179], v146 offset:51200
	ds_read_b128 v[180:183], v146 offset:52224
	ds_read_b128 v[184:187], v146 offset:53248
	ds_read_b128 v[188:191], v146 offset:54272
	ds_read_b128 v[192:195], v146 offset:55296
	ds_read_b128 v[212:215], v146 offset:56320
	global_load_lds_dwordx4 v[142:143], off
	v_lshl_add_u64 v[142:143], v[234:235], 0, s[52:53]
	s_mov_b32 m0, s31
	s_nop 0
	global_load_lds_dwordx4 v[142:143], off
	s_barrier
; #define PG8_WAIT_L(n) asm volatile("s_waitcnt lgkmcnt(" #n ")" ::: "memory")
; #define PG8_BAR __builtin_amdgcn_s_barrier()
; #define PG8_SCHED __builtin_amdgcn_sched_barrier(0)
; template <class Epi, class AddrA, class AddrB>
; __device__ __forceinline__ void gemm_phase(const Sched S, const int lda, const int ldb, const int K, const AddrA addrA,
;                                            const AddrB addrB, const Epi E) {
;     ...
;     for (int t = 0; t < nt; t += 2) {
;       const bool last = (t == nt - 2);
;       const char* a1 = cA + (size_t)(t + 1) * kstep;
;       const char* a2 = last ? nA : cA + (size_t)(t + 2) * kstep;
;       const char* b2 = last ? nB : cB + (size_t)(t + 2) * kstep;
;       const char* a3 = a2 + kstep;
;       const char* b3 = b2 + kstep;
;       PG8_LDB(B0, 0, 0); PG8_SCHED; PG8_LDA(At, 0, 0); PG8_STAGE(PG8_SA(1, 1), a1 + hstepA, voffA);
;       PG8_WAIT_L(8); PG8_BAR; PG8_WAIT_L(0); PG8_MMA(0, 0, At, B0); PG8_BAR; PG8_SCHED;
;       PG8_LDB(B1, 0, 1); PG8_STAGE(PG8_SB(0, 0), b2, voffB);
;       PG8_BAR; PG8_WAIT_L(0); PG8_MMA(0, 1, At, B1); PG8_BAR;
;       PG8_LDA(At, 0, 1); PG8_STAGE(PG8_SA(0, 0), a2, voffA);
;       PG8_BAR; PG8_WAIT_L(0); PG8_MMA(1, 0, At, B0); PG8_BAR; PG8_SCHED;
	s_waitcnt lgkmcnt(0)
	s_setprio 1
	v_mfma_f32_16x16x32_bf16 v[64:67], v[148:151], v[168:171], v[64:67]
	v_mfma_f32_16x16x32_bf16 v[64:67], v[152:155], v[172:175], v[64:67]
	v_mfma_f32_16x16x32_bf16 v[56:59], v[148:151], v[176:179], v[56:59]
	v_mfma_f32_16x16x32_bf16 v[56:59], v[152:155], v[180:183], v[56:59]
	v_mfma_f32_16x16x32_bf16 v[40:43], v[148:151], v[184:187], v[40:43]
	v_mfma_f32_16x16x32_bf16 v[40:43], v[152:155], v[188:191], v[40:43]
	v_mfma_f32_16x16x32_bf16 v[24:27], v[148:151], v[192:195], v[24:27]
	v_mfma_f32_16x16x32_bf16 v[24:27], v[152:155], v[212:215], v[24:27]
	v_mfma_f32_16x16x32_bf16 v[60:63], v[156:159], v[168:171], v[60:63]
	v_mfma_f32_16x16x32_bf16 v[60:63], v[160:163], v[172:175], v[60:63]
	v_mfma_f32_16x16x32_bf16 v[48:51], v[156:159], v[176:179], v[48:51]
	v_mfma_f32_16x16x32_bf16 v[48:51], v[160:163], v[180:183], v[48:51]
	v_mfma_f32_16x16x32_bf16 v[32:35], v[156:159], v[184:187], v[32:35]
	v_mfma_f32_16x16x32_bf16 v[32:35], v[160:163], v[188:191], v[32:35]
	v_mfma_f32_16x16x32_bf16 v[16:19], v[156:159], v[192:195], v[16:19]
	v_mfma_f32_16x16x32_bf16 v[16:19], v[160:163], v[212:215], v[16:19]
	s_barrier
	s_setprio 0
	s_add_u32 s14, s14, 0x80080
	s_addc_u32 s15, s15, 0
	s_add_i32 s16, s16, s19
	v_lshl_add_u64 v[142:143], s[14:15], 0, v[134:135]
	s_mov_b32 m0, s16
	s_nop 0
	global_load_lds_dwordx4 v[142:143], off
	v_lshl_add_u64 v[142:143], s[14:15], 0, v[0:1]
	s_add_i32 m0, s16, 0x2000
	s_nop 0
	global_load_lds_dwordx4 v[142:143], off
	s_waitcnt vmcnt(6)
	s_barrier
	s_setprio 1
	v_mfma_f32_16x16x32_bf16 v[52:55], v[216:219], v[168:171], v[52:55]
	v_mfma_f32_16x16x32_bf16 v[52:55], v[220:223], v[172:175], v[52:55]
	v_mfma_f32_16x16x32_bf16 v[36:39], v[216:219], v[176:179], v[36:39]
	v_mfma_f32_16x16x32_bf16 v[36:39], v[220:223], v[180:183], v[36:39]
	v_mfma_f32_16x16x32_bf16 v[20:23], v[216:219], v[184:187], v[20:23]
	v_mfma_f32_16x16x32_bf16 v[20:23], v[220:223], v[188:191], v[20:23]
	v_mfma_f32_16x16x32_bf16 v[8:11], v[216:219], v[192:195], v[8:11]
	v_mfma_f32_16x16x32_bf16 v[8:11], v[220:223], v[212:215], v[8:11]
	v_mfma_f32_16x16x32_bf16 v[44:47], v[224:227], v[168:171], v[44:47]
	v_mfma_f32_16x16x32_bf16 v[44:47], v[228:231], v[172:175], v[44:47]
	v_mfma_f32_16x16x32_bf16 v[28:31], v[224:227], v[176:179], v[28:31]
	v_mfma_f32_16x16x32_bf16 v[28:31], v[228:231], v[180:183], v[28:31]
	v_mfma_f32_16x16x32_bf16 v[12:15], v[224:227], v[184:187], v[12:15]
	v_mfma_f32_16x16x32_bf16 v[12:15], v[228:231], v[188:191], v[12:15]
	v_mfma_f32_16x16x32_bf16 v[4:7], v[224:227], v[192:195], v[4:7]
	v_mfma_f32_16x16x32_bf16 v[4:7], v[228:231], v[212:215], v[4:7]
	s_add_i32 s39, s39, 2
	s_add_u32 s37, s37, 0x100
	s_addc_u32 s38, s38, 0
	s_add_u32 s12, s12, 0x100
	s_addc_u32 s13, s13, 0
	s_cmp_gt_u32 s39, 29
	s_barrier
	s_setprio 0
.LBB0_109:
	s_add_u32 s14, s12, 0xfff80080
	s_addc_u32 s15, s13, -1
	s_add_i32 s40, 0, 0x10000
	v_add_u32_e32 v142, s40, v145
	ds_read_b128 v[148:151], v142
	ds_read_b128 v[152:155], v142 offset:1024
	ds_read_b128 v[156:159], v142 offset:2048
	ds_read_b128 v[160:163], v142 offset:3072
	s_cmp_eq_u32 s39, 28
	s_cselect_b32 s17, s1, s15
	s_cselect_b32 s16, s11, s14
	s_cselect_b32 s15, s3, s38
	s_cselect_b32 s14, s36, s37
	v_lshl_add_u64 v[142:143], s[12:13], 0, v[140:141]
	s_add_i32 m0, s24, 0xc000
	ds_read_b128 v[168:171], v146
	ds_read_b128 v[172:175], v146 offset:1024
	ds_read_b128 v[176:179], v146 offset:2048
	ds_read_b128 v[180:183], v146 offset:3072
	ds_read_b128 v[184:187], v146 offset:4096
	ds_read_b128 v[188:191], v146 offset:5120
	ds_read_b128 v[192:195], v146 offset:6144
	ds_read_b128 v[212:215], v146 offset:7168
	global_load_lds_dwordx4 v[142:143], off
	v_lshl_add_u64 v[142:143], s[12:13], 0, v[138:139]
	s_add_i32 m0, s24, 0xe000
	s_nop 0
	global_load_lds_dwordx4 v[142:143], off
	s_waitcnt lgkmcnt(8)
	s_barrier
	s_waitcnt lgkmcnt(0)
	s_setprio 1
	v_mfma_f32_16x16x32_bf16 v[128:131], v[148:151], v[168:171], v[128:131]
	v_mfma_f32_16x16x32_bf16 v[128:131], v[152:155], v[172:175], v[128:131]
	v_mfma_f32_16x16x32_bf16 v[120:123], v[148:151], v[176:179], v[120:123]
	v_mfma_f32_16x16x32_bf16 v[120:123], v[152:155], v[180:183], v[120:123]
	v_mfma_f32_16x16x32_bf16 v[104:107], v[148:151], v[184:187], v[104:107]
	v_mfma_f32_16x16x32_bf16 v[104:107], v[152:155], v[188:191], v[104:107]
	v_mfma_f32_16x16x32_bf16 v[88:91], v[148:151], v[192:195], v[88:91]
	v_mfma_f32_16x16x32_bf16 v[88:91], v[152:155], v[212:215], v[88:91]
	v_mfma_f32_16x16x32_bf16 v[124:127], v[156:159], v[168:171], v[124:127]
	v_mfma_f32_16x16x32_bf16 v[124:127], v[160:163], v[172:175], v[124:127]
	v_mfma_f32_16x16x32_bf16 v[112:115], v[156:159], v[176:179], v[112:115]
	v_mfma_f32_16x16x32_bf16 v[112:115], v[160:163], v[180:183], v[112:115]
	v_mfma_f32_16x16x32_bf16 v[96:99], v[156:159], v[184:187], v[96:99]
	v_mfma_f32_16x16x32_bf16 v[96:99], v[160:163], v[188:191], v[96:99]
	v_mfma_f32_16x16x32_bf16 v[80:83], v[156:159], v[192:195], v[80:83]
	v_mfma_f32_16x16x32_bf16 v[80:83], v[160:163], v[212:215], v[80:83]
	s_barrier
	s_setprio 0
	s_add_i32 s42, 0, 0x14000
	v_add_u32_e32 v142, s42, v145
	s_add_i32 s40, s40, s19
	ds_read_b128 v[216:219], v142
	ds_read_b128 v[220:223], v142 offset:1024
	ds_read_b128 v[224:227], v142 offset:2048
	ds_read_b128 v[228:231], v142 offset:3072
	v_lshl_add_u64 v[142:143], s[14:15], 0, v[134:135]
	s_mov_b32 m0, s40
	v_lshl_add_u64 v[196:197], s[14:15], 0, v[0:1]
	global_load_lds_dwordx4 v[142:143], off
	s_add_i32 m0, s40, 0x2000
	s_nop 0
	global_load_lds_dwordx4 v[196:197], off
	s_barrier
; #define PG8_WAIT_V(n) asm volatile("s_waitcnt vmcnt(" #n ")" ::: "memory")
; #define PG8_WAIT_L(n) asm volatile("s_waitcnt lgkmcnt(" #n ")" ::: "memory")
; #define PG8_BAR __builtin_amdgcn_s_barrier()
; #define PG8_SCHED __builtin_amdgcn_sched_barrier(0)
; template <class Epi, class AddrA, class AddrB>
; __device__ __forceinline__ void gemm_phase(const Sched S, const int lda, const int ldb, const int K, const AddrA addrA,
;                                            const AddrB addrB, const Epi E) {
;     ...
;       PG8_WAIT_L(8); PG8_BAR; PG8_WAIT_L(0); PG8_MMA(0, 0, At, B0); PG8_BAR; PG8_SCHED;
;       PG8_LDB(B1, 0, 1); PG8_STAGE(PG8_SB(0, 0), b2, voffB);
;       PG8_BAR; PG8_WAIT_L(0); PG8_MMA(0, 1, At, B1); PG8_BAR;
;       PG8_LDA(At, 0, 1); PG8_STAGE(PG8_SA(0, 0), a2, voffA);
;       PG8_BAR; PG8_WAIT_L(0); PG8_MMA(1, 0, At, B0); PG8_BAR; PG8_SCHED;
;       PG8_STAGE(PG8_SB(0, 1), b2 + hstepB, voffB);
;       PG8_WAIT_V(6); PG8_BAR; PG8_MMA(1, 1, At, B1); PG8_BAR;
;       PG8_LDB(B0, 1, 0); PG8_SCHED; PG8_LDA(At, 1, 0); PG8_STAGE(PG8_SA(0, 1), a2 + hstepA, voffA);
;       PG8_WAIT_L(8); PG8_BAR; PG8_WAIT_L(0); PG8_MMA(0, 0, At, B0); PG8_BAR; PG8_SCHED;
	s_waitcnt lgkmcnt(0)
	s_setprio 1
	v_mfma_f32_16x16x32_bf16 v[116:119], v[216:219], v[168:171], v[116:119]
	v_mfma_f32_16x16x32_bf16 v[116:119], v[220:223], v[172:175], v[116:119]
	v_mfma_f32_16x16x32_bf16 v[100:103], v[216:219], v[176:179], v[100:103]
	v_mfma_f32_16x16x32_bf16 v[100:103], v[220:223], v[180:183], v[100:103]
	v_mfma_f32_16x16x32_bf16 v[84:87], v[216:219], v[184:187], v[84:87]
	v_mfma_f32_16x16x32_bf16 v[84:87], v[220:223], v[188:191], v[84:87]
	v_mfma_f32_16x16x32_bf16 v[72:75], v[216:219], v[192:195], v[72:75]
	v_mfma_f32_16x16x32_bf16 v[72:75], v[220:223], v[212:215], v[72:75]
	v_mfma_f32_16x16x32_bf16 v[108:111], v[224:227], v[168:171], v[108:111]
	v_mfma_f32_16x16x32_bf16 v[108:111], v[228:231], v[172:175], v[108:111]
	v_mfma_f32_16x16x32_bf16 v[92:95], v[224:227], v[176:179], v[92:95]
	v_mfma_f32_16x16x32_bf16 v[92:95], v[228:231], v[180:183], v[92:95]
	v_mfma_f32_16x16x32_bf16 v[76:79], v[224:227], v[184:187], v[76:79]
	v_mfma_f32_16x16x32_bf16 v[76:79], v[228:231], v[188:191], v[76:79]
	v_mfma_f32_16x16x32_bf16 v[68:71], v[224:227], v[192:195], v[68:71]
	v_mfma_f32_16x16x32_bf16 v[68:71], v[228:231], v[212:215], v[68:71]
	s_mov_b32 m0, s24
	v_lshl_add_u64 v[232:233], s[16:17], 0, v[136:137]
	s_barrier
	s_setprio 0
	ds_read_b128 v[168:171], v146 offset:16384
	ds_read_b128 v[172:175], v146 offset:17408
	ds_read_b128 v[176:179], v146 offset:18432
	ds_read_b128 v[180:183], v146 offset:19456
	ds_read_b128 v[184:187], v146 offset:20480
	ds_read_b128 v[188:191], v146 offset:21504
	ds_read_b128 v[192:195], v146 offset:22528
	ds_read_b128 v[212:215], v146 offset:23552
	global_load_lds_dwordx4 v[232:233], off
	v_lshl_add_u64 v[234:235], s[16:17], 0, v[132:133]
	s_mov_b32 m0, s25
	s_nop 0
	global_load_lds_dwordx4 v[234:235], off
	s_barrier
	s_waitcnt lgkmcnt(0)
	s_setprio 1
	v_mfma_f32_16x16x32_bf16 v[64:67], v[148:151], v[168:171], v[64:67]
	v_mfma_f32_16x16x32_bf16 v[64:67], v[152:155], v[172:175], v[64:67]
	v_mfma_f32_16x16x32_bf16 v[56:59], v[148:151], v[176:179], v[56:59]
	v_mfma_f32_16x16x32_bf16 v[56:59], v[152:155], v[180:183], v[56:59]
	v_mfma_f32_16x16x32_bf16 v[40:43], v[148:151], v[184:187], v[40:43]
	v_mfma_f32_16x16x32_bf16 v[40:43], v[152:155], v[188:191], v[40:43]
	v_mfma_f32_16x16x32_bf16 v[24:27], v[148:151], v[192:195], v[24:27]
	v_mfma_f32_16x16x32_bf16 v[24:27], v[152:155], v[212:215], v[24:27]
	v_mfma_f32_16x16x32_bf16 v[60:63], v[156:159], v[168:171], v[60:63]
	v_mfma_f32_16x16x32_bf16 v[60:63], v[160:163], v[172:175], v[60:63]
	v_mfma_f32_16x16x32_bf16 v[48:51], v[156:159], v[176:179], v[48:51]
	v_mfma_f32_16x16x32_bf16 v[48:51], v[160:163], v[180:183], v[48:51]
	v_mfma_f32_16x16x32_bf16 v[32:35], v[156:159], v[184:187], v[32:35]
	v_mfma_f32_16x16x32_bf16 v[32:35], v[160:163], v[188:191], v[32:35]
	v_mfma_f32_16x16x32_bf16 v[16:19], v[156:159], v[192:195], v[16:19]
	v_mfma_f32_16x16x32_bf16 v[16:19], v[160:163], v[212:215], v[16:19]
	s_barrier
	s_setprio 0
	s_add_u32 s40, s14, 0x80000
	s_addc_u32 s41, s15, 0
	s_add_i32 s42, s42, s19
	v_lshl_add_u64 v[148:149], s[40:41], 0, v[134:135]
	s_mov_b32 m0, s42
	s_nop 0
	global_load_lds_dwordx4 v[148:149], off
	v_lshl_add_u64 v[148:149], s[40:41], 0, v[0:1]
	s_add_i32 m0, s42, 0x2000
	s_nop 0
	global_load_lds_dwordx4 v[148:149], off
	s_waitcnt vmcnt(6)
	s_barrier
	s_setprio 1
	v_mfma_f32_16x16x32_bf16 v[52:55], v[216:219], v[168:171], v[52:55]
	v_mfma_f32_16x16x32_bf16 v[52:55], v[220:223], v[172:175], v[52:55]
	v_mfma_f32_16x16x32_bf16 v[36:39], v[216:219], v[176:179], v[36:39]
	v_mfma_f32_16x16x32_bf16 v[36:39], v[220:223], v[180:183], v[36:39]
	v_mfma_f32_16x16x32_bf16 v[20:23], v[216:219], v[184:187], v[20:23]
	v_mfma_f32_16x16x32_bf16 v[20:23], v[220:223], v[188:191], v[20:23]
	v_mfma_f32_16x16x32_bf16 v[8:11], v[216:219], v[192:195], v[8:11]
	v_mfma_f32_16x16x32_bf16 v[8:11], v[220:223], v[212:215], v[8:11]
	v_mfma_f32_16x16x32_bf16 v[44:47], v[224:227], v[168:171], v[44:47]
	v_mfma_f32_16x16x32_bf16 v[44:47], v[228:231], v[172:175], v[44:47]
	v_mfma_f32_16x16x32_bf16 v[28:31], v[224:227], v[176:179], v[28:31]
	v_mfma_f32_16x16x32_bf16 v[28:31], v[228:231], v[180:183], v[28:31]
	v_mfma_f32_16x16x32_bf16 v[12:15], v[224:227], v[184:187], v[12:15]
	v_mfma_f32_16x16x32_bf16 v[12:15], v[228:231], v[188:191], v[12:15]
	v_mfma_f32_16x16x32_bf16 v[4:7], v[224:227], v[192:195], v[4:7]
	v_mfma_f32_16x16x32_bf16 v[4:7], v[228:231], v[212:215], v[4:7]
	s_add_i32 s40, 0, 0x18000
	v_add_u32_e32 v147, s40, v145
	s_barrier
	s_setprio 0
	ds_read_b128 v[148:151], v147
	ds_read_b128 v[152:155], v147 offset:1024
	ds_read_b128 v[156:159], v147 offset:2048
	ds_read_b128 v[160:163], v147 offset:3072
	s_add_u32 s16, s16, 0x80000
	s_addc_u32 s17, s17, 0
	s_mov_b32 m0, s26
	v_lshl_add_u64 v[216:217], s[16:17], 0, v[136:137]
	ds_read_b128 v[168:171], v146 offset:32768
	ds_read_b128 v[172:175], v146 offset:33792
	ds_read_b128 v[176:179], v146 offset:34816
	ds_read_b128 v[180:183], v146 offset:35840
	ds_read_b128 v[184:187], v146 offset:36864
	ds_read_b128 v[188:191], v146 offset:37888
	ds_read_b128 v[192:195], v146 offset:38912
	ds_read_b128 v[212:215], v146 offset:39936
	global_load_lds_dwordx4 v[216:217], off
	v_lshl_add_u64 v[216:217], s[16:17], 0, v[132:133]
	s_mov_b32 m0, s27
	s_nop 0
	global_load_lds_dwordx4 v[216:217], off
	s_waitcnt lgkmcnt(8)
	s_barrier
; #define PG8_WAIT_V(n) asm volatile("s_waitcnt vmcnt(" #n ")" ::: "memory")
; #define PG8_WAIT_L(n) asm volatile("s_waitcnt lgkmcnt(" #n ")" ::: "memory")
; #define PG8_BAR __builtin_amdgcn_s_barrier()
; #define PG8_SCHED __builtin_amdgcn_sched_barrier(0)
; template <class Epi, class AddrA, class AddrB>
; __device__ __forceinline__ void gemm_phase(const Sched S, const int lda, const int ldb, const int K, const AddrA addrA,
;                                            const AddrB addrB, const Epi E) {
;     ...
;       PG8_WAIT_L(8); PG8_BAR; PG8_WAIT_L(0); PG8_MMA(0, 0, At, B0); PG8_BAR; PG8_SCHED;
;       PG8_LDB(B1, 1, 1); PG8_STAGE(PG8_SB(1, 0), b3, voffB);
;       PG8_BAR; PG8_WAIT_L(0); PG8_MMA(0, 1, At, B1); PG8_BAR;
;       PG8_LDA(At, 1, 1); PG8_STAGE(PG8_SA(1, 0), a3, voffA);
;       PG8_BAR; PG8_WAIT_L(0); PG8_MMA(1, 0, At, B0); PG8_BAR; PG8_SCHED;
;       PG8_STAGE(PG8_SB(1, 1), b3 + hstepB, voffB);
;       PG8_WAIT_V(6); PG8_BAR; PG8_MMA(1, 1, At, B1); PG8_BAR;
	s_waitcnt lgkmcnt(0)
	s_setprio 1
	v_mfma_f32_16x16x32_bf16 v[128:131], v[148:151], v[168:171], v[128:131]
	v_mfma_f32_16x16x32_bf16 v[128:131], v[152:155], v[172:175], v[128:131]
	v_mfma_f32_16x16x32_bf16 v[120:123], v[148:151], v[176:179], v[120:123]
	v_mfma_f32_16x16x32_bf16 v[120:123], v[152:155], v[180:183], v[120:123]
	v_mfma_f32_16x16x32_bf16 v[104:107], v[148:151], v[184:187], v[104:107]
	v_mfma_f32_16x16x32_bf16 v[104:107], v[152:155], v[188:191], v[104:107]
	v_mfma_f32_16x16x32_bf16 v[88:91], v[148:151], v[192:195], v[88:91]
	v_mfma_f32_16x16x32_bf16 v[88:91], v[152:155], v[212:215], v[88:91]
	v_mfma_f32_16x16x32_bf16 v[124:127], v[156:159], v[168:171], v[124:127]
	v_mfma_f32_16x16x32_bf16 v[124:127], v[160:163], v[172:175], v[124:127]
	v_mfma_f32_16x16x32_bf16 v[112:115], v[156:159], v[176:179], v[112:115]
	v_mfma_f32_16x16x32_bf16 v[112:115], v[160:163], v[180:183], v[112:115]
	v_mfma_f32_16x16x32_bf16 v[96:99], v[156:159], v[184:187], v[96:99]
	v_mfma_f32_16x16x32_bf16 v[96:99], v[160:163], v[188:191], v[96:99]
	v_mfma_f32_16x16x32_bf16 v[80:83], v[156:159], v[192:195], v[80:83]
	v_mfma_f32_16x16x32_bf16 v[80:83], v[160:163], v[212:215], v[80:83]
	s_barrier
	s_setprio 0
	s_add_i32 s16, 0, 0x1c000
	s_add_i32 s17, s40, s19
	v_add_u32_e32 v147, s16, v145
	v_lshl_add_u64 v[142:143], v[142:143], 0, s[52:53]
	s_mov_b32 m0, s17
	ds_read_b128 v[216:219], v147
	ds_read_b128 v[220:223], v147 offset:1024
	ds_read_b128 v[224:227], v147 offset:2048
	ds_read_b128 v[228:231], v147 offset:3072
	global_load_lds_dwordx4 v[142:143], off
	v_lshl_add_u64 v[142:143], v[196:197], 0, s[52:53]
	s_add_i32 m0, s17, 0x2000
	s_nop 0
	global_load_lds_dwordx4 v[142:143], off
	s_barrier
	s_waitcnt lgkmcnt(0)
	s_setprio 1
	v_mfma_f32_16x16x32_bf16 v[116:119], v[216:219], v[168:171], v[116:119]
	v_mfma_f32_16x16x32_bf16 v[116:119], v[220:223], v[172:175], v[116:119]
	v_mfma_f32_16x16x32_bf16 v[100:103], v[216:219], v[176:179], v[100:103]
	v_mfma_f32_16x16x32_bf16 v[100:103], v[220:223], v[180:183], v[100:103]
	v_mfma_f32_16x16x32_bf16 v[84:87], v[216:219], v[184:187], v[84:87]
	v_mfma_f32_16x16x32_bf16 v[84:87], v[220:223], v[188:191], v[84:87]
	v_mfma_f32_16x16x32_bf16 v[72:75], v[216:219], v[192:195], v[72:75]
	v_mfma_f32_16x16x32_bf16 v[72:75], v[220:223], v[212:215], v[72:75]
	v_mfma_f32_16x16x32_bf16 v[108:111], v[224:227], v[168:171], v[108:111]
	v_mfma_f32_16x16x32_bf16 v[108:111], v[228:231], v[172:175], v[108:111]
	v_mfma_f32_16x16x32_bf16 v[92:95], v[224:227], v[176:179], v[92:95]
	v_mfma_f32_16x16x32_bf16 v[92:95], v[228:231], v[180:183], v[92:95]
	v_mfma_f32_16x16x32_bf16 v[76:79], v[224:227], v[184:187], v[76:79]
	v_mfma_f32_16x16x32_bf16 v[76:79], v[228:231], v[188:191], v[76:79]
	v_mfma_f32_16x16x32_bf16 v[68:71], v[224:227], v[192:195], v[68:71]
	v_mfma_f32_16x16x32_bf16 v[68:71], v[228:231], v[212:215], v[68:71]
	s_mov_b32 m0, s30
	v_lshl_add_u64 v[142:143], v[232:233], 0, s[52:53]
	s_barrier
	s_setprio 0
	ds_read_b128 v[168:171], v146 offset:49152
	ds_read_b128 v[172:175], v146 offset:50176
	ds_read_b128 v[176:179], v146 offset:51200
	ds_read_b128 v[180:183], v146 offset:52224
	ds_read_b128 v[184:187], v146 offset:53248
	ds_read_b128 v[188:191], v146 offset:54272
	ds_read_b128 v[192:195], v146 offset:55296
	ds_read_b128 v[212:215], v146 offset:56320
	global_load_lds_dwordx4 v[142:143], off
	v_lshl_add_u64 v[142:143], v[234:235], 0, s[52:53]
	s_mov_b32 m0, s31
	s_nop 0
	global_load_lds_dwordx4 v[142:143], off
	s_barrier
	s_waitcnt lgkmcnt(0)
	s_setprio 1
	v_mfma_f32_16x16x32_bf16 v[64:67], v[148:151], v[168:171], v[64:67]
	v_mfma_f32_16x16x32_bf16 v[64:67], v[152:155], v[172:175], v[64:67]
	v_mfma_f32_16x16x32_bf16 v[56:59], v[148:151], v[176:179], v[56:59]
	v_mfma_f32_16x16x32_bf16 v[56:59], v[152:155], v[180:183], v[56:59]
	v_mfma_f32_16x16x32_bf16 v[40:43], v[148:151], v[184:187], v[40:43]
	v_mfma_f32_16x16x32_bf16 v[40:43], v[152:155], v[188:191], v[40:43]
	v_mfma_f32_16x16x32_bf16 v[24:27], v[148:151], v[192:195], v[24:27]
	v_mfma_f32_16x16x32_bf16 v[24:27], v[152:155], v[212:215], v[24:27]
	v_mfma_f32_16x16x32_bf16 v[60:63], v[156:159], v[168:171], v[60:63]
	v_mfma_f32_16x16x32_bf16 v[60:63], v[160:163], v[172:175], v[60:63]
	v_mfma_f32_16x16x32_bf16 v[48:51], v[156:159], v[176:179], v[48:51]
	v_mfma_f32_16x16x32_bf16 v[48:51], v[160:163], v[180:183], v[48:51]
	v_mfma_f32_16x16x32_bf16 v[32:35], v[156:159], v[184:187], v[32:35]
	v_mfma_f32_16x16x32_bf16 v[32:35], v[160:163], v[188:191], v[32:35]
	v_mfma_f32_16x16x32_bf16 v[16:19], v[156:159], v[192:195], v[16:19]
	v_mfma_f32_16x16x32_bf16 v[16:19], v[160:163], v[212:215], v[16:19]
	s_barrier
	s_setprio 0
	s_add_u32 s14, s14, 0x80080
	s_addc_u32 s15, s15, 0
	s_add_i32 s16, s16, s19
	v_lshl_add_u64 v[142:143], s[14:15], 0, v[134:135]
	s_mov_b32 m0, s16
	s_nop 0
	global_load_lds_dwordx4 v[142:143], off
	v_lshl_add_u64 v[142:143], s[14:15], 0, v[0:1]
	s_add_i32 m0, s16, 0x2000
	s_nop 0
	global_load_lds_dwordx4 v[142:143], off
	s_waitcnt vmcnt(6)
	s_barrier
; #define PG8_WAIT_V(n) asm volatile("s_waitcnt vmcnt(" #n ")" ::: "memory")
; #define PG8_BAR __builtin_amdgcn_s_barrier()
; template <class Epi, class AddrA, class AddrB>
; __device__ __forceinline__ void gemm_phase(const Sched S, const int lda, const int ldb, const int K, const AddrA addrA,
;                                            const AddrB addrB, const Epi E) {
;     ...
;       PG8_WAIT_V(6); PG8_BAR; PG8_MMA(1, 1, At, B1); PG8_BAR;
;     }
;     E(acc, cur, wr, wc, fr, fq);
;     if (!has_next) break;
;     if (!(Epi::KEEP && cur.br + 1 < S.nbr)) {
; #pragma unroll
;       for (int a = 0; a < 2; ++a)
; #pragma unroll
;         for (int b = 0; b < 2; ++b)
; #pragma unroll
;           for (int m = 0; m < 4; ++m)
; #pragma unroll
;             for (int n = 0; n < 2; ++n) acc[a][b][m][n] = (f32x4){0.f, 0.f, 0.f, 0.f};
;     }
;     cur = nxt; cA = nA; cB = nB; ++ui;
;   }
;   PG8_WAIT_V(0);
;   if (wr == 0) PG8_BAR;
;   __device__ __forceinline__ void operator()(EPI_ARGS) const {
;     bf16_t* base = proj + ((size_t)u.pn * MTOK + (size_t)(u.pm * 256 + wr * 64 + fr)) * PLD + wc * 32 + 8 * fq;
; #pragma unroll
;     for (int ai = 0; ai < 2; ++ai)
; #pragma unroll
;       for (int m = 0; m < 4; ++m) {
;         bf16_t* rowp = base + (size_t)(ai * HALF + m * 16) * PLD;
; #pragma unroll
;         for (int bj = 0; bj < 2; ++bj) {
;           const f32x4 v0 = acc[ai][bj][m][0], v1 = acc[ai][bj][m][1];
;           u32x4 o;
;           o.x = pack2(v0[0], v0[1]); o.y = pack2(v0[2], v0[3]); o.z = pack2(v1[0], v1[1]); o.w = pack2(v1[2], v1[3]);
;           *(u32x4*)(rowp + bj * HALF) = o;
;         }
;       }
	s_setprio 1
	v_mfma_f32_16x16x32_bf16 v[52:55], v[216:219], v[168:171], v[52:55]
	v_mfma_f32_16x16x32_bf16 v[52:55], v[220:223], v[172:175], v[52:55]
	v_mfma_f32_16x16x32_bf16 v[36:39], v[216:219], v[176:179], v[36:39]
	v_mfma_f32_16x16x32_bf16 v[36:39], v[220:223], v[180:183], v[36:39]
	v_mfma_f32_16x16x32_bf16 v[20:23], v[216:219], v[184:187], v[20:23]
	v_mfma_f32_16x16x32_bf16 v[20:23], v[220:223], v[188:191], v[20:23]
	v_mfma_f32_16x16x32_bf16 v[8:11], v[216:219], v[192:195], v[8:11]
	v_mfma_f32_16x16x32_bf16 v[8:11], v[220:223], v[212:215], v[8:11]
	v_mfma_f32_16x16x32_bf16 v[44:47], v[224:227], v[168:171], v[44:47]
	v_mfma_f32_16x16x32_bf16 v[44:47], v[228:231], v[172:175], v[44:47]
	v_mfma_f32_16x16x32_bf16 v[28:31], v[224:227], v[176:179], v[28:31]
	v_mfma_f32_16x16x32_bf16 v[28:31], v[228:231], v[180:183], v[28:31]
	v_mfma_f32_16x16x32_bf16 v[12:15], v[224:227], v[184:187], v[12:15]
	v_mfma_f32_16x16x32_bf16 v[12:15], v[228:231], v[188:191], v[12:15]
	v_mfma_f32_16x16x32_bf16 v[4:7], v[224:227], v[192:195], v[4:7]
	v_mfma_f32_16x16x32_bf16 v[4:7], v[228:231], v[212:215], v[4:7]
	s_add_i32 s39, s39, 2
	s_add_u32 s37, s37, 0x100
	s_addc_u32 s38, s38, 0
	s_add_u32 s12, s12, 0x100
	s_addc_u32 s13, s13, 0
	s_cmp_gt_u32 s39, 29
	s_barrier
	s_setprio 0
	s_cbranch_scc0 .LBB0_109
	s_ashr_i32 s11, s10, 31
	v_lshl_add_u32 v142, s35, 8, v144
	s_lshl_b64 s[10:11], s[10:11], 23
	v_ashrrev_i32_e32 v143, 31, v142
	s_add_u32 s10, s28, s10
	s_addc_u32 s11, s29, s11
	v_lshlrev_b64 v[142:143], 9, v[142:143]
	v_lshl_add_u64 v[142:143], s[10:11], 0, v[142:143]
	v_lshl_add_u64 v[142:143], v[142:143], 0, s[72:73]
	v_lshl_add_u64 v[142:143], v[142:143], 0, v[2:3]
	v_cvt_pk_bf16_f32 v116, v116, v117
	v_cvt_pk_bf16_f32 v117, v118, v119
	v_cvt_pk_bf16_f32 v119, v110, v111
	v_cvt_pk_bf16_f32 v110, v112, v113
	v_add_co_u32_e32 v112, vcc, s96, v142
	s_movk_i32 s1, 0x4000
	s_nop 0
	v_addc_co_u32_e32 v113, vcc, 0, v143, vcc
	v_cvt_pk_bf16_f32 v100, v100, v101
	v_cvt_pk_bf16_f32 v101, v102, v103
	v_cvt_pk_bf16_f32 v103, v94, v95
	v_cvt_pk_bf16_f32 v94, v96, v97
	v_add_co_u32_e32 v96, vcc, s1, v142
	s_movk_i32 s1, 0x6000
	s_nop 0
	v_addc_co_u32_e32 v97, vcc, 0, v143, vcc
	v_cvt_pk_bf16_f32 v84, v84, v85
	v_cvt_pk_bf16_f32 v85, v86, v87
	v_cvt_pk_bf16_f32 v87, v78, v79
	v_cvt_pk_bf16_f32 v78, v80, v81
	v_add_co_u32_e32 v80, vcc, s1, v142
	v_cvt_pk_bf16_f32 v64, v64, v65
	v_cvt_pk_bf16_f32 v65, v66, v67
	v_cvt_pk_bf16_f32 v66, v60, v61
	s_mov_b32 s1, 0x12000
	s_nop 0
	v_addc_co_u32_e32 v81, vcc, 0, v143, vcc
	v_add_co_u32_e32 v60, vcc, s67, v142
	v_cvt_pk_bf16_f32 v52, v52, v53
	v_cvt_pk_bf16_f32 v53, v54, v55
	v_cvt_pk_bf16_f32 v55, v46, v47
	v_cvt_pk_bf16_f32 v46, v48, v49
	s_nop 1
	v_addc_co_u32_e32 v61, vcc, 0, v143, vcc
	v_add_co_u32_e32 v48, vcc, s1, v142
	s_mov_b32 s1, 0x14000
	s_nop 0
	v_addc_co_u32_e32 v49, vcc, 0, v143, vcc
	v_cvt_pk_bf16_f32 v36, v36, v37
	v_cvt_pk_bf16_f32 v37, v38, v39
	v_cvt_pk_bf16_f32 v39, v30, v31
	v_cvt_pk_bf16_f32 v30, v32, v33
	v_add_co_u32_e32 v32, vcc, s1, v142
	s_mov_b32 s1, 0x16000
	s_nop 0
	v_addc_co_u32_e32 v33, vcc, 0, v143, vcc
	v_cvt_pk_bf16_f32 v20, v20, v21
	v_cvt_pk_bf16_f32 v21, v22, v23
	v_cvt_pk_bf16_f32 v23, v14, v15
	v_cvt_pk_bf16_f32 v14, v16, v17
	v_add_co_u32_e32 v16, vcc, s1, v142
	s_mov_b32 s10, s2
	s_nop 0
	v_addc_co_u32_e32 v17, vcc, 0, v143, vcc
	s_and_b64 vcc, exec, s[4:5]
	s_mov_b32 s35, s0
	s_mov_b64 s[12:13], s[8:9]
	s_mov_b64 s[14:15], s[6:7]
	v_cvt_pk_bf16_f32 v128, v128, v129
	v_cvt_pk_bf16_f32 v129, v130, v131
	v_cvt_pk_bf16_f32 v130, v124, v125
	v_cvt_pk_bf16_f32 v131, v126, v127
	flat_store_dwordx4 v[142:143], v[128:131]
	v_cvt_pk_bf16_f32 v118, v108, v109
	flat_store_dwordx4 v[142:143], v[116:119] offset:256
	v_cvt_pk_bf16_f32 v108, v120, v121
	v_cvt_pk_bf16_f32 v109, v122, v123
	v_cvt_pk_bf16_f32 v111, v114, v115
	flat_store_dwordx4 v[112:113], v[108:111]
	v_cvt_pk_bf16_f32 v102, v92, v93
	flat_store_dwordx4 v[112:113], v[100:103] offset:256
	v_cvt_pk_bf16_f32 v92, v104, v105
	v_cvt_pk_bf16_f32 v93, v106, v107
	v_cvt_pk_bf16_f32 v95, v98, v99
	flat_store_dwordx4 v[96:97], v[92:95]
	v_cvt_pk_bf16_f32 v86, v76, v77
	flat_store_dwordx4 v[96:97], v[84:87] offset:256
	v_cvt_pk_bf16_f32 v76, v88, v89
	v_cvt_pk_bf16_f32 v77, v90, v91
	v_cvt_pk_bf16_f32 v79, v82, v83
	flat_store_dwordx4 v[80:81], v[76:79]
	v_cvt_pk_bf16_f32 v72, v72, v73
	v_cvt_pk_bf16_f32 v73, v74, v75
	v_cvt_pk_bf16_f32 v74, v68, v69
	v_cvt_pk_bf16_f32 v75, v70, v71
	flat_store_dwordx4 v[80:81], v[72:75] offset:256
	v_cvt_pk_bf16_f32 v67, v62, v63
	flat_store_dwordx4 v[60:61], v[64:67]
	v_cvt_pk_bf16_f32 v54, v44, v45
	flat_store_dwordx4 v[60:61], v[52:55] offset:256
	v_cvt_pk_bf16_f32 v44, v56, v57
	v_cvt_pk_bf16_f32 v45, v58, v59
	v_cvt_pk_bf16_f32 v47, v50, v51
	flat_store_dwordx4 v[48:49], v[44:47]
	v_cvt_pk_bf16_f32 v38, v28, v29
	flat_store_dwordx4 v[48:49], v[36:39] offset:256
	v_cvt_pk_bf16_f32 v28, v40, v41
	v_cvt_pk_bf16_f32 v29, v42, v43
	v_cvt_pk_bf16_f32 v31, v34, v35
	flat_store_dwordx4 v[32:33], v[28:31]
	v_cvt_pk_bf16_f32 v22, v12, v13
	flat_store_dwordx4 v[32:33], v[20:23] offset:256
	v_cvt_pk_bf16_f32 v12, v24, v25
	v_cvt_pk_bf16_f32 v13, v26, v27
	v_cvt_pk_bf16_f32 v15, v18, v19
	flat_store_dwordx4 v[16:17], v[12:15]
	v_cvt_pk_bf16_f32 v8, v8, v9
	v_cvt_pk_bf16_f32 v9, v10, v11
	v_cvt_pk_bf16_f32 v10, v4, v5
	v_cvt_pk_bf16_f32 v11, v6, v7
	flat_store_dwordx4 v[16:17], v[8:11] offset:256
	s_cbranch_vccz .LBB0_106
	s_waitcnt vmcnt(0)
	s_cmpk_gt_u32 s18, 0xff
	s_cbranch_scc1 .LBB0_113
	s_barrier

; #define PG8_WAIT_L(n) asm volatile("s_waitcnt lgkmcnt(" #n ")" ::: "memory")
; #define PG8_BAR __builtin_amdgcn_s_barrier()
; #define PG8_SCHED __builtin_amdgcn_sched_barrier(0)
; template <class Epi, class AddrA, class AddrB>
; __device__ __forceinline__ void gemm_phase(const Sched S, const int lda, const int ldb, const int K, const AddrA addrA,
;                                            const AddrB addrB, const Epi E) {
;     ...
;     const bool has_next = S.next(ui + 1, nxt);
;     const char* nA = has_next ? addrA(nxt) : cA;
;     const char* nB = has_next ? addrB(nxt) : cB;
;     for (int t = 0; t < nt; t += 2) {
;       const bool last = (t == nt - 2);
;       const char* a1 = cA + (size_t)(t + 1) * kstep;
;       const char* a2 = last ? nA : cA + (size_t)(t + 2) * kstep;
;       const char* b2 = last ? nB : cB + (size_t)(t + 2) * kstep;
;       const char* a3 = a2 + kstep;
;       const char* b3 = b2 + kstep;
;       PG8_LDB(B0, 0, 0); PG8_SCHED; PG8_LDA(At, 0, 0); PG8_STAGE(PG8_SA(1, 1), a1 + hstepA, voffA);
;       PG8_WAIT_L(8); PG8_BAR; PG8_WAIT_L(0); PG8_MMA(0, 0, At, B0); PG8_BAR; PG8_SCHED;
;       PG8_LDB(B1, 0, 1); PG8_STAGE(PG8_SB(0, 0), b2, voffB);
;       PG8_BAR; PG8_WAIT_L(0); PG8_MMA(0, 1, At, B1); PG8_BAR;
;       PG8_LDA(At, 0, 1); PG8_STAGE(PG8_SA(0, 0), a2, voffA);
;       PG8_BAR; PG8_WAIT_L(0); PG8_MMA(1, 0, At, B0); PG8_BAR; PG8_SCHED;
; __device__ void phase_post(const Params& p, int layer) {
;     ...
;     gemm_phase(S, DM, 512, 512,
;                [=](const Unit& u) { return (const char*)(pooled + (size_t)u.pm * 256 * DM + (u.pn >> 1) * 512); },
;                [=](const Unit& u) { return (const char*)(wpt + (size_t)u.pn * 256 * 512); }, EpiPool{proj, psc, y0});
.LBB0_484:
	s_ashr_i32 s15, s14, 31
	s_lshl_b64 s[20:21], s[14:15], 20
	s_add_u32 s3, s25, s20
	s_addc_u32 s15, s26, s21
	s_lshl_b32 s17, s16, 8
	s_and_b32 s20, s17, 0xfffffe00
	s_ashr_i32 s21, s20, 31
	s_lshl_b64 s[20:21], s[20:21], 1
	s_add_u32 s20, s3, s20
	s_addc_u32 s21, s15, s21
	s_and_b64 s[22:23], s[10:11], exec
	s_cselect_b32 s3, s21, s7
	s_cselect_b32 s15, s20, s6
	s_ashr_i32 s17, s16, 31
	s_lshl_b64 s[22:23], s[16:17], 18
	s_add_u32 s22, s27, s22
	s_addc_u32 s23, s28, s23
	s_and_b64 s[10:11], s[10:11], exec
	s_cselect_b32 s17, s23, s5
	s_cselect_b32 s40, s22, s4
	s_add_u32 s41, s4, 0x100
	s_addc_u32 s42, s5, 0
	s_add_u32 s4, s6, 0x80080
	s_addc_u32 s5, s7, 0
	s_mov_b32 s43, -2
	s_add_u32 s6, s4, 0xfff80080
	s_addc_u32 s7, s5, -1
	s_add_i32 s44, 0, 0x10000
	v_add_u32_e32 v2, s44, v167
	ds_read_b128 v[92:95], v2
	ds_read_b128 v[100:103], v2 offset:1024
	ds_read_b128 v[132:135], v2 offset:2048
	ds_read_b128 v[144:147], v2 offset:3072
	s_cmp_eq_u32 s43, 4
	s_cselect_b32 s11, s3, s7
	s_cselect_b32 s10, s15, s6
	s_cselect_b32 s7, s17, s42
	s_cselect_b32 s6, s40, s41
	v_lshl_add_u64 v[196:197], s[4:5], 0, v[172:173]
	s_add_i32 m0, s30, 0xc000
	ds_read_b128 v[148:151], v169
	ds_read_b128 v[152:155], v169 offset:1024
	ds_read_b128 v[176:179], v169 offset:2048
	ds_read_b128 v[180:183], v169 offset:3072
	ds_read_b128 v[184:187], v169 offset:4096
	ds_read_b128 v[188:191], v169 offset:5120
	ds_read_b128 v[192:195], v169 offset:6144
	ds_read_b128 v[212:215], v169 offset:7168
	global_load_lds_dwordx4 v[196:197], off
	v_lshl_add_u64 v[196:197], s[4:5], 0, v[170:171]
	s_add_i32 m0, s30, 0xe000
	s_nop 0
	global_load_lds_dwordx4 v[196:197], off
	s_waitcnt lgkmcnt(8)
	s_barrier
	s_waitcnt lgkmcnt(0)
	s_setprio 1
	v_mfma_f32_16x16x32_bf16 v[140:143], v[92:95], v[148:151], 0
	v_mfma_f32_16x16x32_bf16 v[140:143], v[100:103], v[152:155], v[140:143]
	v_mfma_f32_16x16x32_bf16 v[128:131], v[92:95], v[176:179], 0
	v_mfma_f32_16x16x32_bf16 v[128:131], v[100:103], v[180:183], v[128:131]
	v_mfma_f32_16x16x32_bf16 v[120:123], v[92:95], v[184:187], 0
	v_mfma_f32_16x16x32_bf16 v[120:123], v[100:103], v[188:191], v[120:123]
	v_mfma_f32_16x16x32_bf16 v[112:115], v[92:95], v[192:195], 0
	v_mfma_f32_16x16x32_bf16 v[112:115], v[100:103], v[212:215], v[112:115]
	v_mfma_f32_16x16x32_bf16 v[136:139], v[132:135], v[148:151], 0
	v_mfma_f32_16x16x32_bf16 v[136:139], v[144:147], v[152:155], v[136:139]
	v_mfma_f32_16x16x32_bf16 v[124:127], v[132:135], v[176:179], 0
	v_mfma_f32_16x16x32_bf16 v[124:127], v[144:147], v[180:183], v[124:127]
	v_mfma_f32_16x16x32_bf16 v[116:119], v[132:135], v[184:187], 0
	v_mfma_f32_16x16x32_bf16 v[116:119], v[144:147], v[188:191], v[116:119]
	v_mfma_f32_16x16x32_bf16 v[108:111], v[132:135], v[192:195], 0
	v_mfma_f32_16x16x32_bf16 v[108:111], v[144:147], v[212:215], v[108:111]
	s_barrier
	s_setprio 0
	s_add_i32 s46, 0, 0x14000
	s_add_i32 s44, s44, s29
	v_add_u32_e32 v2, s46, v167
	v_lshl_add_u64 v[196:197], s[6:7], 0, v[158:159]
	s_mov_b32 m0, s44
	ds_read_b128 v[216:219], v2
	ds_read_b128 v[220:223], v2 offset:1024
	ds_read_b128 v[224:227], v2 offset:2048
	ds_read_b128 v[228:231], v2 offset:3072
	global_load_lds_dwordx4 v[196:197], off
	v_lshl_add_u64 v[232:233], s[6:7], 0, v[0:1]
	s_add_i32 m0, s44, 0x2000
	s_nop 0
	global_load_lds_dwordx4 v[232:233], off
	s_barrier
	s_waitcnt lgkmcnt(0)
	s_setprio 1
	v_mfma_f32_16x16x32_bf16 v[64:67], v[216:219], v[148:151], 0
	v_mfma_f32_16x16x32_bf16 v[64:67], v[220:223], v[152:155], v[64:67]
	v_mfma_f32_16x16x32_bf16 v[56:59], v[216:219], v[176:179], 0
	v_mfma_f32_16x16x32_bf16 v[56:59], v[220:223], v[180:183], v[56:59]
	v_mfma_f32_16x16x32_bf16 v[48:51], v[216:219], v[184:187], 0
	v_mfma_f32_16x16x32_bf16 v[48:51], v[220:223], v[188:191], v[48:51]
	v_mfma_f32_16x16x32_bf16 v[40:43], v[216:219], v[192:195], 0
	v_mfma_f32_16x16x32_bf16 v[40:43], v[220:223], v[212:215], v[40:43]
	v_mfma_f32_16x16x32_bf16 v[60:63], v[224:227], v[148:151], 0
	v_mfma_f32_16x16x32_bf16 v[60:63], v[228:231], v[152:155], v[60:63]
	v_mfma_f32_16x16x32_bf16 v[52:55], v[224:227], v[176:179], 0
	v_mfma_f32_16x16x32_bf16 v[52:55], v[228:231], v[180:183], v[52:55]
	v_mfma_f32_16x16x32_bf16 v[44:47], v[224:227], v[184:187], 0
	v_mfma_f32_16x16x32_bf16 v[44:47], v[228:231], v[188:191], v[44:47]
	v_mfma_f32_16x16x32_bf16 v[36:39], v[224:227], v[192:195], 0
	v_mfma_f32_16x16x32_bf16 v[36:39], v[228:231], v[212:215], v[36:39]
	s_mov_b32 m0, s30
	v_lshl_add_u64 v[234:235], s[10:11], 0, v[160:161]
	s_barrier
	s_setprio 0
	ds_read_b128 v[148:151], v169 offset:16384
	ds_read_b128 v[152:155], v169 offset:17408
	ds_read_b128 v[176:179], v169 offset:18432
	ds_read_b128 v[180:183], v169 offset:19456
	ds_read_b128 v[184:187], v169 offset:20480
	ds_read_b128 v[188:191], v169 offset:21504
	ds_read_b128 v[192:195], v169 offset:22528
	ds_read_b128 v[212:215], v169 offset:23552
	global_load_lds_dwordx4 v[234:235], off
	v_lshl_add_u64 v[236:237], s[10:11], 0, v[156:157]
	s_mov_b32 m0, s31
	s_nop 0
	global_load_lds_dwordx4 v[236:237], off
	s_barrier
	s_waitcnt lgkmcnt(0)
	s_setprio 1
	v_mfma_f32_16x16x32_bf16 v[104:107], v[92:95], v[148:151], 0
	v_mfma_f32_16x16x32_bf16 v[104:107], v[100:103], v[152:155], v[104:107]
	v_mfma_f32_16x16x32_bf16 v[88:91], v[92:95], v[176:179], 0
	v_mfma_f32_16x16x32_bf16 v[88:91], v[100:103], v[180:183], v[88:91]
	v_mfma_f32_16x16x32_bf16 v[80:83], v[92:95], v[184:187], 0
	v_mfma_f32_16x16x32_bf16 v[80:83], v[100:103], v[188:191], v[80:83]
	v_mfma_f32_16x16x32_bf16 v[72:75], v[92:95], v[192:195], 0
	v_mfma_f32_16x16x32_bf16 v[72:75], v[100:103], v[212:215], v[72:75]
	v_mfma_f32_16x16x32_bf16 v[96:99], v[132:135], v[148:151], 0
	v_mfma_f32_16x16x32_bf16 v[96:99], v[144:147], v[152:155], v[96:99]
	v_mfma_f32_16x16x32_bf16 v[84:87], v[132:135], v[176:179], 0
	v_mfma_f32_16x16x32_bf16 v[84:87], v[144:147], v[180:183], v[84:87]
	v_mfma_f32_16x16x32_bf16 v[76:79], v[132:135], v[184:187], 0
	v_mfma_f32_16x16x32_bf16 v[76:79], v[144:147], v[188:191], v[76:79]
	v_mfma_f32_16x16x32_bf16 v[68:71], v[132:135], v[192:195], 0
	v_mfma_f32_16x16x32_bf16 v[68:71], v[144:147], v[212:215], v[68:71]
	s_barrier
; #define PG8_WAIT_V(n) asm volatile("s_waitcnt vmcnt(" #n ")" ::: "memory")
; #define PG8_WAIT_L(n) asm volatile("s_waitcnt lgkmcnt(" #n ")" ::: "memory")
; #define PG8_BAR __builtin_amdgcn_s_barrier()
; #define PG8_SCHED __builtin_amdgcn_sched_barrier(0)
; template <class Epi, class AddrA, class AddrB>
; __device__ __forceinline__ void gemm_phase(const Sched S, const int lda, const int ldb, const int K, const AddrA addrA,
;                                            const AddrB addrB, const Epi E) {
;     ...
;       PG8_STAGE(PG8_SB(0, 1), b2 + hstepB, voffB);
;       PG8_WAIT_V(6); PG8_BAR; PG8_MMA(1, 1, At, B1); PG8_BAR;
;       PG8_LDB(B0, 1, 0); PG8_SCHED; PG8_LDA(At, 1, 0); PG8_STAGE(PG8_SA(0, 1), a2 + hstepA, voffA);
;       PG8_WAIT_L(8); PG8_BAR; PG8_WAIT_L(0); PG8_MMA(0, 0, At, B0); PG8_BAR; PG8_SCHED;
;       PG8_LDB(B1, 1, 1); PG8_STAGE(PG8_SB(1, 0), b3, voffB);
;       PG8_BAR; PG8_WAIT_L(0); PG8_MMA(0, 1, At, B1); PG8_BAR;
;       PG8_LDA(At, 1, 1); PG8_STAGE(PG8_SA(1, 0), a3, voffA);
;       PG8_BAR; PG8_WAIT_L(0); PG8_MMA(1, 0, At, B0); PG8_BAR; PG8_SCHED;
	s_setprio 0
	s_add_u32 s44, s6, 0x20000
	s_addc_u32 s45, s7, 0
	s_add_i32 s46, s46, s29
	v_lshl_add_u64 v[92:93], s[44:45], 0, v[158:159]
	s_mov_b32 m0, s46
	s_nop 0
	global_load_lds_dwordx4 v[92:93], off
	v_lshl_add_u64 v[92:93], s[44:45], 0, v[0:1]
	s_add_i32 m0, s46, 0x2000
	s_nop 0
	global_load_lds_dwordx4 v[92:93], off
	s_waitcnt vmcnt(6)
	s_barrier
	s_setprio 1
	v_mfma_f32_16x16x32_bf16 v[32:35], v[216:219], v[148:151], 0
	v_mfma_f32_16x16x32_bf16 v[32:35], v[220:223], v[152:155], v[32:35]
	v_mfma_f32_16x16x32_bf16 v[24:27], v[216:219], v[176:179], 0
	v_mfma_f32_16x16x32_bf16 v[24:27], v[220:223], v[180:183], v[24:27]
	v_mfma_f32_16x16x32_bf16 v[16:19], v[216:219], v[184:187], 0
	v_mfma_f32_16x16x32_bf16 v[16:19], v[220:223], v[188:191], v[16:19]
	v_mfma_f32_16x16x32_bf16 v[8:11], v[216:219], v[192:195], 0
	v_mfma_f32_16x16x32_bf16 v[8:11], v[220:223], v[212:215], v[8:11]
	v_mfma_f32_16x16x32_bf16 v[28:31], v[224:227], v[148:151], 0
	v_mfma_f32_16x16x32_bf16 v[28:31], v[228:231], v[152:155], v[28:31]
	v_mfma_f32_16x16x32_bf16 v[20:23], v[224:227], v[176:179], 0
	v_mfma_f32_16x16x32_bf16 v[20:23], v[228:231], v[180:183], v[20:23]
	v_mfma_f32_16x16x32_bf16 v[12:15], v[224:227], v[184:187], 0
	v_mfma_f32_16x16x32_bf16 v[12:15], v[228:231], v[188:191], v[12:15]
	v_mfma_f32_16x16x32_bf16 v[4:7], v[224:227], v[192:195], 0
	v_mfma_f32_16x16x32_bf16 v[4:7], v[228:231], v[212:215], v[4:7]
	s_add_i32 s44, 0, 0x18000
	v_add_u32_e32 v2, s44, v167
	s_barrier
	s_setprio 0
	ds_read_b128 v[92:95], v2
	ds_read_b128 v[100:103], v2 offset:1024
	ds_read_b128 v[132:135], v2 offset:2048
	ds_read_b128 v[144:147], v2 offset:3072
	s_add_u32 s10, s10, 0x80000
	s_addc_u32 s11, s11, 0
	s_mov_b32 m0, s34
	v_lshl_add_u64 v[216:217], s[10:11], 0, v[160:161]
	ds_read_b128 v[148:151], v169 offset:32768
	ds_read_b128 v[152:155], v169 offset:33792
	ds_read_b128 v[176:179], v169 offset:34816
	ds_read_b128 v[180:183], v169 offset:35840
	ds_read_b128 v[184:187], v169 offset:36864
	ds_read_b128 v[188:191], v169 offset:37888
	ds_read_b128 v[192:195], v169 offset:38912
	ds_read_b128 v[212:215], v169 offset:39936
	global_load_lds_dwordx4 v[216:217], off
	v_lshl_add_u64 v[216:217], s[10:11], 0, v[156:157]
	s_mov_b32 m0, s35
	s_nop 0
	global_load_lds_dwordx4 v[216:217], off
	s_waitcnt lgkmcnt(8)
	s_barrier
	s_waitcnt lgkmcnt(0)
	s_setprio 1
	v_mfma_f32_16x16x32_bf16 v[140:143], v[92:95], v[148:151], v[140:143]
	v_mfma_f32_16x16x32_bf16 v[140:143], v[100:103], v[152:155], v[140:143]
	v_mfma_f32_16x16x32_bf16 v[128:131], v[92:95], v[176:179], v[128:131]
	v_mfma_f32_16x16x32_bf16 v[128:131], v[100:103], v[180:183], v[128:131]
	v_mfma_f32_16x16x32_bf16 v[120:123], v[92:95], v[184:187], v[120:123]
	v_mfma_f32_16x16x32_bf16 v[120:123], v[100:103], v[188:191], v[120:123]
	v_mfma_f32_16x16x32_bf16 v[112:115], v[92:95], v[192:195], v[112:115]
	v_mfma_f32_16x16x32_bf16 v[112:115], v[100:103], v[212:215], v[112:115]
	v_mfma_f32_16x16x32_bf16 v[136:139], v[132:135], v[148:151], v[136:139]
	v_mfma_f32_16x16x32_bf16 v[136:139], v[144:147], v[152:155], v[136:139]
	v_mfma_f32_16x16x32_bf16 v[124:127], v[132:135], v[176:179], v[124:127]
	v_mfma_f32_16x16x32_bf16 v[124:127], v[144:147], v[180:183], v[124:127]
	v_mfma_f32_16x16x32_bf16 v[116:119], v[132:135], v[184:187], v[116:119]
	v_mfma_f32_16x16x32_bf16 v[116:119], v[144:147], v[188:191], v[116:119]
	v_mfma_f32_16x16x32_bf16 v[108:111], v[132:135], v[192:195], v[108:111]
	v_mfma_f32_16x16x32_bf16 v[108:111], v[144:147], v[212:215], v[108:111]
	s_barrier
	s_setprio 0
	s_add_i32 s10, 0, 0x1c000
	s_add_i32 s11, s44, s29
	v_add_u32_e32 v2, s10, v167
	v_lshl_add_u64 v[196:197], v[196:197], 0, s[52:53]
	s_mov_b32 m0, s11
	ds_read_b128 v[216:219], v2
	ds_read_b128 v[220:223], v2 offset:1024
	ds_read_b128 v[224:227], v2 offset:2048
	ds_read_b128 v[228:231], v2 offset:3072
	global_load_lds_dwordx4 v[196:197], off
	v_lshl_add_u64 v[196:197], v[232:233], 0, s[52:53]
	s_add_i32 m0, s11, 0x2000
	s_nop 0
	global_load_lds_dwordx4 v[196:197], off
	s_barrier
	s_waitcnt lgkmcnt(0)
	s_setprio 1
	v_mfma_f32_16x16x32_bf16 v[64:67], v[216:219], v[148:151], v[64:67]
	v_mfma_f32_16x16x32_bf16 v[64:67], v[220:223], v[152:155], v[64:67]
	v_mfma_f32_16x16x32_bf16 v[56:59], v[216:219], v[176:179], v[56:59]
	v_mfma_f32_16x16x32_bf16 v[56:59], v[220:223], v[180:183], v[56:59]
	v_mfma_f32_16x16x32_bf16 v[48:51], v[216:219], v[184:187], v[48:51]
	v_mfma_f32_16x16x32_bf16 v[48:51], v[220:223], v[188:191], v[48:51]
	v_mfma_f32_16x16x32_bf16 v[40:43], v[216:219], v[192:195], v[40:43]
	v_mfma_f32_16x16x32_bf16 v[40:43], v[220:223], v[212:215], v[40:43]
	v_mfma_f32_16x16x32_bf16 v[60:63], v[224:227], v[148:151], v[60:63]
	v_mfma_f32_16x16x32_bf16 v[60:63], v[228:231], v[152:155], v[60:63]
	v_mfma_f32_16x16x32_bf16 v[52:55], v[224:227], v[176:179], v[52:55]
	v_mfma_f32_16x16x32_bf16 v[52:55], v[228:231], v[180:183], v[52:55]
	v_mfma_f32_16x16x32_bf16 v[44:47], v[224:227], v[184:187], v[44:47]
	v_mfma_f32_16x16x32_bf16 v[44:47], v[228:231], v[188:191], v[44:47]
	v_mfma_f32_16x16x32_bf16 v[36:39], v[224:227], v[192:195], v[36:39]
	v_mfma_f32_16x16x32_bf16 v[36:39], v[228:231], v[212:215], v[36:39]
	s_mov_b32 m0, s37
	v_lshl_add_u64 v[196:197], v[234:235], 0, s[52:53]
	s_barrier
	s_setprio 0
	ds_read_b128 v[148:151], v169 offset:49152
	ds_read_b128 v[152:155], v169 offset:50176
	ds_read_b128 v[176:179], v169 offset:51200
	ds_read_b128 v[180:183], v169 offset:52224
	ds_read_b128 v[184:187], v169 offset:53248
	ds_read_b128 v[188:191], v169 offset:54272
	ds_read_b128 v[192:195], v169 offset:55296
	ds_read_b128 v[212:215], v169 offset:56320
	global_load_lds_dwordx4 v[196:197], off
	v_lshl_add_u64 v[196:197], v[236:237], 0, s[52:53]
	s_mov_b32 m0, s38
	s_nop 0
	global_load_lds_dwordx4 v[196:197], off
	s_barrier
; #define PG8_WAIT_L(n) asm volatile("s_waitcnt lgkmcnt(" #n ")" ::: "memory")
; #define PG8_BAR __builtin_amdgcn_s_barrier()
; #define PG8_SCHED __builtin_amdgcn_sched_barrier(0)
; template <class Epi, class AddrA, class AddrB>
; __device__ __forceinline__ void gemm_phase(const Sched S, const int lda, const int ldb, const int K, const AddrA addrA,
;                                            const AddrB addrB, const Epi E) {
;     ...
;     for (int t = 0; t < nt; t += 2) {
;       const bool last = (t == nt - 2);
;       const char* a1 = cA + (size_t)(t + 1) * kstep;
;       const char* a2 = last ? nA : cA + (size_t)(t + 2) * kstep;
;       const char* b2 = last ? nB : cB + (size_t)(t + 2) * kstep;
;       const char* a3 = a2 + kstep;
;       const char* b3 = b2 + kstep;
;       PG8_LDB(B0, 0, 0); PG8_SCHED; PG8_LDA(At, 0, 0); PG8_STAGE(PG8_SA(1, 1), a1 + hstepA, voffA);
;       PG8_WAIT_L(8); PG8_BAR; PG8_WAIT_L(0); PG8_MMA(0, 0, At, B0); PG8_BAR; PG8_SCHED;
;       PG8_LDB(B1, 0, 1); PG8_STAGE(PG8_SB(0, 0), b2, voffB);
;       PG8_BAR; PG8_WAIT_L(0); PG8_MMA(0, 1, At, B1); PG8_BAR;
;       PG8_LDA(At, 0, 1); PG8_STAGE(PG8_SA(0, 0), a2, voffA);
;       PG8_BAR; PG8_WAIT_L(0); PG8_MMA(1, 0, At, B0); PG8_BAR; PG8_SCHED;
	s_waitcnt lgkmcnt(0)
	s_setprio 1
	v_mfma_f32_16x16x32_bf16 v[104:107], v[92:95], v[148:151], v[104:107]
	v_mfma_f32_16x16x32_bf16 v[104:107], v[100:103], v[152:155], v[104:107]
	v_mfma_f32_16x16x32_bf16 v[88:91], v[92:95], v[176:179], v[88:91]
	v_mfma_f32_16x16x32_bf16 v[88:91], v[100:103], v[180:183], v[88:91]
	v_mfma_f32_16x16x32_bf16 v[80:83], v[92:95], v[184:187], v[80:83]
	v_mfma_f32_16x16x32_bf16 v[80:83], v[100:103], v[188:191], v[80:83]
	v_mfma_f32_16x16x32_bf16 v[72:75], v[92:95], v[192:195], v[72:75]
	v_mfma_f32_16x16x32_bf16 v[72:75], v[100:103], v[212:215], v[72:75]
	v_mfma_f32_16x16x32_bf16 v[96:99], v[132:135], v[148:151], v[96:99]
	v_mfma_f32_16x16x32_bf16 v[96:99], v[144:147], v[152:155], v[96:99]
	v_mfma_f32_16x16x32_bf16 v[84:87], v[132:135], v[176:179], v[84:87]
	v_mfma_f32_16x16x32_bf16 v[84:87], v[144:147], v[180:183], v[84:87]
	v_mfma_f32_16x16x32_bf16 v[76:79], v[132:135], v[184:187], v[76:79]
	v_mfma_f32_16x16x32_bf16 v[76:79], v[144:147], v[188:191], v[76:79]
	v_mfma_f32_16x16x32_bf16 v[68:71], v[132:135], v[192:195], v[68:71]
	v_mfma_f32_16x16x32_bf16 v[68:71], v[144:147], v[212:215], v[68:71]
	s_barrier
	s_setprio 0
	s_add_u32 s6, s6, 0x20080
	s_addc_u32 s7, s7, 0
	s_add_i32 s10, s10, s29
	v_lshl_add_u64 v[92:93], s[6:7], 0, v[158:159]
	s_mov_b32 m0, s10
	s_nop 0
	global_load_lds_dwordx4 v[92:93], off
	v_lshl_add_u64 v[92:93], s[6:7], 0, v[0:1]
	s_add_i32 m0, s10, 0x2000
	s_nop 0
	global_load_lds_dwordx4 v[92:93], off
	s_waitcnt vmcnt(6)
	s_barrier
	s_setprio 1
	v_mfma_f32_16x16x32_bf16 v[32:35], v[216:219], v[148:151], v[32:35]
	v_mfma_f32_16x16x32_bf16 v[32:35], v[220:223], v[152:155], v[32:35]
	v_mfma_f32_16x16x32_bf16 v[24:27], v[216:219], v[176:179], v[24:27]
	v_mfma_f32_16x16x32_bf16 v[24:27], v[220:223], v[180:183], v[24:27]
	v_mfma_f32_16x16x32_bf16 v[16:19], v[216:219], v[184:187], v[16:19]
	v_mfma_f32_16x16x32_bf16 v[16:19], v[220:223], v[188:191], v[16:19]
	v_mfma_f32_16x16x32_bf16 v[8:11], v[216:219], v[192:195], v[8:11]
	v_mfma_f32_16x16x32_bf16 v[8:11], v[220:223], v[212:215], v[8:11]
	v_mfma_f32_16x16x32_bf16 v[28:31], v[224:227], v[148:151], v[28:31]
	v_mfma_f32_16x16x32_bf16 v[28:31], v[228:231], v[152:155], v[28:31]
	v_mfma_f32_16x16x32_bf16 v[20:23], v[224:227], v[176:179], v[20:23]
	v_mfma_f32_16x16x32_bf16 v[20:23], v[228:231], v[180:183], v[20:23]
	v_mfma_f32_16x16x32_bf16 v[12:15], v[224:227], v[184:187], v[12:15]
	v_mfma_f32_16x16x32_bf16 v[12:15], v[228:231], v[188:191], v[12:15]
	v_mfma_f32_16x16x32_bf16 v[4:7], v[224:227], v[192:195], v[4:7]
	v_mfma_f32_16x16x32_bf16 v[4:7], v[228:231], v[212:215], v[4:7]
	s_add_i32 s43, s43, 2
	s_add_u32 s41, s41, 0x100
	s_addc_u32 s42, s42, 0
	s_add_u32 s4, s4, 0x100
	s_addc_u32 s5, s5, 0
	s_cmp_gt_u32 s43, 5
	s_barrier
	s_setprio 0
.LBB0_485:
	s_add_u32 s6, s4, 0xfff80080
	s_addc_u32 s7, s5, -1
	s_add_i32 s44, 0, 0x10000
	v_add_u32_e32 v2, s44, v167
	ds_read_b128 v[92:95], v2
	ds_read_b128 v[100:103], v2 offset:1024
	ds_read_b128 v[132:135], v2 offset:2048
	ds_read_b128 v[144:147], v2 offset:3072
	s_cmp_eq_u32 s43, 4
	s_cselect_b32 s11, s3, s7
	s_cselect_b32 s10, s15, s6
	s_cselect_b32 s7, s17, s42
	s_cselect_b32 s6, s40, s41
	v_lshl_add_u64 v[196:197], s[4:5], 0, v[172:173]
	s_add_i32 m0, s30, 0xc000
	ds_read_b128 v[148:151], v169
	ds_read_b128 v[152:155], v169 offset:1024
	ds_read_b128 v[176:179], v169 offset:2048
	ds_read_b128 v[180:183], v169 offset:3072
	ds_read_b128 v[184:187], v169 offset:4096
	ds_read_b128 v[188:191], v169 offset:5120
	ds_read_b128 v[192:195], v169 offset:6144
	ds_read_b128 v[212:215], v169 offset:7168
	global_load_lds_dwordx4 v[196:197], off
	v_lshl_add_u64 v[196:197], s[4:5], 0, v[170:171]
	s_add_i32 m0, s30, 0xe000
	s_nop 0
	global_load_lds_dwordx4 v[196:197], off
	s_waitcnt lgkmcnt(8)
	s_barrier
	s_waitcnt lgkmcnt(0)
	s_setprio 1
	v_mfma_f32_16x16x32_bf16 v[140:143], v[92:95], v[148:151], v[140:143]
	v_mfma_f32_16x16x32_bf16 v[140:143], v[100:103], v[152:155], v[140:143]
	v_mfma_f32_16x16x32_bf16 v[128:131], v[92:95], v[176:179], v[128:131]
	v_mfma_f32_16x16x32_bf16 v[128:131], v[100:103], v[180:183], v[128:131]
	v_mfma_f32_16x16x32_bf16 v[120:123], v[92:95], v[184:187], v[120:123]
	v_mfma_f32_16x16x32_bf16 v[120:123], v[100:103], v[188:191], v[120:123]
	v_mfma_f32_16x16x32_bf16 v[112:115], v[92:95], v[192:195], v[112:115]
	v_mfma_f32_16x16x32_bf16 v[112:115], v[100:103], v[212:215], v[112:115]
	v_mfma_f32_16x16x32_bf16 v[136:139], v[132:135], v[148:151], v[136:139]
	v_mfma_f32_16x16x32_bf16 v[136:139], v[144:147], v[152:155], v[136:139]
	v_mfma_f32_16x16x32_bf16 v[124:127], v[132:135], v[176:179], v[124:127]
	v_mfma_f32_16x16x32_bf16 v[124:127], v[144:147], v[180:183], v[124:127]
	v_mfma_f32_16x16x32_bf16 v[116:119], v[132:135], v[184:187], v[116:119]
	v_mfma_f32_16x16x32_bf16 v[116:119], v[144:147], v[188:191], v[116:119]
	v_mfma_f32_16x16x32_bf16 v[108:111], v[132:135], v[192:195], v[108:111]
	v_mfma_f32_16x16x32_bf16 v[108:111], v[144:147], v[212:215], v[108:111]
	s_barrier
	s_setprio 0
	s_add_i32 s46, 0, 0x14000
	s_add_i32 s44, s44, s29
	v_add_u32_e32 v2, s46, v167
	v_lshl_add_u64 v[196:197], s[6:7], 0, v[158:159]
	s_mov_b32 m0, s44
	ds_read_b128 v[216:219], v2
	ds_read_b128 v[220:223], v2 offset:1024
	ds_read_b128 v[224:227], v2 offset:2048
	ds_read_b128 v[228:231], v2 offset:3072
	global_load_lds_dwordx4 v[196:197], off
	v_lshl_add_u64 v[232:233], s[6:7], 0, v[0:1]
	s_add_i32 m0, s44, 0x2000
	s_nop 0
	global_load_lds_dwordx4 v[232:233], off
	s_barrier
; #define PG8_WAIT_V(n) asm volatile("s_waitcnt vmcnt(" #n ")" ::: "memory")
; #define PG8_WAIT_L(n) asm volatile("s_waitcnt lgkmcnt(" #n ")" ::: "memory")
; #define PG8_BAR __builtin_amdgcn_s_barrier()
; #define PG8_SCHED __builtin_amdgcn_sched_barrier(0)
; template <class Epi, class AddrA, class AddrB>
; __device__ __forceinline__ void gemm_phase(const Sched S, const int lda, const int ldb, const int K, const AddrA addrA,
;                                            const AddrB addrB, const Epi E) {
;     ...
;       PG8_WAIT_L(8); PG8_BAR; PG8_WAIT_L(0); PG8_MMA(0, 0, At, B0); PG8_BAR; PG8_SCHED;
;       PG8_LDB(B1, 0, 1); PG8_STAGE(PG8_SB(0, 0), b2, voffB);
;       PG8_BAR; PG8_WAIT_L(0); PG8_MMA(0, 1, At, B1); PG8_BAR;
;       PG8_LDA(At, 0, 1); PG8_STAGE(PG8_SA(0, 0), a2, voffA);
;       PG8_BAR; PG8_WAIT_L(0); PG8_MMA(1, 0, At, B0); PG8_BAR; PG8_SCHED;
;       PG8_STAGE(PG8_SB(0, 1), b2 + hstepB, voffB);
;       PG8_WAIT_V(6); PG8_BAR; PG8_MMA(1, 1, At, B1); PG8_BAR;
;       PG8_LDB(B0, 1, 0); PG8_SCHED; PG8_LDA(At, 1, 0); PG8_STAGE(PG8_SA(0, 1), a2 + hstepA, voffA);
;       PG8_WAIT_L(8); PG8_BAR; PG8_WAIT_L(0); PG8_MMA(0, 0, At, B0); PG8_BAR; PG8_SCHED;
	s_waitcnt lgkmcnt(0)
	s_setprio 1
	v_mfma_f32_16x16x32_bf16 v[64:67], v[216:219], v[148:151], v[64:67]
	v_mfma_f32_16x16x32_bf16 v[64:67], v[220:223], v[152:155], v[64:67]
	v_mfma_f32_16x16x32_bf16 v[56:59], v[216:219], v[176:179], v[56:59]
	v_mfma_f32_16x16x32_bf16 v[56:59], v[220:223], v[180:183], v[56:59]
	v_mfma_f32_16x16x32_bf16 v[48:51], v[216:219], v[184:187], v[48:51]
	v_mfma_f32_16x16x32_bf16 v[48:51], v[220:223], v[188:191], v[48:51]
	v_mfma_f32_16x16x32_bf16 v[40:43], v[216:219], v[192:195], v[40:43]
	v_mfma_f32_16x16x32_bf16 v[40:43], v[220:223], v[212:215], v[40:43]
	v_mfma_f32_16x16x32_bf16 v[60:63], v[224:227], v[148:151], v[60:63]
	v_mfma_f32_16x16x32_bf16 v[60:63], v[228:231], v[152:155], v[60:63]
	v_mfma_f32_16x16x32_bf16 v[52:55], v[224:227], v[176:179], v[52:55]
	v_mfma_f32_16x16x32_bf16 v[52:55], v[228:231], v[180:183], v[52:55]
	v_mfma_f32_16x16x32_bf16 v[44:47], v[224:227], v[184:187], v[44:47]
	v_mfma_f32_16x16x32_bf16 v[44:47], v[228:231], v[188:191], v[44:47]
	v_mfma_f32_16x16x32_bf16 v[36:39], v[224:227], v[192:195], v[36:39]
	v_mfma_f32_16x16x32_bf16 v[36:39], v[228:231], v[212:215], v[36:39]
	s_mov_b32 m0, s30
	v_lshl_add_u64 v[234:235], s[10:11], 0, v[160:161]
	s_barrier
	s_setprio 0
	ds_read_b128 v[148:151], v169 offset:16384
	ds_read_b128 v[152:155], v169 offset:17408
	ds_read_b128 v[176:179], v169 offset:18432
	ds_read_b128 v[180:183], v169 offset:19456
	ds_read_b128 v[184:187], v169 offset:20480
	ds_read_b128 v[188:191], v169 offset:21504
	ds_read_b128 v[192:195], v169 offset:22528
	ds_read_b128 v[212:215], v169 offset:23552
	global_load_lds_dwordx4 v[234:235], off
	v_lshl_add_u64 v[236:237], s[10:11], 0, v[156:157]
	s_mov_b32 m0, s31
	s_nop 0
	global_load_lds_dwordx4 v[236:237], off
	s_barrier
	s_waitcnt lgkmcnt(0)
	s_setprio 1
	v_mfma_f32_16x16x32_bf16 v[104:107], v[92:95], v[148:151], v[104:107]
	v_mfma_f32_16x16x32_bf16 v[104:107], v[100:103], v[152:155], v[104:107]
	v_mfma_f32_16x16x32_bf16 v[88:91], v[92:95], v[176:179], v[88:91]
	v_mfma_f32_16x16x32_bf16 v[88:91], v[100:103], v[180:183], v[88:91]
	v_mfma_f32_16x16x32_bf16 v[80:83], v[92:95], v[184:187], v[80:83]
	v_mfma_f32_16x16x32_bf16 v[80:83], v[100:103], v[188:191], v[80:83]
	v_mfma_f32_16x16x32_bf16 v[72:75], v[92:95], v[192:195], v[72:75]
	v_mfma_f32_16x16x32_bf16 v[72:75], v[100:103], v[212:215], v[72:75]
	v_mfma_f32_16x16x32_bf16 v[96:99], v[132:135], v[148:151], v[96:99]
	v_mfma_f32_16x16x32_bf16 v[96:99], v[144:147], v[152:155], v[96:99]
	v_mfma_f32_16x16x32_bf16 v[84:87], v[132:135], v[176:179], v[84:87]
	v_mfma_f32_16x16x32_bf16 v[84:87], v[144:147], v[180:183], v[84:87]
	v_mfma_f32_16x16x32_bf16 v[76:79], v[132:135], v[184:187], v[76:79]
	v_mfma_f32_16x16x32_bf16 v[76:79], v[144:147], v[188:191], v[76:79]
	v_mfma_f32_16x16x32_bf16 v[68:71], v[132:135], v[192:195], v[68:71]
	v_mfma_f32_16x16x32_bf16 v[68:71], v[144:147], v[212:215], v[68:71]
	s_barrier
	s_setprio 0
	s_add_u32 s44, s6, 0x20000
	s_addc_u32 s45, s7, 0
	s_add_i32 s46, s46, s29
	v_lshl_add_u64 v[92:93], s[44:45], 0, v[158:159]
	s_mov_b32 m0, s46
	s_nop 0
	global_load_lds_dwordx4 v[92:93], off
	v_lshl_add_u64 v[92:93], s[44:45], 0, v[0:1]
	s_add_i32 m0, s46, 0x2000
	s_nop 0
	global_load_lds_dwordx4 v[92:93], off
	s_waitcnt vmcnt(6)
	s_barrier
	s_setprio 1
	v_mfma_f32_16x16x32_bf16 v[32:35], v[216:219], v[148:151], v[32:35]
	v_mfma_f32_16x16x32_bf16 v[32:35], v[220:223], v[152:155], v[32:35]
	v_mfma_f32_16x16x32_bf16 v[24:27], v[216:219], v[176:179], v[24:27]
	v_mfma_f32_16x16x32_bf16 v[24:27], v[220:223], v[180:183], v[24:27]
	v_mfma_f32_16x16x32_bf16 v[16:19], v[216:219], v[184:187], v[16:19]
	v_mfma_f32_16x16x32_bf16 v[16:19], v[220:223], v[188:191], v[16:19]
	v_mfma_f32_16x16x32_bf16 v[8:11], v[216:219], v[192:195], v[8:11]
	v_mfma_f32_16x16x32_bf16 v[8:11], v[220:223], v[212:215], v[8:11]
	v_mfma_f32_16x16x32_bf16 v[28:31], v[224:227], v[148:151], v[28:31]
	v_mfma_f32_16x16x32_bf16 v[28:31], v[228:231], v[152:155], v[28:31]
	v_mfma_f32_16x16x32_bf16 v[20:23], v[224:227], v[176:179], v[20:23]
	v_mfma_f32_16x16x32_bf16 v[20:23], v[228:231], v[180:183], v[20:23]
	v_mfma_f32_16x16x32_bf16 v[12:15], v[224:227], v[184:187], v[12:15]
	v_mfma_f32_16x16x32_bf16 v[12:15], v[228:231], v[188:191], v[12:15]
	v_mfma_f32_16x16x32_bf16 v[4:7], v[224:227], v[192:195], v[4:7]
	v_mfma_f32_16x16x32_bf16 v[4:7], v[228:231], v[212:215], v[4:7]
	s_add_i32 s44, 0, 0x18000
	v_add_u32_e32 v2, s44, v167
	s_barrier
	s_setprio 0
	ds_read_b128 v[92:95], v2
	ds_read_b128 v[100:103], v2 offset:1024
	ds_read_b128 v[132:135], v2 offset:2048
	ds_read_b128 v[144:147], v2 offset:3072
	s_add_u32 s10, s10, 0x80000
	s_addc_u32 s11, s11, 0
	s_mov_b32 m0, s34
	v_lshl_add_u64 v[216:217], s[10:11], 0, v[160:161]
	ds_read_b128 v[148:151], v169 offset:32768
	ds_read_b128 v[152:155], v169 offset:33792
	ds_read_b128 v[176:179], v169 offset:34816
	ds_read_b128 v[180:183], v169 offset:35840
	ds_read_b128 v[184:187], v169 offset:36864
	ds_read_b128 v[188:191], v169 offset:37888
	ds_read_b128 v[192:195], v169 offset:38912
	ds_read_b128 v[212:215], v169 offset:39936
	global_load_lds_dwordx4 v[216:217], off
	v_lshl_add_u64 v[216:217], s[10:11], 0, v[156:157]
	s_mov_b32 m0, s35
	s_nop 0
	global_load_lds_dwordx4 v[216:217], off
	s_waitcnt lgkmcnt(8)
	s_barrier
; #define PG8_WAIT_V(n) asm volatile("s_waitcnt vmcnt(" #n ")" ::: "memory")
; #define PG8_WAIT_L(n) asm volatile("s_waitcnt lgkmcnt(" #n ")" ::: "memory")
; #define PG8_BAR __builtin_amdgcn_s_barrier()
; #define PG8_SCHED __builtin_amdgcn_sched_barrier(0)
; template <class Epi, class AddrA, class AddrB>
; __device__ __forceinline__ void gemm_phase(const Sched S, const int lda, const int ldb, const int K, const AddrA addrA,
;                                            const AddrB addrB, const Epi E) {
;     ...
;       PG8_WAIT_L(8); PG8_BAR; PG8_WAIT_L(0); PG8_MMA(0, 0, At, B0); PG8_BAR; PG8_SCHED;
;       PG8_LDB(B1, 1, 1); PG8_STAGE(PG8_SB(1, 0), b3, voffB);
;       PG8_BAR; PG8_WAIT_L(0); PG8_MMA(0, 1, At, B1); PG8_BAR;
;       PG8_LDA(At, 1, 1); PG8_STAGE(PG8_SA(1, 0), a3, voffA);
;       PG8_BAR; PG8_WAIT_L(0); PG8_MMA(1, 0, At, B0); PG8_BAR; PG8_SCHED;
;       PG8_STAGE(PG8_SB(1, 1), b3 + hstepB, voffB);
;       PG8_WAIT_V(6); PG8_BAR; PG8_MMA(1, 1, At, B1); PG8_BAR;
	s_waitcnt lgkmcnt(0)
	s_setprio 1
	v_mfma_f32_16x16x32_bf16 v[140:143], v[92:95], v[148:151], v[140:143]
	v_mfma_f32_16x16x32_bf16 v[140:143], v[100:103], v[152:155], v[140:143]
	v_mfma_f32_16x16x32_bf16 v[128:131], v[92:95], v[176:179], v[128:131]
	v_mfma_f32_16x16x32_bf16 v[128:131], v[100:103], v[180:183], v[128:131]
	v_mfma_f32_16x16x32_bf16 v[120:123], v[92:95], v[184:187], v[120:123]
	v_mfma_f32_16x16x32_bf16 v[120:123], v[100:103], v[188:191], v[120:123]
	v_mfma_f32_16x16x32_bf16 v[112:115], v[92:95], v[192:195], v[112:115]
	v_mfma_f32_16x16x32_bf16 v[112:115], v[100:103], v[212:215], v[112:115]
	v_mfma_f32_16x16x32_bf16 v[136:139], v[132:135], v[148:151], v[136:139]
	v_mfma_f32_16x16x32_bf16 v[136:139], v[144:147], v[152:155], v[136:139]
	v_mfma_f32_16x16x32_bf16 v[124:127], v[132:135], v[176:179], v[124:127]
	v_mfma_f32_16x16x32_bf16 v[124:127], v[144:147], v[180:183], v[124:127]
	v_mfma_f32_16x16x32_bf16 v[116:119], v[132:135], v[184:187], v[116:119]
	v_mfma_f32_16x16x32_bf16 v[116:119], v[144:147], v[188:191], v[116:119]
	v_mfma_f32_16x16x32_bf16 v[108:111], v[132:135], v[192:195], v[108:111]
	v_mfma_f32_16x16x32_bf16 v[108:111], v[144:147], v[212:215], v[108:111]
	s_barrier
	s_setprio 0
	s_add_i32 s10, 0, 0x1c000
	s_add_i32 s11, s44, s29
	v_add_u32_e32 v2, s10, v167
	v_lshl_add_u64 v[196:197], v[196:197], 0, s[52:53]
	s_mov_b32 m0, s11
	ds_read_b128 v[216:219], v2
	ds_read_b128 v[220:223], v2 offset:1024
	ds_read_b128 v[224:227], v2 offset:2048
	ds_read_b128 v[228:231], v2 offset:3072
	global_load_lds_dwordx4 v[196:197], off
	v_lshl_add_u64 v[196:197], v[232:233], 0, s[52:53]
	s_add_i32 m0, s11, 0x2000
	s_nop 0
	global_load_lds_dwordx4 v[196:197], off
	s_barrier
	s_waitcnt lgkmcnt(0)
	s_setprio 1
	v_mfma_f32_16x16x32_bf16 v[64:67], v[216:219], v[148:151], v[64:67]
	v_mfma_f32_16x16x32_bf16 v[64:67], v[220:223], v[152:155], v[64:67]
	v_mfma_f32_16x16x32_bf16 v[56:59], v[216:219], v[176:179], v[56:59]
	v_mfma_f32_16x16x32_bf16 v[56:59], v[220:223], v[180:183], v[56:59]
	v_mfma_f32_16x16x32_bf16 v[48:51], v[216:219], v[184:187], v[48:51]
	v_mfma_f32_16x16x32_bf16 v[48:51], v[220:223], v[188:191], v[48:51]
	v_mfma_f32_16x16x32_bf16 v[40:43], v[216:219], v[192:195], v[40:43]
	v_mfma_f32_16x16x32_bf16 v[40:43], v[220:223], v[212:215], v[40:43]
	v_mfma_f32_16x16x32_bf16 v[60:63], v[224:227], v[148:151], v[60:63]
	v_mfma_f32_16x16x32_bf16 v[60:63], v[228:231], v[152:155], v[60:63]
	v_mfma_f32_16x16x32_bf16 v[52:55], v[224:227], v[176:179], v[52:55]
	v_mfma_f32_16x16x32_bf16 v[52:55], v[228:231], v[180:183], v[52:55]
	v_mfma_f32_16x16x32_bf16 v[44:47], v[224:227], v[184:187], v[44:47]
	v_mfma_f32_16x16x32_bf16 v[44:47], v[228:231], v[188:191], v[44:47]
	v_mfma_f32_16x16x32_bf16 v[36:39], v[224:227], v[192:195], v[36:39]
	v_mfma_f32_16x16x32_bf16 v[36:39], v[228:231], v[212:215], v[36:39]
	s_mov_b32 m0, s37
	v_lshl_add_u64 v[196:197], v[234:235], 0, s[52:53]
	s_barrier
	s_setprio 0
	ds_read_b128 v[148:151], v169 offset:49152
	ds_read_b128 v[152:155], v169 offset:50176
	ds_read_b128 v[176:179], v169 offset:51200
	ds_read_b128 v[180:183], v169 offset:52224
	ds_read_b128 v[184:187], v169 offset:53248
	ds_read_b128 v[188:191], v169 offset:54272
	ds_read_b128 v[192:195], v169 offset:55296
	ds_read_b128 v[212:215], v169 offset:56320
	global_load_lds_dwordx4 v[196:197], off
	v_lshl_add_u64 v[196:197], v[236:237], 0, s[52:53]
	s_mov_b32 m0, s38
	s_nop 0
	global_load_lds_dwordx4 v[196:197], off
	s_barrier
	s_waitcnt lgkmcnt(0)
	s_setprio 1
	v_mfma_f32_16x16x32_bf16 v[104:107], v[92:95], v[148:151], v[104:107]
	v_mfma_f32_16x16x32_bf16 v[104:107], v[100:103], v[152:155], v[104:107]
	v_mfma_f32_16x16x32_bf16 v[88:91], v[92:95], v[176:179], v[88:91]
	v_mfma_f32_16x16x32_bf16 v[88:91], v[100:103], v[180:183], v[88:91]
	v_mfma_f32_16x16x32_bf16 v[80:83], v[92:95], v[184:187], v[80:83]
	v_mfma_f32_16x16x32_bf16 v[80:83], v[100:103], v[188:191], v[80:83]
	v_mfma_f32_16x16x32_bf16 v[72:75], v[92:95], v[192:195], v[72:75]
	v_mfma_f32_16x16x32_bf16 v[72:75], v[100:103], v[212:215], v[72:75]
	v_mfma_f32_16x16x32_bf16 v[96:99], v[132:135], v[148:151], v[96:99]
	v_mfma_f32_16x16x32_bf16 v[96:99], v[144:147], v[152:155], v[96:99]
	v_mfma_f32_16x16x32_bf16 v[84:87], v[132:135], v[176:179], v[84:87]
	v_mfma_f32_16x16x32_bf16 v[84:87], v[144:147], v[180:183], v[84:87]
	v_mfma_f32_16x16x32_bf16 v[76:79], v[132:135], v[184:187], v[76:79]
	v_mfma_f32_16x16x32_bf16 v[76:79], v[144:147], v[188:191], v[76:79]
	v_mfma_f32_16x16x32_bf16 v[68:71], v[132:135], v[192:195], v[68:71]
	v_mfma_f32_16x16x32_bf16 v[68:71], v[144:147], v[212:215], v[68:71]
	s_barrier
	s_setprio 0
	s_add_u32 s6, s6, 0x20080
	s_addc_u32 s7, s7, 0
	s_add_i32 s10, s10, s29
	v_lshl_add_u64 v[92:93], s[6:7], 0, v[158:159]
	s_mov_b32 m0, s10
	s_nop 0
	global_load_lds_dwordx4 v[92:93], off
	v_lshl_add_u64 v[92:93], s[6:7], 0, v[0:1]
	s_add_i32 m0, s10, 0x2000
	s_nop 0
	global_load_lds_dwordx4 v[92:93], off
	s_waitcnt vmcnt(6)
	s_barrier
	s_setprio 1
	v_mfma_f32_16x16x32_bf16 v[32:35], v[216:219], v[148:151], v[32:35]
	v_mfma_f32_16x16x32_bf16 v[32:35], v[220:223], v[152:155], v[32:35]
	v_mfma_f32_16x16x32_bf16 v[24:27], v[216:219], v[176:179], v[24:27]
	v_mfma_f32_16x16x32_bf16 v[24:27], v[220:223], v[180:183], v[24:27]
	v_mfma_f32_16x16x32_bf16 v[16:19], v[216:219], v[184:187], v[16:19]
	v_mfma_f32_16x16x32_bf16 v[16:19], v[220:223], v[188:191], v[16:19]
	v_mfma_f32_16x16x32_bf16 v[8:11], v[216:219], v[192:195], v[8:11]
	v_mfma_f32_16x16x32_bf16 v[8:11], v[220:223], v[212:215], v[8:11]
	v_mfma_f32_16x16x32_bf16 v[28:31], v[224:227], v[148:151], v[28:31]
	v_mfma_f32_16x16x32_bf16 v[28:31], v[228:231], v[152:155], v[28:31]
	v_mfma_f32_16x16x32_bf16 v[20:23], v[224:227], v[176:179], v[20:23]
	v_mfma_f32_16x16x32_bf16 v[20:23], v[228:231], v[180:183], v[20:23]
	v_mfma_f32_16x16x32_bf16 v[12:15], v[224:227], v[184:187], v[12:15]
	v_mfma_f32_16x16x32_bf16 v[12:15], v[228:231], v[188:191], v[12:15]
	v_mfma_f32_16x16x32_bf16 v[4:7], v[224:227], v[192:195], v[4:7]
	v_mfma_f32_16x16x32_bf16 v[4:7], v[228:231], v[212:215], v[4:7]
	s_add_i32 s43, s43, 2
	s_add_u32 s41, s41, 0x100
	s_addc_u32 s42, s42, 0
	s_add_u32 s4, s4, 0x100
	s_addc_u32 s5, s5, 0
	s_cmp_gt_u32 s43, 5
	s_barrier
; __device__ __forceinline__ size_t pidx(size_t row, int col) { return ((size_t)(col >> 8) * MTOK + row) * PLD + (col & 255); }
; __device__ __forceinline__ float bflo(unsigned v) { return __uint_as_float(v << 16); }
; __device__ __forceinline__ float bfhi(unsigned v) { return __uint_as_float(v & 0xffff0000u); }
; __device__ __forceinline__ float siluf_(float x) { return x * __builtin_amdgcn_rcpf(1.0f + __expf(-x)); }
;   __device__ __forceinline__ void operator()(EPI_ARGS) const {
;     const size_t row0 = (size_t)u.pm * 256 + wr * 64 + fr;
;     const int col0 = u.pn * 256 + wc * 32 + 8 * fq;
; #pragma unroll
;     for (int bj = 0; bj < 2; ++bj) {
;       const int c = col0 + bj * HALF;
;       const f32x4 s0 = *(const f32x4*)(psc + c), s1 = *(const f32x4*)(psc + c + 4);
; #pragma unroll
;       for (int ai = 0; ai < 2; ++ai) {
;         u32x4 z[4];
; #pragma unroll
;         for (int m = 0; m < 4; ++m) z[m] = *(const u32x4*)(proj + pidx(row0 + ai * HALF + m * 16, PZ + c));
;         __builtin_amdgcn_sched_barrier(0);
; #pragma unroll
;         for (int m = 0; m < 4; ++m) {
;           const size_t row = row0 + ai * HALF + m * 16;
;           const f32x4 v0 = acc[ai][bj][m][0], v1 = acc[ai][bj][m][1];
;           u32x4 o;
;           o.x = pack2(v0[0] * s0[0] * siluf_(bflo(z[m].x)), v0[1] * s0[1] * siluf_(bfhi(z[m].x)));
;           o.y = pack2(v0[2] * s0[2] * siluf_(bflo(z[m].y)), v0[3] * s0[3] * siluf_(bfhi(z[m].y)));
;           o.z = pack2(v1[0] * s1[0] * siluf_(bflo(z[m].z)), v1[1] * s1[1] * siluf_(bfhi(z[m].z)));
;           o.w = pack2(v1[2] * s1[2] * siluf_(bflo(z[m].w)), v1[3] * s1[3] * siluf_(bfhi(z[m].w)));
;           *(u32x4*)(y0 + row * DM + c) = o;
	s_setprio 0
	s_cbranch_scc0 .LBB0_485
	s_ashr_i32 s3, s2, 31
	s_lshl_b64 s[2:3], s[2:3], 8
	v_lshl_add_u64 v[186:187], s[2:3], 0, v[162:163]
	s_lshl_b32 s2, s33, 8
	v_or_b32_e32 v196, s2, v168
	s_addk_i32 s2, 0x800
	s_ashr_i32 s2, s2, 8
	s_ashr_i32 s3, s2, 31
	s_lshl_b64 s[2:3], s[2:3], 23
	s_add_u32 s2, s0, s2
	s_addc_u32 s3, s1, s3
	v_lshlrev_b32_e32 v2, 1, v168
	v_or_b32_e32 v194, 16, v186
	v_mov_b32_e32 v195, v187
	v_ashrrev_i32_e32 v197, 31, v196
	v_lshl_add_u64 v[188:189], s[2:3], 0, v[2:3]
	v_lshlrev_b64 v[178:179], 9, v[186:187]
	v_lshlrev_b64 v[180:181], 9, v[194:195]
	v_or_b32_e32 v192, 32, v186
	v_mov_b32_e32 v193, v187
	v_or_b32_e32 v190, 48, v186
	v_mov_b32_e32 v191, v187
	v_lshl_add_u64 v[176:177], v[196:197], 2, s[12:13]
	v_lshl_add_u64 v[132:133], v[188:189], 0, v[178:179]
	v_lshl_add_u64 v[134:135], v[188:189], 0, v[180:181]
	v_lshlrev_b64 v[182:183], 9, v[192:193]
	v_lshlrev_b64 v[184:185], 9, v[190:191]
	global_load_dwordx4 v[92:95], v[176:177], off offset:16
	global_load_dwordx4 v[100:103], v[176:177], off
	flat_load_dwordx4 v[152:155], v[132:133]
	flat_load_dwordx4 v[148:151], v[134:135]
	v_lshl_add_u64 v[132:133], v[188:189], 0, v[182:183]
	v_lshl_add_u64 v[134:135], v[188:189], 0, v[184:185]
	flat_load_dwordx4 v[144:147], v[132:133]
	s_nop 0
	flat_load_dwordx4 v[132:135], v[134:135]
	s_waitcnt vmcnt(0) lgkmcnt(0)
	v_lshlrev_b32_e32 v213, 16, v152
	v_mul_f32_e32 v2, 0xbfb8aa3b, v213
	v_exp_f32_e32 v2, v2
	v_mov_b32_e32 v214, v140
	v_mov_b32_e32 v212, v100
	s_mov_b64 s[4:5], 0x90
	v_add_f32_e32 v2, 1.0, v2
	v_rcp_f32_e32 v215, v2
	s_nop 0
	v_pk_mul_f32 v[212:213], v[214:215], v[212:213]
	s_nop 0
	v_mul_f32_e32 v2, v212, v213
	v_and_b32_e32 v213, 0xffff0000, v152
	v_mul_f32_e32 v140, 0xbfb8aa3b, v213
	v_exp_f32_e32 v140, v140
	v_mov_b32_e32 v214, v141
	v_mov_b32_e32 v212, v101
	v_add_f32_e32 v140, 1.0, v140
	v_rcp_f32_e32 v215, v140
	s_nop 0
	v_pk_mul_f32 v[140:141], v[214:215], v[212:213]
	s_nop 0
	v_mul_f32_e32 v140, v140, v141
	v_lshlrev_b32_e32 v141, 16, v153
	v_cvt_pk_bf16_f32 v152, v2, v140
	v_mul_f32_e32 v2, 0xbfb8aa3b, v141
	v_exp_f32_e32 v2, v2
	v_mov_b32_e32 v212, v142
	v_mov_b32_e32 v140, v102
	v_mov_b32_e32 v142, v136
	v_add_f32_e32 v2, 1.0, v2
	v_rcp_f32_e32 v213, v2
	s_nop 0
	v_pk_mul_f32 v[140:141], v[212:213], v[140:141]
	s_nop 0
	v_mul_f32_e32 v2, v140, v141
	v_and_b32_e32 v141, 0xffff0000, v153
	v_mul_f32_e32 v140, 0xbfb8aa3b, v141
	v_exp_f32_e32 v140, v140
	v_mov_b32_e32 v212, v143
	v_add_f32_e32 v140, 1.0, v140
	v_rcp_f32_e32 v213, v140
	v_mov_b32_e32 v140, v103
	v_pk_mul_f32 v[140:141], v[212:213], v[140:141]
	s_nop 0
	v_mul_f32_e32 v140, v140, v141
	v_lshlrev_b32_e32 v141, 16, v154
	v_cvt_pk_bf16_f32 v153, v2, v140
	v_mul_f32_e32 v2, 0xbfb8aa3b, v141
	v_exp_f32_e32 v2, v2
	v_mov_b32_e32 v140, v92
	v_add_f32_e32 v2, 1.0, v2
	v_rcp_f32_e32 v143, v2
	s_nop 0
	v_pk_mul_f32 v[140:141], v[142:143], v[140:141]
	s_nop 0
	v_mul_f32_e32 v2, v140, v141
	v_and_b32_e32 v141, 0xffff0000, v154
	v_mul_f32_e32 v136, 0xbfb8aa3b, v141
	v_exp_f32_e32 v136, v136
	v_mov_b32_e32 v142, v137
	v_mov_b32_e32 v140, v93
	v_add_f32_e32 v136, 1.0, v136
	v_rcp_f32_e32 v143, v136
	s_nop 0
	v_pk_mul_f32 v[136:137], v[142:143], v[140:141]
	s_nop 0
	v_mul_f32_e32 v136, v136, v137
	v_lshlrev_b32_e32 v137, 16, v155
	v_cvt_pk_bf16_f32 v154, v2, v136
	v_mul_f32_e32 v2, 0xbfb8aa3b, v137
	v_exp_f32_e32 v2, v2
	v_mov_b32_e32 v140, v138
	v_mov_b32_e32 v136, v94
	v_mov_b32_e32 v142, v128
	v_add_f32_e32 v2, 1.0, v2
	v_rcp_f32_e32 v141, v2
	v_mov_b32_e32 v138, v100
	v_pk_mul_f32 v[136:137], v[140:141], v[136:137]
	s_nop 0
	v_mul_f32_e32 v2, v136, v137
	v_and_b32_e32 v137, 0xffff0000, v155
	v_mul_f32_e32 v136, 0xbfb8aa3b, v137
	v_exp_f32_e32 v136, v136
	v_mov_b32_e32 v140, v139
	v_lshlrev_b32_e32 v139, 16, v148
	v_add_f32_e32 v136, 1.0, v136
	v_rcp_f32_e32 v141, v136
	v_mov_b32_e32 v136, v95
	v_pk_mul_f32 v[136:137], v[140:141], v[136:137]
	s_nop 0
	v_mul_f32_e32 v136, v136, v137
	v_cvt_pk_bf16_f32 v155, v2, v136
	v_mul_f32_e32 v2, 0xbfb8aa3b, v139
	v_exp_f32_e32 v2, v2
	v_lshlrev_b64 v[140:141], 1, v[196:197]
	v_lshlrev_b64 v[136:137], 12, v[186:187]
	v_lshl_add_u64 v[136:137], s[8:9], 0, v[136:137]
	v_add_f32_e32 v2, 1.0, v2
	v_rcp_f32_e32 v143, v2
	v_lshl_add_u64 v[136:137], v[136:137], 0, v[140:141]
	flat_store_dwordx4 v[136:137], v[152:155]
	v_pk_mul_f32 v[138:139], v[142:143], v[138:139]
	s_nop 0
	v_mul_f32_e32 v2, v138, v139
	v_and_b32_e32 v139, 0xffff0000, v148
	v_mul_f32_e32 v128, 0xbfb8aa3b, v139
	v_exp_f32_e32 v128, v128
	v_mov_b32_e32 v142, v129
	v_mov_b32_e32 v138, v101
	v_add_f32_e32 v128, 1.0, v128
	v_rcp_f32_e32 v143, v128
	s_nop 0
	v_pk_mul_f32 v[128:129], v[142:143], v[138:139]
	s_nop 0
	v_mul_f32_e32 v128, v128, v129
	v_lshlrev_b32_e32 v139, 16, v149
	v_cvt_pk_bf16_f32 v128, v2, v128
	v_mul_f32_e32 v2, 0xbfb8aa3b, v139
	v_exp_f32_e32 v2, v2
	v_mov_b32_e32 v142, v130
	v_mov_b32_e32 v138, v102
	v_add_f32_e32 v2, 1.0, v2
	v_rcp_f32_e32 v143, v2
	s_nop 0
	v_pk_mul_f32 v[138:139], v[142:143], v[138:139]
	s_nop 0
	v_mul_f32_e32 v2, v138, v139
	v_and_b32_e32 v139, 0xffff0000, v149
	v_mul_f32_e32 v129, 0xbfb8aa3b, v139
	v_exp_f32_e32 v129, v129
	v_mov_b32_e32 v142, v131
	v_mov_b32_e32 v138, v103
	v_lshl_add_u64 v[148:149], v[186:187], 0, s[52:53]
	v_add_f32_e32 v129, 1.0, v129
	v_rcp_f32_e32 v143, v129
	s_nop 0
	v_pk_mul_f32 v[130:131], v[142:143], v[138:139]
	s_nop 0
	v_mul_f32_e32 v129, v130, v131
	v_lshlrev_b32_e32 v131, 16, v150
	v_cvt_pk_bf16_f32 v129, v2, v129
	v_mul_f32_e32 v2, 0xbfb8aa3b, v131
	v_exp_f32_e32 v2, v2
	v_mov_b32_e32 v138, v124
	v_mov_b32_e32 v130, v92
	v_add_f32_e32 v2, 1.0, v2
	v_rcp_f32_e32 v139, v2
	s_nop 0
; __device__ __forceinline__ float bflo(unsigned v) { return __uint_as_float(v << 16); }
; __device__ __forceinline__ float bfhi(unsigned v) { return __uint_as_float(v & 0xffff0000u); }
; __device__ __forceinline__ float siluf_(float x) { return x * __builtin_amdgcn_rcpf(1.0f + __expf(-x)); }
;   __device__ __forceinline__ void operator()(EPI_ARGS) const {
;     ...
;         for (int m = 0; m < 4; ++m) {
;           const size_t row = row0 + ai * HALF + m * 16;
;           const f32x4 v0 = acc[ai][bj][m][0], v1 = acc[ai][bj][m][1];
;           u32x4 o;
;           o.x = pack2(v0[0] * s0[0] * siluf_(bflo(z[m].x)), v0[1] * s0[1] * siluf_(bfhi(z[m].x)));
;           o.y = pack2(v0[2] * s0[2] * siluf_(bflo(z[m].y)), v0[3] * s0[3] * siluf_(bfhi(z[m].y)));
;           o.z = pack2(v1[0] * s1[0] * siluf_(bflo(z[m].z)), v1[1] * s1[1] * siluf_(bfhi(z[m].z)));
;           o.w = pack2(v1[2] * s1[2] * siluf_(bflo(z[m].w)), v1[3] * s1[3] * siluf_(bfhi(z[m].w)));
;           *(u32x4*)(y0 + row * DM + c) = o;
	v_pk_mul_f32 v[130:131], v[138:139], v[130:131]
	s_nop 0
	v_mul_f32_e32 v2, v130, v131
	v_and_b32_e32 v131, 0xffff0000, v150
	v_mul_f32_e32 v124, 0xbfb8aa3b, v131
	v_exp_f32_e32 v124, v124
	v_mov_b32_e32 v138, v125
	v_mov_b32_e32 v130, v93
	v_add_f32_e32 v124, 1.0, v124
	v_rcp_f32_e32 v139, v124
	s_nop 0
	v_pk_mul_f32 v[124:125], v[138:139], v[130:131]
	s_nop 0
	v_mul_f32_e32 v124, v124, v125
	v_lshlrev_b32_e32 v125, 16, v151
	v_cvt_pk_bf16_f32 v130, v2, v124
	v_mul_f32_e32 v2, 0xbfb8aa3b, v125
	v_exp_f32_e32 v2, v2
	v_mov_b32_e32 v138, v126
	v_mov_b32_e32 v124, v94
	v_mov_b32_e32 v126, v100
	v_add_f32_e32 v2, 1.0, v2
	v_rcp_f32_e32 v139, v2
	s_nop 0
	v_pk_mul_f32 v[124:125], v[138:139], v[124:125]
	s_nop 0
	v_mul_f32_e32 v2, v124, v125
	v_and_b32_e32 v125, 0xffff0000, v151
	v_mul_f32_e32 v124, 0xbfb8aa3b, v125
	v_exp_f32_e32 v124, v124
	v_mov_b32_e32 v138, v127
	v_lshlrev_b32_e32 v127, 16, v144
	v_add_f32_e32 v124, 1.0, v124
	v_rcp_f32_e32 v139, v124
	v_mov_b32_e32 v124, v95
	v_pk_mul_f32 v[124:125], v[138:139], v[124:125]
	s_nop 0
	v_mul_f32_e32 v124, v124, v125
	v_cvt_pk_bf16_f32 v131, v2, v124
	v_mul_f32_e32 v2, 0xbfb8aa3b, v127
	v_exp_f32_e32 v2, v2
	v_lshlrev_b64 v[124:125], 12, v[194:195]
	v_lshl_add_u64 v[124:125], s[8:9], 0, v[124:125]
	v_lshl_add_u64 v[124:125], v[124:125], 0, v[140:141]
	v_add_f32_e32 v2, 1.0, v2
	flat_store_dwordx4 v[124:125], v[128:131]
	s_nop 1
	v_rcp_f32_e32 v129, v2
	v_mov_b32_e32 v128, v120
	v_lshlrev_b64 v[130:131], 9, v[148:149]
	v_pk_mul_f32 v[126:127], v[128:129], v[126:127]
	s_nop 0
	v_mul_f32_e32 v2, v126, v127
	v_and_b32_e32 v127, 0xffff0000, v144
	v_mul_f32_e32 v120, 0xbfb8aa3b, v127
	v_exp_f32_e32 v120, v120
	v_mov_b32_e32 v128, v121
	v_mov_b32_e32 v126, v101
	v_add_f32_e32 v120, 1.0, v120
	v_rcp_f32_e32 v129, v120
	s_nop 0
	v_pk_mul_f32 v[120:121], v[128:129], v[126:127]
	s_nop 0
	v_mul_f32_e32 v120, v120, v121
	v_lshlrev_b32_e32 v127, 16, v145
	v_cvt_pk_bf16_f32 v120, v2, v120
	v_mul_f32_e32 v2, 0xbfb8aa3b, v127
	v_exp_f32_e32 v2, v2
	v_mov_b32_e32 v128, v122
	v_mov_b32_e32 v126, v102
	v_add_f32_e32 v2, 1.0, v2
	v_rcp_f32_e32 v129, v2
	s_nop 0
	v_pk_mul_f32 v[126:127], v[128:129], v[126:127]
	s_nop 0
	v_mul_f32_e32 v2, v126, v127
	v_and_b32_e32 v127, 0xffff0000, v145
	v_mul_f32_e32 v121, 0xbfb8aa3b, v127
	v_exp_f32_e32 v121, v121
	v_mov_b32_e32 v128, v123
	v_mov_b32_e32 v126, v103
	v_add_f32_e32 v121, 1.0, v121
	v_rcp_f32_e32 v129, v121
	s_nop 0
	v_pk_mul_f32 v[122:123], v[128:129], v[126:127]
	s_nop 0
	v_mul_f32_e32 v121, v122, v123
	v_lshlrev_b32_e32 v123, 16, v146
	v_cvt_pk_bf16_f32 v121, v2, v121
	v_mul_f32_e32 v2, 0xbfb8aa3b, v123
	v_exp_f32_e32 v2, v2
	v_mov_b32_e32 v126, v116
	v_mov_b32_e32 v122, v92
	v_add_f32_e32 v2, 1.0, v2
	v_rcp_f32_e32 v127, v2
	s_nop 0
	v_pk_mul_f32 v[122:123], v[126:127], v[122:123]
	s_nop 0
	v_mul_f32_e32 v2, v122, v123
	v_and_b32_e32 v123, 0xffff0000, v146
	v_mul_f32_e32 v116, 0xbfb8aa3b, v123
	v_exp_f32_e32 v116, v116
	v_mov_b32_e32 v126, v117
	v_mov_b32_e32 v122, v93
	v_add_f32_e32 v116, 1.0, v116
	v_rcp_f32_e32 v127, v116
	s_nop 0
	v_pk_mul_f32 v[116:117], v[126:127], v[122:123]
	s_nop 0
	v_mul_f32_e32 v116, v116, v117
	v_lshlrev_b32_e32 v117, 16, v147
	v_cvt_pk_bf16_f32 v122, v2, v116
	v_mul_f32_e32 v2, 0xbfb8aa3b, v117
	v_exp_f32_e32 v2, v2
	v_mov_b32_e32 v126, v118
	v_mov_b32_e32 v116, v94
	v_mov_b32_e32 v118, v112
	v_add_f32_e32 v2, 1.0, v2
	v_rcp_f32_e32 v127, v2
	s_nop 0
	v_pk_mul_f32 v[116:117], v[126:127], v[116:117]
	s_nop 0
	v_mul_f32_e32 v2, v116, v117
	v_and_b32_e32 v117, 0xffff0000, v147
	v_mul_f32_e32 v116, 0xbfb8aa3b, v117
	v_exp_f32_e32 v116, v116
	v_mov_b32_e32 v126, v119
	v_lshl_add_u64 v[146:147], v[186:187], 0, s[4:5]
	s_mov_b64 s[4:5], 0xa0
	v_add_f32_e32 v116, 1.0, v116
	v_rcp_f32_e32 v127, v116
	v_mov_b32_e32 v116, v95
	v_lshl_add_u64 v[144:145], v[186:187], 0, s[4:5]
	s_mov_b64 s[4:5], 0xb0
	v_pk_mul_f32 v[116:117], v[126:127], v[116:117]
	v_lshl_add_u64 v[142:143], v[186:187], 0, s[4:5]
	v_mul_f32_e32 v116, v116, v117
	v_cvt_pk_bf16_f32 v123, v2, v116
	v_lshlrev_b64 v[116:117], 12, v[192:193]
	v_lshl_add_u64 v[116:117], s[8:9], 0, v[116:117]
	v_lshl_add_u64 v[128:129], v[116:117], 0, v[140:141]
	v_lshlrev_b32_e32 v117, 16, v132
	v_mul_f32_e32 v2, 0xbfb8aa3b, v117
	v_exp_f32_e32 v2, v2
	v_mov_b32_e32 v116, v100
	flat_store_dwordx4 v[128:129], v[120:123]
	v_lshlrev_b64 v[138:139], 9, v[142:143]
	v_add_f32_e32 v2, 1.0, v2
	v_rcp_f32_e32 v119, v2
	s_nop 0
	v_pk_mul_f32 v[116:117], v[118:119], v[116:117]
	s_nop 0
	v_mul_f32_e32 v2, v116, v117
	v_and_b32_e32 v117, 0xffff0000, v132
	v_mul_f32_e32 v112, 0xbfb8aa3b, v117
	v_exp_f32_e32 v112, v112
	v_mov_b32_e32 v118, v113
	v_mov_b32_e32 v116, v101
	v_add_f32_e32 v112, 1.0, v112
	v_rcp_f32_e32 v119, v112
	s_nop 0
	v_pk_mul_f32 v[112:113], v[118:119], v[116:117]
	s_nop 0
	v_mul_f32_e32 v112, v112, v113
	v_lshlrev_b32_e32 v117, 16, v133
	v_cvt_pk_bf16_f32 v112, v2, v112
	v_mul_f32_e32 v2, 0xbfb8aa3b, v117
	v_exp_f32_e32 v2, v2
	v_mov_b32_e32 v118, v114
	v_mov_b32_e32 v116, v102
	v_add_f32_e32 v2, 1.0, v2
	v_rcp_f32_e32 v119, v2
	s_nop 0
	v_pk_mul_f32 v[116:117], v[118:119], v[116:117]
	s_nop 0
	v_mul_f32_e32 v2, v116, v117
	v_and_b32_e32 v117, 0xffff0000, v133
	v_mul_f32_e32 v113, 0xbfb8aa3b, v117
	v_exp_f32_e32 v113, v113
	v_mov_b32_e32 v118, v115
	v_mov_b32_e32 v116, v103
	v_lshlrev_b64 v[132:133], 9, v[146:147]
	v_add_f32_e32 v113, 1.0, v113
	v_rcp_f32_e32 v119, v113
	s_nop 0
	v_pk_mul_f32 v[114:115], v[118:119], v[116:117]
	s_nop 0
	v_mul_f32_e32 v113, v114, v115
	v_lshlrev_b32_e32 v115, 16, v134
	v_cvt_pk_bf16_f32 v113, v2, v113
	v_mul_f32_e32 v2, 0xbfb8aa3b, v115
	v_exp_f32_e32 v2, v2
; __device__ __forceinline__ size_t pidx(size_t row, int col) { return ((size_t)(col >> 8) * MTOK + row) * PLD + (col & 255); }
; __device__ __forceinline__ float bflo(unsigned v) { return __uint_as_float(v << 16); }
; __device__ __forceinline__ float bfhi(unsigned v) { return __uint_as_float(v & 0xffff0000u); }
; __device__ __forceinline__ float siluf_(float x) { return x * __builtin_amdgcn_rcpf(1.0f + __expf(-x)); }
;   __device__ __forceinline__ void operator()(EPI_ARGS) const {
;     ...
;         for (int m = 0; m < 4; ++m) z[m] = *(const u32x4*)(proj + pidx(row0 + ai * HALF + m * 16, PZ + c));
;         __builtin_amdgcn_sched_barrier(0);
; #pragma unroll
;         for (int m = 0; m < 4; ++m) {
;           const size_t row = row0 + ai * HALF + m * 16;
;           const f32x4 v0 = acc[ai][bj][m][0], v1 = acc[ai][bj][m][1];
;           u32x4 o;
;           o.x = pack2(v0[0] * s0[0] * siluf_(bflo(z[m].x)), v0[1] * s0[1] * siluf_(bfhi(z[m].x)));
;           o.y = pack2(v0[2] * s0[2] * siluf_(bflo(z[m].y)), v0[3] * s0[3] * siluf_(bfhi(z[m].y)));
;           o.z = pack2(v1[0] * s1[0] * siluf_(bflo(z[m].z)), v1[1] * s1[1] * siluf_(bfhi(z[m].z)));
;           o.w = pack2(v1[2] * s1[2] * siluf_(bflo(z[m].w)), v1[3] * s1[3] * siluf_(bfhi(z[m].w)));
;           *(u32x4*)(y0 + row * DM + c) = o;
	v_mov_b32_e32 v116, v108
	v_mov_b32_e32 v114, v92
	v_add_f32_e32 v2, 1.0, v2
	v_rcp_f32_e32 v117, v2
	s_nop 0
	v_pk_mul_f32 v[114:115], v[116:117], v[114:115]
	s_nop 0
	v_mul_f32_e32 v2, v114, v115
	v_and_b32_e32 v115, 0xffff0000, v134
	v_mul_f32_e32 v108, 0xbfb8aa3b, v115
	v_exp_f32_e32 v108, v108
	v_mov_b32_e32 v116, v109
	v_mov_b32_e32 v114, v93
	v_add_f32_e32 v108, 1.0, v108
	v_rcp_f32_e32 v117, v108
	s_nop 0
	v_pk_mul_f32 v[108:109], v[116:117], v[114:115]
	s_nop 0
	v_mul_f32_e32 v108, v108, v109
	v_lshlrev_b32_e32 v109, 16, v135
	v_cvt_pk_bf16_f32 v114, v2, v108
	v_mul_f32_e32 v2, 0xbfb8aa3b, v109
	v_exp_f32_e32 v2, v2
	v_mov_b32_e32 v116, v110
	v_mov_b32_e32 v108, v94
	v_add_f32_e32 v2, 1.0, v2
	v_rcp_f32_e32 v117, v2
	s_nop 0
	v_pk_mul_f32 v[108:109], v[116:117], v[108:109]
	s_nop 0
	v_mul_f32_e32 v2, v108, v109
	v_and_b32_e32 v109, 0xffff0000, v135
	v_mul_f32_e32 v108, 0xbfb8aa3b, v109
	v_exp_f32_e32 v108, v108
	v_mov_b32_e32 v116, v111
	v_lshlrev_b64 v[134:135], 9, v[144:145]
	v_add_f32_e32 v108, 1.0, v108
	v_rcp_f32_e32 v117, v108
	v_mov_b32_e32 v108, v95
	v_pk_mul_f32 v[108:109], v[116:117], v[108:109]
	s_nop 0
	v_mul_f32_e32 v108, v108, v109
	v_cvt_pk_bf16_f32 v115, v2, v108
	v_lshlrev_b64 v[108:109], 12, v[190:191]
	v_lshl_add_u64 v[108:109], s[8:9], 0, v[108:109]
	v_lshl_add_u64 v[126:127], v[108:109], 0, v[140:141]
	flat_store_dwordx4 v[126:127], v[112:115]
	v_lshl_add_u64 v[108:109], v[188:189], 0, v[130:131]
	flat_load_dwordx4 v[120:123], v[108:109]
	v_lshl_add_u64 v[108:109], v[188:189], 0, v[132:133]
	flat_load_dwordx4 v[116:119], v[108:109]
	v_lshl_add_u64 v[108:109], v[188:189], 0, v[134:135]
	flat_load_dwordx4 v[112:115], v[108:109]
	v_lshl_add_u64 v[108:109], v[188:189], 0, v[138:139]
	flat_load_dwordx4 v[108:111], v[108:109]
	s_waitcnt vmcnt(0) lgkmcnt(0)
	v_lshlrev_b32_e32 v151, 16, v120
	v_mul_f32_e32 v2, 0xbfb8aa3b, v151
	v_exp_f32_e32 v2, v2
	v_mov_b32_e32 v152, v104
	v_mov_b32_e32 v150, v100
	v_mov_b32_e32 v175, v3
	v_add_f32_e32 v2, 1.0, v2
	v_rcp_f32_e32 v153, v2
	s_nop 0
	v_pk_mul_f32 v[150:151], v[152:153], v[150:151]
	s_nop 0
	v_mul_f32_e32 v2, v150, v151
	v_and_b32_e32 v151, 0xffff0000, v120
	v_mul_f32_e32 v104, 0xbfb8aa3b, v151
	v_exp_f32_e32 v104, v104
	v_mov_b32_e32 v152, v105
	v_mov_b32_e32 v150, v101
	v_mov_b32_e32 v120, v103
	v_add_f32_e32 v104, 1.0, v104
	v_rcp_f32_e32 v153, v104
	s_nop 0
	v_pk_mul_f32 v[104:105], v[152:153], v[150:151]
	s_nop 0
	v_mul_f32_e32 v104, v104, v105
	v_lshlrev_b32_e32 v151, 16, v121
	v_cvt_pk_bf16_f32 v104, v2, v104
	v_mul_f32_e32 v2, 0xbfb8aa3b, v151
	v_exp_f32_e32 v2, v2
	v_and_b32_e32 v121, 0xffff0000, v121
	v_mul_f32_e32 v105, 0xbfb8aa3b, v121
	v_exp_f32_e32 v105, v105
	v_add_f32_e32 v2, 1.0, v2
	v_rcp_f32_e32 v153, v2
	v_mov_b32_e32 v152, v106
	v_mov_b32_e32 v150, v102
	v_add_f32_e32 v105, 1.0, v105
	v_pk_mul_f32 v[150:151], v[152:153], v[150:151]
	s_nop 0
	v_mul_f32_e32 v2, v150, v151
	v_rcp_f32_e32 v151, v105
	v_mov_b32_e32 v150, v107
	v_pk_mul_f32 v[106:107], v[150:151], v[120:121]
	s_nop 0
	v_mul_f32_e32 v105, v106, v107
	v_lshlrev_b32_e32 v107, 16, v122
	v_cvt_pk_bf16_f32 v105, v2, v105
	v_mul_f32_e32 v2, 0xbfb8aa3b, v107
	v_exp_f32_e32 v2, v2
	v_mov_b32_e32 v120, v96
	v_mov_b32_e32 v106, v92
	v_add_f32_e32 v2, 1.0, v2
	v_rcp_f32_e32 v121, v2
	s_nop 0
	v_pk_mul_f32 v[106:107], v[120:121], v[106:107]
	s_nop 0
	v_mul_f32_e32 v2, v106, v107
	v_and_b32_e32 v107, 0xffff0000, v122
	v_mul_f32_e32 v96, 0xbfb8aa3b, v107
	v_exp_f32_e32 v96, v96
	v_mov_b32_e32 v120, v97
	v_mov_b32_e32 v106, v93
	v_add_f32_e32 v96, 1.0, v96
	v_rcp_f32_e32 v121, v96
	s_nop 0
	v_pk_mul_f32 v[96:97], v[120:121], v[106:107]
	s_nop 0
	v_mul_f32_e32 v96, v96, v97
	v_lshlrev_b32_e32 v97, 16, v123
	v_cvt_pk_bf16_f32 v106, v2, v96
	v_mul_f32_e32 v2, 0xbfb8aa3b, v97
	v_exp_f32_e32 v2, v2
	v_mov_b32_e32 v120, v98
	v_mov_b32_e32 v96, v94
	v_mov_b32_e32 v98, v100
	v_add_f32_e32 v2, 1.0, v2
	v_rcp_f32_e32 v121, v2
	s_nop 0
	v_pk_mul_f32 v[96:97], v[120:121], v[96:97]
	s_nop 0
	v_mul_f32_e32 v2, v96, v97
	v_and_b32_e32 v97, 0xffff0000, v123
	v_mul_f32_e32 v96, 0xbfb8aa3b, v97
	v_exp_f32_e32 v96, v96
	v_mov_b32_e32 v120, v99
	v_lshlrev_b32_e32 v99, 16, v116
	v_add_f32_e32 v96, 1.0, v96
	v_rcp_f32_e32 v121, v96
	v_mov_b32_e32 v96, v95
	v_pk_mul_f32 v[96:97], v[120:121], v[96:97]
	s_nop 0
	v_mul_f32_e32 v96, v96, v97
	v_cvt_pk_bf16_f32 v107, v2, v96
	v_mul_f32_e32 v2, 0xbfb8aa3b, v99
	v_exp_f32_e32 v2, v2
	v_lshlrev_b64 v[96:97], 12, v[148:149]
	v_lshl_add_u64 v[96:97], s[8:9], 0, v[96:97]
	v_lshl_add_u64 v[96:97], v[96:97], 0, v[140:141]
	v_add_f32_e32 v2, 1.0, v2
	flat_store_dwordx4 v[96:97], v[104:107]
	s_nop 1
	v_rcp_f32_e32 v105, v2
	v_mov_b32_e32 v104, v88
	v_pk_mul_f32 v[98:99], v[104:105], v[98:99]
	s_nop 0
	v_mul_f32_e32 v2, v98, v99
	v_and_b32_e32 v99, 0xffff0000, v116
	v_mul_f32_e32 v88, 0xbfb8aa3b, v99
	v_exp_f32_e32 v88, v88
	v_mov_b32_e32 v104, v89
	v_mov_b32_e32 v98, v101
	v_add_f32_e32 v88, 1.0, v88
	v_rcp_f32_e32 v105, v88
	s_nop 0
	v_pk_mul_f32 v[88:89], v[104:105], v[98:99]
	s_nop 0
	v_mul_f32_e32 v88, v88, v89
	v_lshlrev_b32_e32 v99, 16, v117
	v_cvt_pk_bf16_f32 v88, v2, v88
	v_mul_f32_e32 v2, 0xbfb8aa3b, v99
	v_exp_f32_e32 v2, v2
	v_mov_b32_e32 v104, v90
	v_mov_b32_e32 v98, v102
	v_add_f32_e32 v2, 1.0, v2
	v_rcp_f32_e32 v105, v2
	s_nop 0
	v_pk_mul_f32 v[98:99], v[104:105], v[98:99]
	s_nop 0
	v_mul_f32_e32 v2, v98, v99
	v_and_b32_e32 v99, 0xffff0000, v117
	v_mul_f32_e32 v89, 0xbfb8aa3b, v99
	v_exp_f32_e32 v89, v89
	v_mov_b32_e32 v104, v91
	v_mov_b32_e32 v98, v103
	v_add_f32_e32 v89, 1.0, v89
	v_rcp_f32_e32 v105, v89
	s_nop 0
	v_pk_mul_f32 v[90:91], v[104:105], v[98:99]
	s_nop 0
; __device__ __forceinline__ float bflo(unsigned v) { return __uint_as_float(v << 16); }
; __device__ __forceinline__ float bfhi(unsigned v) { return __uint_as_float(v & 0xffff0000u); }
; __device__ __forceinline__ float siluf_(float x) { return x * __builtin_amdgcn_rcpf(1.0f + __expf(-x)); }
;   __device__ __forceinline__ void operator()(EPI_ARGS) const {
;     ...
;         for (int m = 0; m < 4; ++m) {
;           const size_t row = row0 + ai * HALF + m * 16;
;           const f32x4 v0 = acc[ai][bj][m][0], v1 = acc[ai][bj][m][1];
;           u32x4 o;
;           o.x = pack2(v0[0] * s0[0] * siluf_(bflo(z[m].x)), v0[1] * s0[1] * siluf_(bfhi(z[m].x)));
;           o.y = pack2(v0[2] * s0[2] * siluf_(bflo(z[m].y)), v0[3] * s0[3] * siluf_(bfhi(z[m].y)));
;           o.z = pack2(v1[0] * s1[0] * siluf_(bflo(z[m].z)), v1[1] * s1[1] * siluf_(bfhi(z[m].z)));
;           o.w = pack2(v1[2] * s1[2] * siluf_(bflo(z[m].w)), v1[3] * s1[3] * siluf_(bfhi(z[m].w)));
;           *(u32x4*)(y0 + row * DM + c) = o;
	v_mul_f32_e32 v89, v90, v91
	v_lshlrev_b32_e32 v91, 16, v118
	v_cvt_pk_bf16_f32 v89, v2, v89
	v_mul_f32_e32 v2, 0xbfb8aa3b, v91
	v_exp_f32_e32 v2, v2
	v_mov_b32_e32 v98, v84
	v_mov_b32_e32 v90, v92
	v_add_f32_e32 v2, 1.0, v2
	v_rcp_f32_e32 v99, v2
	s_nop 0
	v_pk_mul_f32 v[90:91], v[98:99], v[90:91]
	s_nop 0
	v_mul_f32_e32 v2, v90, v91
	v_and_b32_e32 v91, 0xffff0000, v118
	v_mul_f32_e32 v84, 0xbfb8aa3b, v91
	v_exp_f32_e32 v84, v84
	v_mov_b32_e32 v98, v85
	v_mov_b32_e32 v90, v93
	v_add_f32_e32 v84, 1.0, v84
	v_rcp_f32_e32 v99, v84
	s_nop 0
	v_pk_mul_f32 v[84:85], v[98:99], v[90:91]
	s_nop 0
	v_mul_f32_e32 v84, v84, v85
	v_lshlrev_b32_e32 v85, 16, v119
	v_cvt_pk_bf16_f32 v90, v2, v84
	v_mul_f32_e32 v2, 0xbfb8aa3b, v85
	v_exp_f32_e32 v2, v2
	v_mov_b32_e32 v98, v86
	v_mov_b32_e32 v84, v94
	v_mov_b32_e32 v86, v80
	v_add_f32_e32 v2, 1.0, v2
	v_rcp_f32_e32 v99, v2
	s_nop 0
	v_pk_mul_f32 v[84:85], v[98:99], v[84:85]
	s_nop 0
	v_mul_f32_e32 v2, v84, v85
	v_and_b32_e32 v85, 0xffff0000, v119
	v_mul_f32_e32 v84, 0xbfb8aa3b, v85
	v_exp_f32_e32 v84, v84
	v_mov_b32_e32 v98, v87
	v_add_f32_e32 v84, 1.0, v84
	v_rcp_f32_e32 v99, v84
	v_mov_b32_e32 v84, v95
	v_pk_mul_f32 v[84:85], v[98:99], v[84:85]
	s_nop 0
	v_mul_f32_e32 v84, v84, v85
	v_cvt_pk_bf16_f32 v91, v2, v84
	v_lshlrev_b64 v[84:85], 12, v[146:147]
	v_lshl_add_u64 v[84:85], s[8:9], 0, v[84:85]
	v_lshl_add_u64 v[98:99], v[84:85], 0, v[140:141]
	v_lshlrev_b32_e32 v85, 16, v112
	v_mul_f32_e32 v2, 0xbfb8aa3b, v85
	v_exp_f32_e32 v2, v2
	v_mov_b32_e32 v84, v100
	flat_store_dwordx4 v[98:99], v[88:91]
	v_add_f32_e32 v2, 1.0, v2
	v_rcp_f32_e32 v87, v2
	s_nop 0
	v_pk_mul_f32 v[84:85], v[86:87], v[84:85]
	s_nop 0
	v_mul_f32_e32 v2, v84, v85
	v_and_b32_e32 v85, 0xffff0000, v112
	v_mul_f32_e32 v80, 0xbfb8aa3b, v85
	v_exp_f32_e32 v80, v80
	v_mov_b32_e32 v86, v81
	v_mov_b32_e32 v84, v101
	v_add_f32_e32 v80, 1.0, v80
	v_rcp_f32_e32 v87, v80
	s_nop 0
	v_pk_mul_f32 v[80:81], v[86:87], v[84:85]
	s_nop 0
	v_mul_f32_e32 v80, v80, v81
	v_lshlrev_b32_e32 v85, 16, v113
	v_cvt_pk_bf16_f32 v80, v2, v80
	v_mul_f32_e32 v2, 0xbfb8aa3b, v85
	v_exp_f32_e32 v2, v2
	v_mov_b32_e32 v86, v82
	v_mov_b32_e32 v84, v102
	v_add_f32_e32 v2, 1.0, v2
	v_rcp_f32_e32 v87, v2
	s_nop 0
	v_pk_mul_f32 v[84:85], v[86:87], v[84:85]
	s_nop 0
	v_mul_f32_e32 v2, v84, v85
	v_and_b32_e32 v85, 0xffff0000, v113
	v_mul_f32_e32 v81, 0xbfb8aa3b, v85
	v_exp_f32_e32 v81, v81
	v_mov_b32_e32 v86, v83
	v_mov_b32_e32 v84, v103
	v_add_f32_e32 v81, 1.0, v81
	v_rcp_f32_e32 v87, v81
	s_nop 0
	v_pk_mul_f32 v[82:83], v[86:87], v[84:85]
	s_nop 0
	v_mul_f32_e32 v81, v82, v83
	v_lshlrev_b32_e32 v83, 16, v114
	v_cvt_pk_bf16_f32 v81, v2, v81
	v_mul_f32_e32 v2, 0xbfb8aa3b, v83
	v_exp_f32_e32 v2, v2
	v_mov_b32_e32 v84, v76
	v_mov_b32_e32 v82, v92
	v_add_f32_e32 v2, 1.0, v2
	v_rcp_f32_e32 v85, v2
	s_nop 0
	v_pk_mul_f32 v[82:83], v[84:85], v[82:83]
	s_nop 0
	v_mul_f32_e32 v2, v82, v83
	v_and_b32_e32 v83, 0xffff0000, v114
	v_mul_f32_e32 v76, 0xbfb8aa3b, v83
	v_exp_f32_e32 v76, v76
	v_mov_b32_e32 v84, v77
	v_mov_b32_e32 v82, v93
	v_add_f32_e32 v76, 1.0, v76
	v_rcp_f32_e32 v85, v76
	s_nop 0
	v_pk_mul_f32 v[76:77], v[84:85], v[82:83]
	s_nop 0
	v_mul_f32_e32 v76, v76, v77
	v_lshlrev_b32_e32 v77, 16, v115
	v_cvt_pk_bf16_f32 v82, v2, v76
	v_mul_f32_e32 v2, 0xbfb8aa3b, v77
	v_exp_f32_e32 v2, v2
	v_mov_b32_e32 v84, v78
	v_mov_b32_e32 v76, v94
	v_mov_b32_e32 v78, v72
	v_add_f32_e32 v2, 1.0, v2
	v_rcp_f32_e32 v85, v2
	s_nop 0
	v_pk_mul_f32 v[76:77], v[84:85], v[76:77]
	s_nop 0
	v_mul_f32_e32 v2, v76, v77
	v_and_b32_e32 v77, 0xffff0000, v115
	v_mul_f32_e32 v76, 0xbfb8aa3b, v77
	v_exp_f32_e32 v76, v76
	v_mov_b32_e32 v84, v79
	v_add_f32_e32 v76, 1.0, v76
	v_rcp_f32_e32 v85, v76
	v_mov_b32_e32 v76, v95
	v_pk_mul_f32 v[76:77], v[84:85], v[76:77]
	s_nop 0
	v_mul_f32_e32 v76, v76, v77
	v_cvt_pk_bf16_f32 v83, v2, v76
	v_lshlrev_b64 v[76:77], 12, v[144:145]
	v_lshl_add_u64 v[76:77], s[8:9], 0, v[76:77]
	v_lshl_add_u64 v[104:105], v[76:77], 0, v[140:141]
	v_lshlrev_b32_e32 v77, 16, v108
	v_mul_f32_e32 v2, 0xbfb8aa3b, v77
	v_exp_f32_e32 v2, v2
	v_mov_b32_e32 v76, v100
	flat_store_dwordx4 v[104:105], v[80:83]
	v_add_f32_e32 v2, 1.0, v2
	v_rcp_f32_e32 v79, v2
	s_nop 0
	v_pk_mul_f32 v[76:77], v[78:79], v[76:77]
	s_nop 0
	v_mul_f32_e32 v2, v76, v77
	v_and_b32_e32 v77, 0xffff0000, v108
	v_mul_f32_e32 v72, 0xbfb8aa3b, v77
	v_exp_f32_e32 v72, v72
	v_mov_b32_e32 v78, v73
	v_mov_b32_e32 v76, v101
	v_add_f32_e32 v72, 1.0, v72
	v_rcp_f32_e32 v79, v72
	s_nop 0
	v_pk_mul_f32 v[72:73], v[78:79], v[76:77]
	s_nop 0
	v_mul_f32_e32 v72, v72, v73
	v_lshlrev_b32_e32 v77, 16, v109
	v_cvt_pk_bf16_f32 v72, v2, v72
	v_mul_f32_e32 v2, 0xbfb8aa3b, v77
	v_exp_f32_e32 v2, v2
	v_mov_b32_e32 v78, v74
	v_mov_b32_e32 v76, v102
	v_add_f32_e32 v2, 1.0, v2
	v_rcp_f32_e32 v79, v2
	s_nop 0
	v_pk_mul_f32 v[76:77], v[78:79], v[76:77]
	s_nop 0
	v_mul_f32_e32 v2, v76, v77
	v_and_b32_e32 v77, 0xffff0000, v109
	v_mul_f32_e32 v73, 0xbfb8aa3b, v77
	v_exp_f32_e32 v73, v73
	v_mov_b32_e32 v78, v75
	v_mov_b32_e32 v76, v103
	v_add_f32_e32 v73, 1.0, v73
	v_rcp_f32_e32 v79, v73
	s_nop 0
	v_pk_mul_f32 v[74:75], v[78:79], v[76:77]
	s_nop 0
	v_mul_f32_e32 v73, v74, v75
	v_lshlrev_b32_e32 v75, 16, v110
	v_cvt_pk_bf16_f32 v73, v2, v73
	v_mul_f32_e32 v2, 0xbfb8aa3b, v75
	v_exp_f32_e32 v2, v2
	v_mov_b32_e32 v76, v68
	v_mov_b32_e32 v74, v92
	v_add_f32_e32 v2, 1.0, v2
	v_rcp_f32_e32 v77, v2
	s_nop 0
	v_pk_mul_f32 v[74:75], v[76:77], v[74:75]
	s_nop 0
	v_mul_f32_e32 v2, v74, v75
	v_and_b32_e32 v75, 0xffff0000, v110
	v_mul_f32_e32 v68, 0xbfb8aa3b, v75
	v_exp_f32_e32 v68, v68
	v_mov_b32_e32 v76, v69
	v_mov_b32_e32 v74, v93
	v_add_f32_e32 v68, 1.0, v68
; __device__ __forceinline__ size_t pidx(size_t row, int col) { return ((size_t)(col >> 8) * MTOK + row) * PLD + (col & 255); }
; __device__ __forceinline__ float bflo(unsigned v) { return __uint_as_float(v << 16); }
; __device__ __forceinline__ float bfhi(unsigned v) { return __uint_as_float(v & 0xffff0000u); }
; __device__ __forceinline__ float siluf_(float x) { return x * __builtin_amdgcn_rcpf(1.0f + __expf(-x)); }
;   __device__ __forceinline__ void operator()(EPI_ARGS) const {
;     ...
;     for (int bj = 0; bj < 2; ++bj) {
;       const int c = col0 + bj * HALF;
;       const f32x4 s0 = *(const f32x4*)(psc + c), s1 = *(const f32x4*)(psc + c + 4);
; #pragma unroll
;       for (int ai = 0; ai < 2; ++ai) {
;         u32x4 z[4];
; #pragma unroll
;         for (int m = 0; m < 4; ++m) z[m] = *(const u32x4*)(proj + pidx(row0 + ai * HALF + m * 16, PZ + c));
;         __builtin_amdgcn_sched_barrier(0);
; #pragma unroll
;         for (int m = 0; m < 4; ++m) {
;           const size_t row = row0 + ai * HALF + m * 16;
;           const f32x4 v0 = acc[ai][bj][m][0], v1 = acc[ai][bj][m][1];
;           u32x4 o;
;           o.x = pack2(v0[0] * s0[0] * siluf_(bflo(z[m].x)), v0[1] * s0[1] * siluf_(bfhi(z[m].x)));
;           o.y = pack2(v0[2] * s0[2] * siluf_(bflo(z[m].y)), v0[3] * s0[3] * siluf_(bfhi(z[m].y)));
;           o.z = pack2(v1[0] * s1[0] * siluf_(bflo(z[m].z)), v1[1] * s1[1] * siluf_(bfhi(z[m].z)));
;           o.w = pack2(v1[2] * s1[2] * siluf_(bflo(z[m].w)), v1[3] * s1[3] * siluf_(bfhi(z[m].w)));
;           *(u32x4*)(y0 + row * DM + c) = o;
	v_rcp_f32_e32 v77, v68
	s_nop 0
	v_pk_mul_f32 v[68:69], v[76:77], v[74:75]
	s_nop 0
	v_mul_f32_e32 v68, v68, v69
	v_lshlrev_b32_e32 v69, 16, v111
	v_cvt_pk_bf16_f32 v74, v2, v68
	v_mul_f32_e32 v2, 0xbfb8aa3b, v69
	v_exp_f32_e32 v2, v2
	v_mov_b32_e32 v76, v70
	v_mov_b32_e32 v68, v94
	v_add_f32_e32 v2, 1.0, v2
	v_rcp_f32_e32 v77, v2
	s_nop 0
	v_pk_mul_f32 v[68:69], v[76:77], v[68:69]
	s_nop 0
	v_mul_f32_e32 v2, v68, v69
	v_and_b32_e32 v69, 0xffff0000, v111
	v_mul_f32_e32 v68, 0xbfb8aa3b, v69
	v_exp_f32_e32 v68, v68
	v_mov_b32_e32 v76, v71
	v_add_f32_e32 v68, 1.0, v68
	v_rcp_f32_e32 v77, v68
	v_mov_b32_e32 v68, v95
	v_lshl_add_u64 v[94:95], s[2:3], 0, v[174:175]
	v_pk_mul_f32 v[68:69], v[76:77], v[68:69]
	s_nop 0
	v_mul_f32_e32 v68, v68, v69
	v_cvt_pk_bf16_f32 v75, v2, v68
	v_lshlrev_b64 v[68:69], 12, v[142:143]
	v_lshl_add_u64 v[68:69], s[8:9], 0, v[68:69]
	v_lshl_add_u64 v[92:93], v[68:69], 0, v[140:141]
	flat_store_dwordx4 v[92:93], v[72:75]
	v_lshl_add_u64 v[76:77], v[94:95], 0, v[178:179]
	global_load_dwordx4 v[68:71], v[176:177], off offset:528
	global_load_dwordx4 v[72:75], v[176:177], off offset:512
	flat_load_dwordx4 v[88:91], v[76:77]
	v_lshl_add_u64 v[76:77], v[94:95], 0, v[180:181]
	flat_load_dwordx4 v[84:87], v[76:77]
	v_lshl_add_u64 v[76:77], v[94:95], 0, v[182:183]
	flat_load_dwordx4 v[80:83], v[76:77]
	v_lshl_add_u64 v[76:77], v[94:95], 0, v[184:185]
	flat_load_dwordx4 v[76:79], v[76:77]
	s_waitcnt vmcnt(0) lgkmcnt(0)
	v_lshlrev_b32_e32 v101, 16, v88
	v_mul_f32_e32 v2, 0xbfb8aa3b, v101
	v_exp_f32_e32 v2, v2
	v_mov_b32_e32 v102, v64
	v_mov_b32_e32 v100, v72
	v_add_f32_e32 v2, 1.0, v2
	v_rcp_f32_e32 v103, v2
	s_nop 0
	v_pk_mul_f32 v[100:101], v[102:103], v[100:101]
	s_nop 0
	v_mul_f32_e32 v2, v100, v101
	v_and_b32_e32 v101, 0xffff0000, v88
	v_mul_f32_e32 v64, 0xbfb8aa3b, v101
	v_exp_f32_e32 v64, v64
	v_mov_b32_e32 v102, v65
	v_mov_b32_e32 v100, v73
	v_mov_b32_e32 v88, v75
	v_add_f32_e32 v64, 1.0, v64
	v_rcp_f32_e32 v103, v64
	s_nop 0
	v_pk_mul_f32 v[64:65], v[102:103], v[100:101]
	s_nop 0
	v_mul_f32_e32 v64, v64, v65
	v_lshlrev_b32_e32 v101, 16, v89
	v_cvt_pk_bf16_f32 v64, v2, v64
	v_mul_f32_e32 v2, 0xbfb8aa3b, v101
	v_exp_f32_e32 v2, v2
	v_and_b32_e32 v89, 0xffff0000, v89
	v_mul_f32_e32 v65, 0xbfb8aa3b, v89
	v_exp_f32_e32 v65, v65
	v_add_f32_e32 v2, 1.0, v2
	v_rcp_f32_e32 v103, v2
	v_mov_b32_e32 v102, v66
	v_mov_b32_e32 v100, v74
	v_add_f32_e32 v65, 1.0, v65
	v_pk_mul_f32 v[100:101], v[102:103], v[100:101]
	s_nop 0
	v_mul_f32_e32 v2, v100, v101
	v_rcp_f32_e32 v101, v65
	v_mov_b32_e32 v100, v67
	v_pk_mul_f32 v[66:67], v[100:101], v[88:89]
	s_nop 0
	v_mul_f32_e32 v65, v66, v67
	v_lshlrev_b32_e32 v67, 16, v90
	v_cvt_pk_bf16_f32 v65, v2, v65
	v_mul_f32_e32 v2, 0xbfb8aa3b, v67
	v_exp_f32_e32 v2, v2
	v_mov_b32_e32 v88, v60
	v_mov_b32_e32 v66, v68
	v_add_f32_e32 v2, 1.0, v2
	v_rcp_f32_e32 v89, v2
	s_nop 0
	v_pk_mul_f32 v[66:67], v[88:89], v[66:67]
	s_nop 0
	v_mul_f32_e32 v2, v66, v67
	v_and_b32_e32 v67, 0xffff0000, v90
	v_mul_f32_e32 v60, 0xbfb8aa3b, v67
	v_exp_f32_e32 v60, v60
	v_mov_b32_e32 v88, v61
	v_mov_b32_e32 v66, v69
	v_add_f32_e32 v60, 1.0, v60
	v_rcp_f32_e32 v89, v60
	s_nop 0
	v_pk_mul_f32 v[60:61], v[88:89], v[66:67]
	s_nop 0
	v_mul_f32_e32 v60, v60, v61
	v_lshlrev_b32_e32 v61, 16, v91
	v_cvt_pk_bf16_f32 v66, v2, v60
	v_mul_f32_e32 v2, 0xbfb8aa3b, v61
	v_exp_f32_e32 v2, v2
	v_mov_b32_e32 v88, v62
	v_mov_b32_e32 v60, v70
	v_mov_b32_e32 v62, v56
	v_add_f32_e32 v2, 1.0, v2
	v_rcp_f32_e32 v89, v2
	s_nop 0
	v_pk_mul_f32 v[60:61], v[88:89], v[60:61]
	s_nop 0
	v_mul_f32_e32 v2, v60, v61
	v_and_b32_e32 v61, 0xffff0000, v91
	v_mul_f32_e32 v60, 0xbfb8aa3b, v61
	v_exp_f32_e32 v60, v60
	v_mov_b32_e32 v88, v63
	v_add_f32_e32 v60, 1.0, v60
	v_rcp_f32_e32 v89, v60
	v_mov_b32_e32 v60, v71
	v_pk_mul_f32 v[60:61], v[88:89], v[60:61]
	s_nop 0
	v_mul_f32_e32 v60, v60, v61
	v_lshlrev_b32_e32 v61, 16, v84
	v_cvt_pk_bf16_f32 v67, v2, v60
	v_mul_f32_e32 v2, 0xbfb8aa3b, v61
	v_exp_f32_e32 v2, v2
	v_mov_b32_e32 v60, v72
	flat_store_dwordx4 v[136:137], v[64:67] offset:256
	v_add_f32_e32 v2, 1.0, v2
	v_rcp_f32_e32 v63, v2
	s_nop 0
	v_pk_mul_f32 v[60:61], v[62:63], v[60:61]
	s_nop 0
	v_mul_f32_e32 v2, v60, v61
	v_and_b32_e32 v61, 0xffff0000, v84
	v_mul_f32_e32 v56, 0xbfb8aa3b, v61
	v_exp_f32_e32 v56, v56
	v_mov_b32_e32 v62, v57
	v_mov_b32_e32 v60, v73
	v_add_f32_e32 v56, 1.0, v56
	v_rcp_f32_e32 v63, v56
	s_nop 0
	v_pk_mul_f32 v[56:57], v[62:63], v[60:61]
	s_nop 0
	v_mul_f32_e32 v56, v56, v57
	v_lshlrev_b32_e32 v61, 16, v85
	v_cvt_pk_bf16_f32 v56, v2, v56
	v_mul_f32_e32 v2, 0xbfb8aa3b, v61
	v_exp_f32_e32 v2, v2
	v_mov_b32_e32 v62, v58
	v_mov_b32_e32 v60, v74
	v_add_f32_e32 v2, 1.0, v2
	v_rcp_f32_e32 v63, v2
	s_nop 0
	v_pk_mul_f32 v[60:61], v[62:63], v[60:61]
	s_nop 0
	v_mul_f32_e32 v2, v60, v61
	v_and_b32_e32 v61, 0xffff0000, v85
	v_mul_f32_e32 v57, 0xbfb8aa3b, v61
	v_exp_f32_e32 v57, v57
	v_mov_b32_e32 v62, v59
	v_mov_b32_e32 v60, v75
	v_add_f32_e32 v57, 1.0, v57
	v_rcp_f32_e32 v63, v57
	s_nop 0
	v_pk_mul_f32 v[58:59], v[62:63], v[60:61]
	s_nop 0
	v_mul_f32_e32 v57, v58, v59
	v_lshlrev_b32_e32 v59, 16, v86
	v_cvt_pk_bf16_f32 v57, v2, v57
	v_mul_f32_e32 v2, 0xbfb8aa3b, v59
	v_exp_f32_e32 v2, v2
	v_mov_b32_e32 v60, v52
	v_mov_b32_e32 v58, v68
	v_add_f32_e32 v2, 1.0, v2
	v_rcp_f32_e32 v61, v2
	s_nop 0
	v_pk_mul_f32 v[58:59], v[60:61], v[58:59]
	s_nop 0
	v_mul_f32_e32 v2, v58, v59
	v_and_b32_e32 v59, 0xffff0000, v86
	v_mul_f32_e32 v52, 0xbfb8aa3b, v59
	v_exp_f32_e32 v52, v52
	v_mov_b32_e32 v60, v53
	v_mov_b32_e32 v58, v69
	v_add_f32_e32 v52, 1.0, v52
	v_rcp_f32_e32 v61, v52
	s_nop 0
	v_pk_mul_f32 v[52:53], v[60:61], v[58:59]
	s_nop 0
	v_mul_f32_e32 v52, v52, v53
; __device__ __forceinline__ size_t pidx(size_t row, int col) { return ((size_t)(col >> 8) * MTOK + row) * PLD + (col & 255); }
; __device__ __forceinline__ float bflo(unsigned v) { return __uint_as_float(v << 16); }
; __device__ __forceinline__ float bfhi(unsigned v) { return __uint_as_float(v & 0xffff0000u); }
; __device__ __forceinline__ float siluf_(float x) { return x * __builtin_amdgcn_rcpf(1.0f + __expf(-x)); }
;   __device__ __forceinline__ void operator()(EPI_ARGS) const {
;     ...
;         for (int m = 0; m < 4; ++m) z[m] = *(const u32x4*)(proj + pidx(row0 + ai * HALF + m * 16, PZ + c));
;         __builtin_amdgcn_sched_barrier(0);
; #pragma unroll
;         for (int m = 0; m < 4; ++m) {
;           const size_t row = row0 + ai * HALF + m * 16;
;           const f32x4 v0 = acc[ai][bj][m][0], v1 = acc[ai][bj][m][1];
;           u32x4 o;
;           o.x = pack2(v0[0] * s0[0] * siluf_(bflo(z[m].x)), v0[1] * s0[1] * siluf_(bfhi(z[m].x)));
;           o.y = pack2(v0[2] * s0[2] * siluf_(bflo(z[m].y)), v0[3] * s0[3] * siluf_(bfhi(z[m].y)));
;           o.z = pack2(v1[0] * s1[0] * siluf_(bflo(z[m].z)), v1[1] * s1[1] * siluf_(bfhi(z[m].z)));
;           o.w = pack2(v1[2] * s1[2] * siluf_(bflo(z[m].w)), v1[3] * s1[3] * siluf_(bfhi(z[m].w)));
;           *(u32x4*)(y0 + row * DM + c) = o;
	v_lshlrev_b32_e32 v53, 16, v87
	v_cvt_pk_bf16_f32 v58, v2, v52
	v_mul_f32_e32 v2, 0xbfb8aa3b, v53
	v_exp_f32_e32 v2, v2
	v_mov_b32_e32 v60, v54
	v_mov_b32_e32 v52, v70
	v_mov_b32_e32 v54, v48
	v_add_f32_e32 v2, 1.0, v2
	v_rcp_f32_e32 v61, v2
	s_nop 0
	v_pk_mul_f32 v[52:53], v[60:61], v[52:53]
	s_nop 0
	v_mul_f32_e32 v2, v52, v53
	v_and_b32_e32 v53, 0xffff0000, v87
	v_mul_f32_e32 v52, 0xbfb8aa3b, v53
	v_exp_f32_e32 v52, v52
	v_mov_b32_e32 v60, v55
	v_add_f32_e32 v52, 1.0, v52
	v_rcp_f32_e32 v61, v52
	v_mov_b32_e32 v52, v71
	v_pk_mul_f32 v[52:53], v[60:61], v[52:53]
	s_nop 0
	v_mul_f32_e32 v52, v52, v53
	v_lshlrev_b32_e32 v53, 16, v80
	v_cvt_pk_bf16_f32 v59, v2, v52
	v_mul_f32_e32 v2, 0xbfb8aa3b, v53
	v_exp_f32_e32 v2, v2
	v_mov_b32_e32 v52, v72
	flat_store_dwordx4 v[124:125], v[56:59] offset:256
	v_add_f32_e32 v2, 1.0, v2
	v_rcp_f32_e32 v55, v2
	s_nop 0
	v_pk_mul_f32 v[52:53], v[54:55], v[52:53]
	s_nop 0
	v_mul_f32_e32 v2, v52, v53
	v_and_b32_e32 v53, 0xffff0000, v80
	v_mul_f32_e32 v48, 0xbfb8aa3b, v53
	v_exp_f32_e32 v48, v48
	v_mov_b32_e32 v54, v49
	v_mov_b32_e32 v52, v73
	v_add_f32_e32 v48, 1.0, v48
	v_rcp_f32_e32 v55, v48
	s_nop 0
	v_pk_mul_f32 v[48:49], v[54:55], v[52:53]
	s_nop 0
	v_mul_f32_e32 v48, v48, v49
	v_lshlrev_b32_e32 v53, 16, v81
	v_cvt_pk_bf16_f32 v48, v2, v48
	v_mul_f32_e32 v2, 0xbfb8aa3b, v53
	v_exp_f32_e32 v2, v2
	v_mov_b32_e32 v54, v50
	v_mov_b32_e32 v52, v74
	v_add_f32_e32 v2, 1.0, v2
	v_rcp_f32_e32 v55, v2
	s_nop 0
	v_pk_mul_f32 v[52:53], v[54:55], v[52:53]
	s_nop 0
	v_mul_f32_e32 v2, v52, v53
	v_and_b32_e32 v53, 0xffff0000, v81
	v_mul_f32_e32 v49, 0xbfb8aa3b, v53
	v_exp_f32_e32 v49, v49
	v_mov_b32_e32 v54, v51
	v_mov_b32_e32 v52, v75
	v_add_f32_e32 v49, 1.0, v49
	v_rcp_f32_e32 v55, v49
	s_nop 0
	v_pk_mul_f32 v[50:51], v[54:55], v[52:53]
	s_nop 0
	v_mul_f32_e32 v49, v50, v51
	v_lshlrev_b32_e32 v51, 16, v82
	v_cvt_pk_bf16_f32 v49, v2, v49
	v_mul_f32_e32 v2, 0xbfb8aa3b, v51
	v_exp_f32_e32 v2, v2
	v_mov_b32_e32 v52, v44
	v_mov_b32_e32 v50, v68
	v_add_f32_e32 v2, 1.0, v2
	v_rcp_f32_e32 v53, v2
	s_nop 0
	v_pk_mul_f32 v[50:51], v[52:53], v[50:51]
	s_nop 0
	v_mul_f32_e32 v2, v50, v51
	v_and_b32_e32 v51, 0xffff0000, v82
	v_mul_f32_e32 v44, 0xbfb8aa3b, v51
	v_exp_f32_e32 v44, v44
	v_mov_b32_e32 v52, v45
	v_mov_b32_e32 v50, v69
	v_add_f32_e32 v44, 1.0, v44
	v_rcp_f32_e32 v53, v44
	s_nop 0
	v_pk_mul_f32 v[44:45], v[52:53], v[50:51]
	s_nop 0
	v_mul_f32_e32 v44, v44, v45
	v_lshlrev_b32_e32 v45, 16, v83
	v_cvt_pk_bf16_f32 v50, v2, v44
	v_mul_f32_e32 v2, 0xbfb8aa3b, v45
	v_exp_f32_e32 v2, v2
	v_mov_b32_e32 v52, v46
	v_mov_b32_e32 v44, v70
	v_mov_b32_e32 v46, v40
	v_add_f32_e32 v2, 1.0, v2
	v_rcp_f32_e32 v53, v2
	s_nop 0
	v_pk_mul_f32 v[44:45], v[52:53], v[44:45]
	s_nop 0
	v_mul_f32_e32 v2, v44, v45
	v_and_b32_e32 v45, 0xffff0000, v83
	v_mul_f32_e32 v44, 0xbfb8aa3b, v45
	v_exp_f32_e32 v44, v44
	v_mov_b32_e32 v52, v47
	v_add_f32_e32 v44, 1.0, v44
	v_rcp_f32_e32 v53, v44
	v_mov_b32_e32 v44, v71
	v_pk_mul_f32 v[44:45], v[52:53], v[44:45]
	s_nop 0
	v_mul_f32_e32 v44, v44, v45
	v_lshlrev_b32_e32 v45, 16, v76
	v_cvt_pk_bf16_f32 v51, v2, v44
	v_mul_f32_e32 v2, 0xbfb8aa3b, v45
	v_exp_f32_e32 v2, v2
	v_mov_b32_e32 v44, v72
	flat_store_dwordx4 v[128:129], v[48:51] offset:256
	v_add_f32_e32 v2, 1.0, v2
	v_rcp_f32_e32 v47, v2
	s_nop 0
	v_pk_mul_f32 v[44:45], v[46:47], v[44:45]
	s_nop 0
	v_mul_f32_e32 v2, v44, v45
	v_and_b32_e32 v45, 0xffff0000, v76
	v_mul_f32_e32 v40, 0xbfb8aa3b, v45
	v_exp_f32_e32 v40, v40
	v_mov_b32_e32 v46, v41
	v_mov_b32_e32 v44, v73
	v_add_f32_e32 v40, 1.0, v40
	v_rcp_f32_e32 v47, v40
	s_nop 0
	v_pk_mul_f32 v[40:41], v[46:47], v[44:45]
	s_nop 0
	v_mul_f32_e32 v40, v40, v41
	v_lshlrev_b32_e32 v45, 16, v77
	v_cvt_pk_bf16_f32 v40, v2, v40
	v_mul_f32_e32 v2, 0xbfb8aa3b, v45
	v_exp_f32_e32 v2, v2
	v_mov_b32_e32 v46, v42
	v_mov_b32_e32 v44, v74
	v_add_f32_e32 v2, 1.0, v2
	v_rcp_f32_e32 v47, v2
	s_nop 0
	v_pk_mul_f32 v[44:45], v[46:47], v[44:45]
	s_nop 0
	v_mul_f32_e32 v2, v44, v45
	v_and_b32_e32 v45, 0xffff0000, v77
	v_mul_f32_e32 v41, 0xbfb8aa3b, v45
	v_exp_f32_e32 v41, v41
	v_mov_b32_e32 v46, v43
	v_mov_b32_e32 v44, v75
	v_add_f32_e32 v41, 1.0, v41
	v_rcp_f32_e32 v47, v41
	s_nop 0
	v_pk_mul_f32 v[42:43], v[46:47], v[44:45]
	s_nop 0
	v_mul_f32_e32 v41, v42, v43
	v_lshlrev_b32_e32 v43, 16, v78
	v_cvt_pk_bf16_f32 v41, v2, v41
	v_mul_f32_e32 v2, 0xbfb8aa3b, v43
	v_exp_f32_e32 v2, v2
	v_mov_b32_e32 v44, v36
	v_mov_b32_e32 v42, v68
	v_add_f32_e32 v2, 1.0, v2
	v_rcp_f32_e32 v45, v2
	s_nop 0
	v_pk_mul_f32 v[42:43], v[44:45], v[42:43]
	s_nop 0
	v_mul_f32_e32 v2, v42, v43
	v_and_b32_e32 v43, 0xffff0000, v78
	v_mul_f32_e32 v36, 0xbfb8aa3b, v43
	v_exp_f32_e32 v36, v36
	v_mov_b32_e32 v44, v37
	v_mov_b32_e32 v42, v69
	v_add_f32_e32 v36, 1.0, v36
	v_rcp_f32_e32 v45, v36
	s_nop 0
	v_pk_mul_f32 v[36:37], v[44:45], v[42:43]
	s_nop 0
	v_mul_f32_e32 v36, v36, v37
	v_lshlrev_b32_e32 v37, 16, v79
	v_cvt_pk_bf16_f32 v42, v2, v36
	v_mul_f32_e32 v2, 0xbfb8aa3b, v37
	v_exp_f32_e32 v2, v2
	v_mov_b32_e32 v44, v38
	v_mov_b32_e32 v36, v70
	v_add_f32_e32 v2, 1.0, v2
	v_rcp_f32_e32 v45, v2
	s_nop 0
	v_pk_mul_f32 v[36:37], v[44:45], v[36:37]
	s_nop 0
	v_mul_f32_e32 v2, v36, v37
	v_and_b32_e32 v37, 0xffff0000, v79
	v_mul_f32_e32 v36, 0xbfb8aa3b, v37
	v_exp_f32_e32 v36, v36
	v_mov_b32_e32 v44, v39
	v_add_f32_e32 v36, 1.0, v36
	v_rcp_f32_e32 v45, v36
	v_mov_b32_e32 v36, v71
	v_pk_mul_f32 v[36:37], v[44:45], v[36:37]
	s_nop 0
	v_mul_f32_e32 v36, v36, v37
	v_cvt_pk_bf16_f32 v43, v2, v36
	flat_store_dwordx4 v[126:127], v[40:43] offset:256
	v_lshl_add_u64 v[36:37], v[94:95], 0, v[130:131]
	flat_load_dwordx4 v[48:51], v[36:37]
	v_lshl_add_u64 v[36:37], v[94:95], 0, v[132:133]
	flat_load_dwordx4 v[44:47], v[36:37]
	v_lshl_add_u64 v[36:37], v[94:95], 0, v[134:135]
	flat_load_dwordx4 v[40:43], v[36:37]
	v_lshl_add_u64 v[36:37], v[94:95], 0, v[138:139]
	flat_load_dwordx4 v[36:39], v[36:37]
	s_waitcnt vmcnt(0) lgkmcnt(0)
; __device__ __forceinline__ float bflo(unsigned v) { return __uint_as_float(v << 16); }
; __device__ __forceinline__ float bfhi(unsigned v) { return __uint_as_float(v & 0xffff0000u); }
; __device__ __forceinline__ float siluf_(float x) { return x * __builtin_amdgcn_rcpf(1.0f + __expf(-x)); }
;   __device__ __forceinline__ void operator()(EPI_ARGS) const {
;     ...
;         for (int m = 0; m < 4; ++m) {
;           const size_t row = row0 + ai * HALF + m * 16;
;           const f32x4 v0 = acc[ai][bj][m][0], v1 = acc[ai][bj][m][1];
;           u32x4 o;
;           o.x = pack2(v0[0] * s0[0] * siluf_(bflo(z[m].x)), v0[1] * s0[1] * siluf_(bfhi(z[m].x)));
;           o.y = pack2(v0[2] * s0[2] * siluf_(bflo(z[m].y)), v0[3] * s0[3] * siluf_(bfhi(z[m].y)));
;           o.z = pack2(v1[0] * s1[0] * siluf_(bflo(z[m].z)), v1[1] * s1[1] * siluf_(bfhi(z[m].z)));
;           o.w = pack2(v1[2] * s1[2] * siluf_(bflo(z[m].w)), v1[3] * s1[3] * siluf_(bfhi(z[m].w)));
;           *(u32x4*)(y0 + row * DM + c) = o;
	v_lshlrev_b32_e32 v53, 16, v48
	v_mul_f32_e32 v2, 0xbfb8aa3b, v53
	v_exp_f32_e32 v2, v2
	v_mov_b32_e32 v54, v32
	v_mov_b32_e32 v52, v72
	s_and_b64 vcc, exec, s[18:19]
	v_add_f32_e32 v2, 1.0, v2
	v_rcp_f32_e32 v55, v2
	s_mov_b32 s33, s16
	s_mov_b32 s2, s14
	s_mov_b64 s[4:5], s[22:23]
	v_pk_mul_f32 v[52:53], v[54:55], v[52:53]
	v_mov_b32_e32 v54, v33
	v_mul_f32_e32 v2, v52, v53
	v_and_b32_e32 v53, 0xffff0000, v48
	v_mul_f32_e32 v32, 0xbfb8aa3b, v53
	v_exp_f32_e32 v32, v32
	v_mov_b32_e32 v52, v73
	v_mov_b32_e32 v48, v75
	s_mov_b64 s[6:7], s[20:21]
	v_add_f32_e32 v32, 1.0, v32
	v_rcp_f32_e32 v55, v32
	s_nop 0
	v_pk_mul_f32 v[32:33], v[54:55], v[52:53]
	s_nop 0
	v_mul_f32_e32 v32, v32, v33
	v_lshlrev_b32_e32 v53, 16, v49
	v_cvt_pk_bf16_f32 v32, v2, v32
	v_mul_f32_e32 v2, 0xbfb8aa3b, v53
	v_exp_f32_e32 v2, v2
	v_and_b32_e32 v49, 0xffff0000, v49
	v_mul_f32_e32 v33, 0xbfb8aa3b, v49
	v_exp_f32_e32 v33, v33
	v_add_f32_e32 v2, 1.0, v2
	v_rcp_f32_e32 v55, v2
	v_mov_b32_e32 v54, v34
	v_mov_b32_e32 v52, v74
	v_add_f32_e32 v33, 1.0, v33
	v_pk_mul_f32 v[52:53], v[54:55], v[52:53]
	s_nop 0
	v_mul_f32_e32 v2, v52, v53
	v_rcp_f32_e32 v53, v33
	v_mov_b32_e32 v52, v35
	v_pk_mul_f32 v[34:35], v[52:53], v[48:49]
	s_nop 0
	v_mul_f32_e32 v33, v34, v35
	v_lshlrev_b32_e32 v35, 16, v50
	v_cvt_pk_bf16_f32 v33, v2, v33
	v_mul_f32_e32 v2, 0xbfb8aa3b, v35
	v_exp_f32_e32 v2, v2
	v_mov_b32_e32 v48, v28
	v_mov_b32_e32 v34, v68
	v_add_f32_e32 v2, 1.0, v2
	v_rcp_f32_e32 v49, v2
	s_nop 0
	v_pk_mul_f32 v[34:35], v[48:49], v[34:35]
	s_nop 0
	v_mul_f32_e32 v2, v34, v35
	v_and_b32_e32 v35, 0xffff0000, v50
	v_mul_f32_e32 v28, 0xbfb8aa3b, v35
	v_exp_f32_e32 v28, v28
	v_mov_b32_e32 v48, v29
	v_mov_b32_e32 v34, v69
	v_add_f32_e32 v28, 1.0, v28
	v_rcp_f32_e32 v49, v28
	s_nop 0
	v_pk_mul_f32 v[28:29], v[48:49], v[34:35]
	s_nop 0
	v_mul_f32_e32 v28, v28, v29
	v_lshlrev_b32_e32 v29, 16, v51
	v_cvt_pk_bf16_f32 v34, v2, v28
	v_mul_f32_e32 v2, 0xbfb8aa3b, v29
	v_exp_f32_e32 v2, v2
	v_mov_b32_e32 v48, v30
	v_mov_b32_e32 v28, v70
	v_mov_b32_e32 v30, v24
	v_add_f32_e32 v2, 1.0, v2
	v_rcp_f32_e32 v49, v2
	s_nop 0
	v_pk_mul_f32 v[28:29], v[48:49], v[28:29]
	s_nop 0
	v_mul_f32_e32 v2, v28, v29
	v_and_b32_e32 v29, 0xffff0000, v51
	v_mul_f32_e32 v28, 0xbfb8aa3b, v29
	v_exp_f32_e32 v28, v28
	v_mov_b32_e32 v48, v31
	v_add_f32_e32 v28, 1.0, v28
	v_rcp_f32_e32 v49, v28
	v_mov_b32_e32 v28, v71
	v_pk_mul_f32 v[28:29], v[48:49], v[28:29]
	s_nop 0
	v_mul_f32_e32 v28, v28, v29
	v_lshlrev_b32_e32 v29, 16, v44
	v_cvt_pk_bf16_f32 v35, v2, v28
	v_mul_f32_e32 v2, 0xbfb8aa3b, v29
	v_exp_f32_e32 v2, v2
	v_mov_b32_e32 v28, v72
	flat_store_dwordx4 v[96:97], v[32:35] offset:256
	v_add_f32_e32 v2, 1.0, v2
	v_rcp_f32_e32 v31, v2
	s_nop 0
	v_pk_mul_f32 v[28:29], v[30:31], v[28:29]
	s_nop 0
	v_mul_f32_e32 v2, v28, v29
	v_and_b32_e32 v29, 0xffff0000, v44
	v_mul_f32_e32 v24, 0xbfb8aa3b, v29
	v_exp_f32_e32 v24, v24
	v_mov_b32_e32 v30, v25
	v_mov_b32_e32 v28, v73
	v_add_f32_e32 v24, 1.0, v24
	v_rcp_f32_e32 v31, v24
	s_nop 0
	v_pk_mul_f32 v[24:25], v[30:31], v[28:29]
	s_nop 0
	v_mul_f32_e32 v24, v24, v25
	v_lshlrev_b32_e32 v29, 16, v45
	v_cvt_pk_bf16_f32 v24, v2, v24
	v_mul_f32_e32 v2, 0xbfb8aa3b, v29
	v_exp_f32_e32 v2, v2
	v_mov_b32_e32 v30, v26
	v_mov_b32_e32 v28, v74
	v_add_f32_e32 v2, 1.0, v2
	v_rcp_f32_e32 v31, v2
	s_nop 0
	v_pk_mul_f32 v[28:29], v[30:31], v[28:29]
	s_nop 0
	v_mul_f32_e32 v2, v28, v29
	v_and_b32_e32 v29, 0xffff0000, v45
	v_mul_f32_e32 v25, 0xbfb8aa3b, v29
	v_exp_f32_e32 v25, v25
	v_mov_b32_e32 v30, v27
	v_mov_b32_e32 v28, v75
	v_add_f32_e32 v25, 1.0, v25
	v_rcp_f32_e32 v31, v25
	s_nop 0
	v_pk_mul_f32 v[26:27], v[30:31], v[28:29]
	s_nop 0
	v_mul_f32_e32 v25, v26, v27
	v_lshlrev_b32_e32 v27, 16, v46
	v_cvt_pk_bf16_f32 v25, v2, v25
	v_mul_f32_e32 v2, 0xbfb8aa3b, v27
	v_exp_f32_e32 v2, v2
	v_mov_b32_e32 v28, v20
	v_mov_b32_e32 v26, v68
	v_add_f32_e32 v2, 1.0, v2
	v_rcp_f32_e32 v29, v2
	s_nop 0
	v_pk_mul_f32 v[26:27], v[28:29], v[26:27]
	s_nop 0
	v_mul_f32_e32 v2, v26, v27
	v_and_b32_e32 v27, 0xffff0000, v46
	v_mul_f32_e32 v20, 0xbfb8aa3b, v27
	v_exp_f32_e32 v20, v20
	v_mov_b32_e32 v28, v21
	v_mov_b32_e32 v26, v69
	v_add_f32_e32 v20, 1.0, v20
	v_rcp_f32_e32 v29, v20
	s_nop 0
	v_pk_mul_f32 v[20:21], v[28:29], v[26:27]
	s_nop 0
	v_mul_f32_e32 v20, v20, v21
	v_lshlrev_b32_e32 v21, 16, v47
	v_cvt_pk_bf16_f32 v26, v2, v20
	v_mul_f32_e32 v2, 0xbfb8aa3b, v21
	v_exp_f32_e32 v2, v2
	v_mov_b32_e32 v28, v22
	v_mov_b32_e32 v20, v70
	v_mov_b32_e32 v22, v16
	v_add_f32_e32 v2, 1.0, v2
	v_rcp_f32_e32 v29, v2
	s_nop 0
	v_pk_mul_f32 v[20:21], v[28:29], v[20:21]
	s_nop 0
	v_mul_f32_e32 v2, v20, v21
	v_and_b32_e32 v21, 0xffff0000, v47
	v_mul_f32_e32 v20, 0xbfb8aa3b, v21
	v_exp_f32_e32 v20, v20
	v_mov_b32_e32 v28, v23
	v_add_f32_e32 v20, 1.0, v20
	v_rcp_f32_e32 v29, v20
	v_mov_b32_e32 v20, v71
	v_pk_mul_f32 v[20:21], v[28:29], v[20:21]
	s_nop 0
	v_mul_f32_e32 v20, v20, v21
	v_lshlrev_b32_e32 v21, 16, v40
	v_cvt_pk_bf16_f32 v27, v2, v20
	v_mul_f32_e32 v2, 0xbfb8aa3b, v21
	v_exp_f32_e32 v2, v2
	v_mov_b32_e32 v20, v72
	flat_store_dwordx4 v[98:99], v[24:27] offset:256
; __device__ __forceinline__ float bflo(unsigned v) { return __uint_as_float(v << 16); }
; __device__ __forceinline__ float bfhi(unsigned v) { return __uint_as_float(v & 0xffff0000u); }
; __device__ __forceinline__ float siluf_(float x) { return x * __builtin_amdgcn_rcpf(1.0f + __expf(-x)); }
; #define PG8_WAIT_V(n) asm volatile("s_waitcnt vmcnt(" #n ")" ::: "memory")
; #define PG8_BAR __builtin_amdgcn_s_barrier()
; template <class Epi, class AddrA, class AddrB>
; __device__ __forceinline__ void gemm_phase(const Sched S, const int lda, const int ldb, const int K, const AddrA addrA,
;                                            const AddrB addrB, const Epi E) {
;     ...
;     E(acc, cur, wr, wc, fr, fq);
;     if (!has_next) break;
;     if (!(Epi::KEEP && cur.br + 1 < S.nbr)) {
; #pragma unroll
;       for (int a = 0; a < 2; ++a)
; #pragma unroll
;         for (int b = 0; b < 2; ++b)
; #pragma unroll
;           for (int m = 0; m < 4; ++m)
; #pragma unroll
;             for (int n = 0; n < 2; ++n) acc[a][b][m][n] = (f32x4){0.f, 0.f, 0.f, 0.f};
;     }
;     cur = nxt; cA = nA; cB = nB; ++ui;
;   }
;   PG8_WAIT_V(0);
;   if (wr == 0) PG8_BAR;
;   PG8_BAR;
;   __device__ __forceinline__ void operator()(EPI_ARGS) const {
;     ...
;         for (int m = 0; m < 4; ++m) {
;           const size_t row = row0 + ai * HALF + m * 16;
;           const f32x4 v0 = acc[ai][bj][m][0], v1 = acc[ai][bj][m][1];
;           u32x4 o;
;           o.x = pack2(v0[0] * s0[0] * siluf_(bflo(z[m].x)), v0[1] * s0[1] * siluf_(bfhi(z[m].x)));
;           o.y = pack2(v0[2] * s0[2] * siluf_(bflo(z[m].y)), v0[3] * s0[3] * siluf_(bfhi(z[m].y)));
;           o.z = pack2(v1[0] * s1[0] * siluf_(bflo(z[m].z)), v1[1] * s1[1] * siluf_(bfhi(z[m].z)));
;           o.w = pack2(v1[2] * s1[2] * siluf_(bflo(z[m].w)), v1[3] * s1[3] * siluf_(bfhi(z[m].w)));
;           *(u32x4*)(y0 + row * DM + c) = o;
;         }
;       }
	v_add_f32_e32 v2, 1.0, v2
	v_rcp_f32_e32 v23, v2
	s_nop 0
	v_pk_mul_f32 v[20:21], v[22:23], v[20:21]
	s_nop 0
	v_mul_f32_e32 v2, v20, v21
	v_and_b32_e32 v21, 0xffff0000, v40
	v_mul_f32_e32 v16, 0xbfb8aa3b, v21
	v_exp_f32_e32 v16, v16
	v_mov_b32_e32 v22, v17
	v_mov_b32_e32 v20, v73
	v_add_f32_e32 v16, 1.0, v16
	v_rcp_f32_e32 v23, v16
	s_nop 0
	v_pk_mul_f32 v[16:17], v[22:23], v[20:21]
	s_nop 0
	v_mul_f32_e32 v16, v16, v17
	v_lshlrev_b32_e32 v21, 16, v41
	v_cvt_pk_bf16_f32 v16, v2, v16
	v_mul_f32_e32 v2, 0xbfb8aa3b, v21
	v_exp_f32_e32 v2, v2
	v_mov_b32_e32 v22, v18
	v_mov_b32_e32 v20, v74
	v_add_f32_e32 v2, 1.0, v2
	v_rcp_f32_e32 v23, v2
	s_nop 0
	v_pk_mul_f32 v[20:21], v[22:23], v[20:21]
	s_nop 0
	v_mul_f32_e32 v2, v20, v21
	v_and_b32_e32 v21, 0xffff0000, v41
	v_mul_f32_e32 v17, 0xbfb8aa3b, v21
	v_exp_f32_e32 v17, v17
	v_mov_b32_e32 v22, v19
	v_mov_b32_e32 v20, v75
	v_add_f32_e32 v17, 1.0, v17
	v_rcp_f32_e32 v23, v17
	s_nop 0
	v_pk_mul_f32 v[18:19], v[22:23], v[20:21]
	s_nop 0
	v_mul_f32_e32 v17, v18, v19
	v_lshlrev_b32_e32 v19, 16, v42
	v_cvt_pk_bf16_f32 v17, v2, v17
	v_mul_f32_e32 v2, 0xbfb8aa3b, v19
	v_exp_f32_e32 v2, v2
	v_mov_b32_e32 v20, v12
	v_mov_b32_e32 v18, v68
	v_add_f32_e32 v2, 1.0, v2
	v_rcp_f32_e32 v21, v2
	s_nop 0
	v_pk_mul_f32 v[18:19], v[20:21], v[18:19]
	s_nop 0
	v_mul_f32_e32 v2, v18, v19
	v_and_b32_e32 v19, 0xffff0000, v42
	v_mul_f32_e32 v12, 0xbfb8aa3b, v19
	v_exp_f32_e32 v12, v12
	v_mov_b32_e32 v20, v13
	v_mov_b32_e32 v18, v69
	v_add_f32_e32 v12, 1.0, v12
	v_rcp_f32_e32 v21, v12
	s_nop 0
	v_pk_mul_f32 v[12:13], v[20:21], v[18:19]
	s_nop 0
	v_mul_f32_e32 v12, v12, v13
	v_lshlrev_b32_e32 v13, 16, v43
	v_cvt_pk_bf16_f32 v18, v2, v12
	v_mul_f32_e32 v2, 0xbfb8aa3b, v13
	v_exp_f32_e32 v2, v2
	v_mov_b32_e32 v20, v14
	v_mov_b32_e32 v12, v70
	v_mov_b32_e32 v14, v8
	v_add_f32_e32 v2, 1.0, v2
	v_rcp_f32_e32 v21, v2
	s_nop 0
	v_pk_mul_f32 v[12:13], v[20:21], v[12:13]
	s_nop 0
	v_mul_f32_e32 v2, v12, v13
	v_and_b32_e32 v13, 0xffff0000, v43
	v_mul_f32_e32 v12, 0xbfb8aa3b, v13
	v_exp_f32_e32 v12, v12
	v_mov_b32_e32 v20, v15
	v_add_f32_e32 v12, 1.0, v12
	v_rcp_f32_e32 v21, v12
	v_mov_b32_e32 v12, v71
	v_pk_mul_f32 v[12:13], v[20:21], v[12:13]
	s_nop 0
	v_mul_f32_e32 v12, v12, v13
	v_lshlrev_b32_e32 v13, 16, v36
	v_cvt_pk_bf16_f32 v19, v2, v12
	v_mul_f32_e32 v2, 0xbfb8aa3b, v13
	v_exp_f32_e32 v2, v2
	v_mov_b32_e32 v12, v72
	flat_store_dwordx4 v[104:105], v[16:19] offset:256
	v_add_f32_e32 v2, 1.0, v2
	v_rcp_f32_e32 v15, v2
	s_nop 0
	v_pk_mul_f32 v[12:13], v[14:15], v[12:13]
	s_nop 0
	v_mul_f32_e32 v2, v12, v13
	v_and_b32_e32 v13, 0xffff0000, v36
	v_mul_f32_e32 v8, 0xbfb8aa3b, v13
	v_exp_f32_e32 v8, v8
	v_mov_b32_e32 v14, v9
	v_mov_b32_e32 v12, v73
	v_add_f32_e32 v8, 1.0, v8
	v_rcp_f32_e32 v15, v8
	s_nop 0
	v_pk_mul_f32 v[8:9], v[14:15], v[12:13]
	s_nop 0
	v_mul_f32_e32 v8, v8, v9
	v_lshlrev_b32_e32 v13, 16, v37
	v_cvt_pk_bf16_f32 v8, v2, v8
	v_mul_f32_e32 v2, 0xbfb8aa3b, v13
	v_exp_f32_e32 v2, v2
	v_mov_b32_e32 v14, v10
	v_mov_b32_e32 v12, v74
	v_add_f32_e32 v2, 1.0, v2
	v_rcp_f32_e32 v15, v2
	s_nop 0
	v_pk_mul_f32 v[12:13], v[14:15], v[12:13]
	s_nop 0
	v_mul_f32_e32 v2, v12, v13
	v_and_b32_e32 v13, 0xffff0000, v37
	v_mul_f32_e32 v9, 0xbfb8aa3b, v13
	v_exp_f32_e32 v9, v9
	v_mov_b32_e32 v14, v11
	v_mov_b32_e32 v12, v75
	v_add_f32_e32 v9, 1.0, v9
	v_rcp_f32_e32 v15, v9
	s_nop 0
	v_pk_mul_f32 v[10:11], v[14:15], v[12:13]
	s_nop 0
	v_mul_f32_e32 v9, v10, v11
	v_lshlrev_b32_e32 v11, 16, v38
	v_cvt_pk_bf16_f32 v9, v2, v9
	v_mul_f32_e32 v2, 0xbfb8aa3b, v11
	v_exp_f32_e32 v2, v2
	v_mov_b32_e32 v12, v4
	v_mov_b32_e32 v10, v68
	v_add_f32_e32 v2, 1.0, v2
	v_rcp_f32_e32 v13, v2
	s_nop 0
	v_pk_mul_f32 v[10:11], v[12:13], v[10:11]
	s_nop 0
	v_mul_f32_e32 v2, v10, v11
	v_and_b32_e32 v11, 0xffff0000, v38
	v_mul_f32_e32 v4, 0xbfb8aa3b, v11
	v_exp_f32_e32 v4, v4
	v_mov_b32_e32 v12, v5
	v_mov_b32_e32 v10, v69
	v_add_f32_e32 v4, 1.0, v4
	v_rcp_f32_e32 v13, v4
	s_nop 0
	v_pk_mul_f32 v[4:5], v[12:13], v[10:11]
	s_nop 0
	v_mul_f32_e32 v4, v4, v5
	v_lshlrev_b32_e32 v5, 16, v39
	v_cvt_pk_bf16_f32 v10, v2, v4
	v_mul_f32_e32 v2, 0xbfb8aa3b, v5
	v_exp_f32_e32 v2, v2
	v_mov_b32_e32 v12, v6
	v_mov_b32_e32 v4, v70
	v_add_f32_e32 v2, 1.0, v2
	v_rcp_f32_e32 v13, v2
	s_nop 0
	v_pk_mul_f32 v[4:5], v[12:13], v[4:5]
	s_nop 0
	v_mul_f32_e32 v2, v4, v5
	v_and_b32_e32 v5, 0xffff0000, v39
	v_mul_f32_e32 v4, 0xbfb8aa3b, v5
	v_exp_f32_e32 v4, v4
	v_mov_b32_e32 v12, v7
	v_add_f32_e32 v4, 1.0, v4
	v_rcp_f32_e32 v13, v4
	v_mov_b32_e32 v4, v71
	v_pk_mul_f32 v[4:5], v[12:13], v[4:5]
	s_nop 0
	v_mul_f32_e32 v4, v4, v5
	v_cvt_pk_bf16_f32 v11, v2, v4
	flat_store_dwordx4 v[92:93], v[8:11] offset:256
	s_cbranch_vccz .LBB0_482
	s_waitcnt vmcnt(0)
	v_readlane_b32 s44, v244, 59
	v_readlane_b32 s40, v243, 18
	s_cmpk_gt_u32 s24, 0xff
	s_mov_b32 s43, 0x800000
	v_readlane_b32 s45, v244, 60
	v_readlane_b32 s46, v244, 61
	v_readlane_b32 s47, v244, 62
	v_readlane_b32 s48, v244, 63
	v_readlane_b32 s49, v243, 0
	v_readlane_b32 s50, v243, 1
	v_readlane_b32 s51, v243, 2
	v_readlane_b32 s41, v243, 19
	s_cbranch_scc1 .LBB0_489
	s_barrier

; #define PG8_WAIT_L(n) asm volatile("s_waitcnt lgkmcnt(" #n ")" ::: "memory")
; #define PG8_BAR __builtin_amdgcn_s_barrier()
; #define PG8_SCHED __builtin_amdgcn_sched_barrier(0)
; template <class Epi, class AddrA, class AddrB>
; __device__ __forceinline__ void gemm_phase(const Sched S, const int lda, const int ldb, const int K, const AddrA addrA,
;                                            const AddrB addrB, const Epi E) {
;     ...
;     for (int t = 0; t < nt; t += 2) {
;       const bool last = (t == nt - 2);
;       const char* a1 = cA + (size_t)(t + 1) * kstep;
;       const char* a2 = last ? nA : cA + (size_t)(t + 2) * kstep;
;       const char* b2 = last ? nB : cB + (size_t)(t + 2) * kstep;
;       const char* a3 = a2 + kstep;
;       const char* b3 = b2 + kstep;
;       PG8_LDB(B0, 0, 0); PG8_SCHED; PG8_LDA(At, 0, 0); PG8_STAGE(PG8_SA(1, 1), a1 + hstepA, voffA);
;       PG8_WAIT_L(8); PG8_BAR; PG8_WAIT_L(0); PG8_MMA(0, 0, At, B0); PG8_BAR; PG8_SCHED;
;       PG8_LDB(B1, 0, 1); PG8_STAGE(PG8_SB(0, 0), b2, voffB);
;       PG8_BAR; PG8_WAIT_L(0); PG8_MMA(0, 1, At, B1); PG8_BAR;
;       PG8_LDA(At, 0, 1); PG8_STAGE(PG8_SA(0, 0), a2, voffA);
;       PG8_BAR; PG8_WAIT_L(0); PG8_MMA(1, 0, At, B0); PG8_BAR; PG8_SCHED;
.LBB0_543:
	s_add_u32 s4, s2, 0xfff80080
	s_addc_u32 s5, s3, -1
	s_add_i32 s43, 0, 0x10000
	v_add_u32_e32 v0, s43, v167
	ds_read_b128 v[132:135], v0
	ds_read_b128 v[136:139], v0 offset:1024
	ds_read_b128 v[140:143], v0 offset:2048
	ds_read_b128 v[144:147], v0 offset:3072
	s_cmp_eq_u32 s42, 28
	s_cselect_b32 s7, s1, s5
	s_cselect_b32 s6, s9, s4
	s_cselect_b32 s5, s13, s41
	s_cselect_b32 s4, s15, s33
	v_lshl_add_u64 v[0:1], s[2:3], 0, v[180:181]
	s_add_i32 m0, s28, 0xc000
	ds_read_b128 v[148:151], v188
	ds_read_b128 v[152:155], v188 offset:1024
	ds_read_b128 v[156:159], v188 offset:2048
	ds_read_b128 v[160:163], v188 offset:3072
	ds_read_b128 v[182:185], v188 offset:4096
	ds_read_b128 v[190:193], v188 offset:5120
	ds_read_b128 v[194:197], v188 offset:6144
	ds_read_b128 v[212:215], v188 offset:7168
	global_load_lds_dwordx4 v[0:1], off
	v_lshl_add_u64 v[0:1], s[2:3], 0, v[178:179]
	s_add_i32 m0, s28, 0xe000
	s_nop 0
	global_load_lds_dwordx4 v[0:1], off
	s_waitcnt lgkmcnt(8)
	s_barrier
	s_waitcnt lgkmcnt(0)
	s_setprio 1
	v_mfma_f32_16x16x32_bf16 v[128:131], v[132:135], v[148:151], v[128:131]
	v_mfma_f32_16x16x32_bf16 v[128:131], v[136:139], v[152:155], v[128:131]
	v_mfma_f32_16x16x32_bf16 v[120:123], v[132:135], v[156:159], v[120:123]
	v_mfma_f32_16x16x32_bf16 v[120:123], v[136:139], v[160:163], v[120:123]
	v_mfma_f32_16x16x32_bf16 v[112:115], v[132:135], v[182:185], v[112:115]
	v_mfma_f32_16x16x32_bf16 v[112:115], v[136:139], v[190:193], v[112:115]
	v_mfma_f32_16x16x32_bf16 v[104:107], v[132:135], v[194:197], v[104:107]
	v_mfma_f32_16x16x32_bf16 v[104:107], v[136:139], v[212:215], v[104:107]
	v_mfma_f32_16x16x32_bf16 v[124:127], v[140:143], v[148:151], v[124:127]
	v_mfma_f32_16x16x32_bf16 v[124:127], v[144:147], v[152:155], v[124:127]
	v_mfma_f32_16x16x32_bf16 v[116:119], v[140:143], v[156:159], v[116:119]
	v_mfma_f32_16x16x32_bf16 v[116:119], v[144:147], v[160:163], v[116:119]
	v_mfma_f32_16x16x32_bf16 v[108:111], v[140:143], v[182:185], v[108:111]
	v_mfma_f32_16x16x32_bf16 v[108:111], v[144:147], v[190:193], v[108:111]
	v_mfma_f32_16x16x32_bf16 v[100:103], v[140:143], v[194:197], v[100:103]
	v_mfma_f32_16x16x32_bf16 v[100:103], v[144:147], v[212:215], v[100:103]
	s_barrier
	s_setprio 0
	s_add_i32 s46, 0, 0x14000
	v_add_u32_e32 v0, s46, v167
	s_add_i32 s43, s43, s27
	ds_read_b128 v[216:219], v0
	ds_read_b128 v[220:223], v0 offset:1024
	ds_read_b128 v[224:227], v0 offset:2048
	ds_read_b128 v[228:231], v0 offset:3072
	v_lshl_add_u64 v[0:1], s[4:5], 0, v[172:173]
	s_mov_b32 m0, s43
	v_lshl_add_u64 v[232:233], s[4:5], 0, v[168:169]
	global_load_lds_dwordx4 v[0:1], off
	s_add_i32 m0, s43, 0x2000
	s_nop 0
	global_load_lds_dwordx4 v[232:233], off
	s_barrier
	s_waitcnt lgkmcnt(0)
	s_setprio 1
	v_mfma_f32_16x16x32_bf16 v[96:99], v[216:219], v[148:151], v[96:99]
	v_mfma_f32_16x16x32_bf16 v[96:99], v[220:223], v[152:155], v[96:99]
	v_mfma_f32_16x16x32_bf16 v[88:91], v[216:219], v[156:159], v[88:91]
	v_mfma_f32_16x16x32_bf16 v[88:91], v[220:223], v[160:163], v[88:91]
	v_mfma_f32_16x16x32_bf16 v[80:83], v[216:219], v[182:185], v[80:83]
	v_mfma_f32_16x16x32_bf16 v[80:83], v[220:223], v[190:193], v[80:83]
	v_mfma_f32_16x16x32_bf16 v[72:75], v[216:219], v[194:197], v[72:75]
	v_mfma_f32_16x16x32_bf16 v[72:75], v[220:223], v[212:215], v[72:75]
	v_mfma_f32_16x16x32_bf16 v[92:95], v[224:227], v[148:151], v[92:95]
	v_mfma_f32_16x16x32_bf16 v[92:95], v[228:231], v[152:155], v[92:95]
	v_mfma_f32_16x16x32_bf16 v[84:87], v[224:227], v[156:159], v[84:87]
	v_mfma_f32_16x16x32_bf16 v[84:87], v[228:231], v[160:163], v[84:87]
	v_mfma_f32_16x16x32_bf16 v[76:79], v[224:227], v[182:185], v[76:79]
	v_mfma_f32_16x16x32_bf16 v[76:79], v[228:231], v[190:193], v[76:79]
	v_mfma_f32_16x16x32_bf16 v[68:71], v[224:227], v[194:197], v[68:71]
	v_mfma_f32_16x16x32_bf16 v[68:71], v[228:231], v[212:215], v[68:71]
	s_mov_b32 m0, s28
	v_lshl_add_u64 v[234:235], s[6:7], 0, v[174:175]
	s_barrier
	s_setprio 0
	ds_read_b128 v[148:151], v188 offset:16384
	ds_read_b128 v[152:155], v188 offset:17408
	ds_read_b128 v[156:159], v188 offset:18432
	ds_read_b128 v[160:163], v188 offset:19456
	ds_read_b128 v[182:185], v188 offset:20480
	ds_read_b128 v[190:193], v188 offset:21504
	ds_read_b128 v[194:197], v188 offset:22528
	ds_read_b128 v[212:215], v188 offset:23552
	global_load_lds_dwordx4 v[234:235], off
	v_lshl_add_u64 v[236:237], s[6:7], 0, v[170:171]
	s_mov_b32 m0, s29
	s_nop 0
	global_load_lds_dwordx4 v[236:237], off
	s_barrier
	s_waitcnt lgkmcnt(0)
	s_setprio 1
	v_mfma_f32_16x16x32_bf16 v[64:67], v[132:135], v[148:151], v[64:67]
	v_mfma_f32_16x16x32_bf16 v[64:67], v[136:139], v[152:155], v[64:67]
	v_mfma_f32_16x16x32_bf16 v[56:59], v[132:135], v[156:159], v[56:59]
	v_mfma_f32_16x16x32_bf16 v[56:59], v[136:139], v[160:163], v[56:59]
	v_mfma_f32_16x16x32_bf16 v[48:51], v[132:135], v[182:185], v[48:51]
	v_mfma_f32_16x16x32_bf16 v[48:51], v[136:139], v[190:193], v[48:51]
	v_mfma_f32_16x16x32_bf16 v[40:43], v[132:135], v[194:197], v[40:43]
	v_mfma_f32_16x16x32_bf16 v[40:43], v[136:139], v[212:215], v[40:43]
	v_mfma_f32_16x16x32_bf16 v[60:63], v[140:143], v[148:151], v[60:63]
	v_mfma_f32_16x16x32_bf16 v[60:63], v[144:147], v[152:155], v[60:63]
	v_mfma_f32_16x16x32_bf16 v[52:55], v[140:143], v[156:159], v[52:55]
	v_mfma_f32_16x16x32_bf16 v[52:55], v[144:147], v[160:163], v[52:55]
	v_mfma_f32_16x16x32_bf16 v[44:47], v[140:143], v[182:185], v[44:47]
	v_mfma_f32_16x16x32_bf16 v[44:47], v[144:147], v[190:193], v[44:47]
	v_mfma_f32_16x16x32_bf16 v[36:39], v[140:143], v[194:197], v[36:39]
	v_mfma_f32_16x16x32_bf16 v[36:39], v[144:147], v[212:215], v[36:39]
	s_barrier
; #define PG8_WAIT_V(n) asm volatile("s_waitcnt vmcnt(" #n ")" ::: "memory")
; #define PG8_WAIT_L(n) asm volatile("s_waitcnt lgkmcnt(" #n ")" ::: "memory")
; #define PG8_BAR __builtin_amdgcn_s_barrier()
; #define PG8_SCHED __builtin_amdgcn_sched_barrier(0)
; template <class Epi, class AddrA, class AddrB>
; __device__ __forceinline__ void gemm_phase(const Sched S, const int lda, const int ldb, const int K, const AddrA addrA,
;                                            const AddrB addrB, const Epi E) {
;     ...
;       PG8_LDB(B0, 0, 0); PG8_SCHED; PG8_LDA(At, 0, 0); PG8_STAGE(PG8_SA(1, 1), a1 + hstepA, voffA);
;       PG8_WAIT_L(8); PG8_BAR; PG8_WAIT_L(0); PG8_MMA(0, 0, At, B0); PG8_BAR; PG8_SCHED;
;       PG8_LDB(B1, 0, 1); PG8_STAGE(PG8_SB(0, 0), b2, voffB);
;       PG8_BAR; PG8_WAIT_L(0); PG8_MMA(0, 1, At, B1); PG8_BAR;
;       PG8_LDA(At, 0, 1); PG8_STAGE(PG8_SA(0, 0), a2, voffA);
;       PG8_BAR; PG8_WAIT_L(0); PG8_MMA(1, 0, At, B0); PG8_BAR; PG8_SCHED;
;       PG8_STAGE(PG8_SB(0, 1), b2 + hstepB, voffB);
;       PG8_WAIT_V(6); PG8_BAR; PG8_MMA(1, 1, At, B1); PG8_BAR;
;       PG8_LDB(B0, 1, 0); PG8_SCHED; PG8_LDA(At, 1, 0); PG8_STAGE(PG8_SA(0, 1), a2 + hstepA, voffA);
;       PG8_WAIT_L(8); PG8_BAR; PG8_WAIT_L(0); PG8_MMA(0, 0, At, B0); PG8_BAR; PG8_SCHED;
;       PG8_LDB(B1, 1, 1); PG8_STAGE(PG8_SB(1, 0), b3, voffB);
;       PG8_BAR; PG8_WAIT_L(0); PG8_MMA(0, 1, At, B1); PG8_BAR;
;       PG8_LDA(At, 1, 1); PG8_STAGE(PG8_SA(1, 0), a3, voffA);
;       PG8_BAR; PG8_WAIT_L(0); PG8_MMA(1, 0, At, B0); PG8_BAR; PG8_SCHED;
;       PG8_STAGE(PG8_SB(1, 1), b3 + hstepB, voffB);
;       PG8_WAIT_V(6); PG8_BAR; PG8_MMA(1, 1, At, B1); PG8_BAR;
	s_setprio 0
	s_add_u32 s44, s4, 0x80000
	s_addc_u32 s45, s5, 0
	s_add_i32 s43, s46, s27
	v_lshl_add_u64 v[132:133], s[44:45], 0, v[172:173]
	s_mov_b32 m0, s43
	s_nop 0
	global_load_lds_dwordx4 v[132:133], off
	v_lshl_add_u64 v[132:133], s[44:45], 0, v[168:169]
	s_add_i32 m0, s43, 0x2000
	s_nop 0
	global_load_lds_dwordx4 v[132:133], off
	s_waitcnt vmcnt(6)
	s_barrier
	s_setprio 1
	v_mfma_f32_16x16x32_bf16 v[32:35], v[216:219], v[148:151], v[32:35]
	v_mfma_f32_16x16x32_bf16 v[32:35], v[220:223], v[152:155], v[32:35]
	v_mfma_f32_16x16x32_bf16 v[24:27], v[216:219], v[156:159], v[24:27]
	v_mfma_f32_16x16x32_bf16 v[24:27], v[220:223], v[160:163], v[24:27]
	v_mfma_f32_16x16x32_bf16 v[16:19], v[216:219], v[182:185], v[16:19]
	v_mfma_f32_16x16x32_bf16 v[16:19], v[220:223], v[190:193], v[16:19]
	v_mfma_f32_16x16x32_bf16 v[8:11], v[216:219], v[194:197], v[8:11]
	v_mfma_f32_16x16x32_bf16 v[8:11], v[220:223], v[212:215], v[8:11]
	v_mfma_f32_16x16x32_bf16 v[28:31], v[224:227], v[148:151], v[28:31]
	v_mfma_f32_16x16x32_bf16 v[28:31], v[228:231], v[152:155], v[28:31]
	v_mfma_f32_16x16x32_bf16 v[20:23], v[224:227], v[156:159], v[20:23]
	v_mfma_f32_16x16x32_bf16 v[20:23], v[228:231], v[160:163], v[20:23]
	v_mfma_f32_16x16x32_bf16 v[12:15], v[224:227], v[182:185], v[12:15]
	v_mfma_f32_16x16x32_bf16 v[12:15], v[228:231], v[190:193], v[12:15]
	v_mfma_f32_16x16x32_bf16 v[4:7], v[224:227], v[194:197], v[4:7]
	v_mfma_f32_16x16x32_bf16 v[4:7], v[228:231], v[212:215], v[4:7]
	s_add_i32 s43, 0, 0x18000
	v_add_u32_e32 v2, s43, v167
	s_barrier
	s_setprio 0
	ds_read_b128 v[132:135], v2
	ds_read_b128 v[136:139], v2 offset:1024
	ds_read_b128 v[140:143], v2 offset:2048
	ds_read_b128 v[144:147], v2 offset:3072
	s_add_u32 s6, s6, 0x80000
	s_addc_u32 s7, s7, 0
	s_mov_b32 m0, s30
	v_lshl_add_u64 v[216:217], s[6:7], 0, v[174:175]
	ds_read_b128 v[148:151], v188 offset:32768
	ds_read_b128 v[152:155], v188 offset:33792
	ds_read_b128 v[156:159], v188 offset:34816
	ds_read_b128 v[160:163], v188 offset:35840
	ds_read_b128 v[182:185], v188 offset:36864
	ds_read_b128 v[190:193], v188 offset:37888
	ds_read_b128 v[194:197], v188 offset:38912
	ds_read_b128 v[212:215], v188 offset:39936
	global_load_lds_dwordx4 v[216:217], off
	v_lshl_add_u64 v[216:217], s[6:7], 0, v[170:171]
	s_mov_b32 m0, s31
	s_nop 0
	global_load_lds_dwordx4 v[216:217], off
	s_waitcnt lgkmcnt(8)
	s_barrier
	s_waitcnt lgkmcnt(0)
	s_setprio 1
	v_mfma_f32_16x16x32_bf16 v[128:131], v[132:135], v[148:151], v[128:131]
	v_mfma_f32_16x16x32_bf16 v[128:131], v[136:139], v[152:155], v[128:131]
	v_mfma_f32_16x16x32_bf16 v[120:123], v[132:135], v[156:159], v[120:123]
	v_mfma_f32_16x16x32_bf16 v[120:123], v[136:139], v[160:163], v[120:123]
	v_mfma_f32_16x16x32_bf16 v[112:115], v[132:135], v[182:185], v[112:115]
	v_mfma_f32_16x16x32_bf16 v[112:115], v[136:139], v[190:193], v[112:115]
	v_mfma_f32_16x16x32_bf16 v[104:107], v[132:135], v[194:197], v[104:107]
	v_mfma_f32_16x16x32_bf16 v[104:107], v[136:139], v[212:215], v[104:107]
	v_mfma_f32_16x16x32_bf16 v[124:127], v[140:143], v[148:151], v[124:127]
	v_mfma_f32_16x16x32_bf16 v[124:127], v[144:147], v[152:155], v[124:127]
	v_mfma_f32_16x16x32_bf16 v[116:119], v[140:143], v[156:159], v[116:119]
	v_mfma_f32_16x16x32_bf16 v[116:119], v[144:147], v[160:163], v[116:119]
	v_mfma_f32_16x16x32_bf16 v[108:111], v[140:143], v[182:185], v[108:111]
	v_mfma_f32_16x16x32_bf16 v[108:111], v[144:147], v[190:193], v[108:111]
	v_mfma_f32_16x16x32_bf16 v[100:103], v[140:143], v[194:197], v[100:103]
	v_mfma_f32_16x16x32_bf16 v[100:103], v[144:147], v[212:215], v[100:103]
	s_barrier
	s_setprio 0
	s_add_i32 s6, 0, 0x1c000
	s_add_i32 s7, s43, s27
	v_add_u32_e32 v2, s6, v167
	v_lshl_add_u64 v[0:1], v[0:1], 0, s[52:53]
	s_mov_b32 m0, s7
	ds_read_b128 v[216:219], v2
	ds_read_b128 v[220:223], v2 offset:1024
	ds_read_b128 v[224:227], v2 offset:2048
	ds_read_b128 v[228:231], v2 offset:3072
	global_load_lds_dwordx4 v[0:1], off
	v_lshl_add_u64 v[0:1], v[232:233], 0, s[52:53]
	s_add_i32 m0, s7, 0x2000
	s_nop 0
	global_load_lds_dwordx4 v[0:1], off
	s_barrier
	s_waitcnt lgkmcnt(0)
	s_setprio 1
	v_mfma_f32_16x16x32_bf16 v[96:99], v[216:219], v[148:151], v[96:99]
	v_mfma_f32_16x16x32_bf16 v[96:99], v[220:223], v[152:155], v[96:99]
	v_mfma_f32_16x16x32_bf16 v[88:91], v[216:219], v[156:159], v[88:91]
	v_mfma_f32_16x16x32_bf16 v[88:91], v[220:223], v[160:163], v[88:91]
	v_mfma_f32_16x16x32_bf16 v[80:83], v[216:219], v[182:185], v[80:83]
	v_mfma_f32_16x16x32_bf16 v[80:83], v[220:223], v[190:193], v[80:83]
	v_mfma_f32_16x16x32_bf16 v[72:75], v[216:219], v[194:197], v[72:75]
	v_mfma_f32_16x16x32_bf16 v[72:75], v[220:223], v[212:215], v[72:75]
	v_mfma_f32_16x16x32_bf16 v[92:95], v[224:227], v[148:151], v[92:95]
	v_mfma_f32_16x16x32_bf16 v[92:95], v[228:231], v[152:155], v[92:95]
	v_mfma_f32_16x16x32_bf16 v[84:87], v[224:227], v[156:159], v[84:87]
	v_mfma_f32_16x16x32_bf16 v[84:87], v[228:231], v[160:163], v[84:87]
	v_mfma_f32_16x16x32_bf16 v[76:79], v[224:227], v[182:185], v[76:79]
	v_mfma_f32_16x16x32_bf16 v[76:79], v[228:231], v[190:193], v[76:79]
	v_mfma_f32_16x16x32_bf16 v[68:71], v[224:227], v[194:197], v[68:71]
	v_mfma_f32_16x16x32_bf16 v[68:71], v[228:231], v[212:215], v[68:71]
	s_mov_b32 m0, s38
	v_lshl_add_u64 v[0:1], v[234:235], 0, s[52:53]
	s_barrier
	s_setprio 0
	ds_read_b128 v[148:151], v188 offset:49152
	ds_read_b128 v[152:155], v188 offset:50176
	ds_read_b128 v[156:159], v188 offset:51200
	ds_read_b128 v[160:163], v188 offset:52224
	ds_read_b128 v[182:185], v188 offset:53248
	ds_read_b128 v[190:193], v188 offset:54272
	ds_read_b128 v[194:197], v188 offset:55296
	ds_read_b128 v[212:215], v188 offset:56320
	global_load_lds_dwordx4 v[0:1], off
	v_lshl_add_u64 v[0:1], v[236:237], 0, s[52:53]
	s_mov_b32 m0, s39
	s_nop 0
	global_load_lds_dwordx4 v[0:1], off
	s_barrier
; #define PG8_WAIT_V(n) asm volatile("s_waitcnt vmcnt(" #n ")" ::: "memory")
; #define PG8_WAIT_L(n) asm volatile("s_waitcnt lgkmcnt(" #n ")" ::: "memory")
; #define PG8_BAR __builtin_amdgcn_s_barrier()
; #define PG8_SCHED __builtin_amdgcn_sched_barrier(0)
; template <class Epi, class AddrA, class AddrB>
; __device__ __forceinline__ void gemm_phase(const Sched S, const int lda, const int ldb, const int K, const AddrA addrA,
;                                            const AddrB addrB, const Epi E) {
;     ...
;       PG8_BAR; PG8_WAIT_L(0); PG8_MMA(1, 0, At, B0); PG8_BAR; PG8_SCHED;
;       PG8_STAGE(PG8_SB(1, 1), b3 + hstepB, voffB);
;       PG8_WAIT_V(6); PG8_BAR; PG8_MMA(1, 1, At, B1); PG8_BAR;
;   __device__ __forceinline__ void operator()(EPI_ARGS) const {
;     const int col0 = u.pn * 256 + wc * 32 + 8 * fq;
;     const int br = u.br, brn = br < 2 ? br + 1 : 2;
;     const unsigned loff0 = (unsigned)((wr * 64 + fr) * PLD + wc * 32 + 8 * fq);
;     const bf16_t* pc = proj + ((size_t)((GT + br * DM) / 256 + u.pn) * MTOK + (size_t)u.pm * 256) * PLD;
;     const bf16_t* pn_ = proj + ((size_t)((GT + brn * DM) / 256 + u.pn) * MTOK + (size_t)u.pm * 256) * PLD;
;     bf16_t* mrow = merged + ((size_t)u.pm * 256 + wr * 64 + fr) * DM + col0;
; #pragma unroll
;     for (int bj = 0; bj < 2; ++bj) {
;       const int c = col0 + bj * HALF;
;       float gc[8], gn[8];
;       {
;         const f32x4 a0 = *(const f32x4*)(bg + br * DM + c), a1 = *(const f32x4*)(bg + br * DM + c + 4);
;         const f32x4 b0 = *(const f32x4*)(bg + brn * DM + c), b1 = *(const f32x4*)(bg + brn * DM + c + 4);
; #pragma unroll
;         for (int k = 0; k < 4; ++k) { gc[k] = a0[k]; gc[4 + k] = a1[k]; gn[k] = b0[k]; gn[4 + k] = b1[k]; }
;       }
; #pragma unroll
;       for (int ai = 0; ai < 2; ++ai) {
;         unsigned loff = loff0;
;         asm volatile("" : "+v"(loff));
;         u32x4 zc[4], zn[4];
; #pragma unroll
;         for (int m = 0; m < 4; ++m) {
;           const unsigned o = loff + (unsigned)((ai * HALF + m * 16) * PLD + bj * HALF);
;           zc[m] = *(const u32x4*)(pc + o);
;           zn[m] = *(const u32x4*)(pn_ + o);
;         }
;         __builtin_amdgcn_sched_barrier(0);
	s_waitcnt lgkmcnt(0)
	s_setprio 1
	v_mfma_f32_16x16x32_bf16 v[64:67], v[132:135], v[148:151], v[64:67]
	v_mfma_f32_16x16x32_bf16 v[64:67], v[136:139], v[152:155], v[64:67]
	v_mfma_f32_16x16x32_bf16 v[56:59], v[132:135], v[156:159], v[56:59]
	v_mfma_f32_16x16x32_bf16 v[56:59], v[136:139], v[160:163], v[56:59]
	v_mfma_f32_16x16x32_bf16 v[48:51], v[132:135], v[182:185], v[48:51]
	v_mfma_f32_16x16x32_bf16 v[48:51], v[136:139], v[190:193], v[48:51]
	v_mfma_f32_16x16x32_bf16 v[40:43], v[132:135], v[194:197], v[40:43]
	v_mfma_f32_16x16x32_bf16 v[40:43], v[136:139], v[212:215], v[40:43]
	v_mfma_f32_16x16x32_bf16 v[60:63], v[140:143], v[148:151], v[60:63]
	v_mfma_f32_16x16x32_bf16 v[60:63], v[144:147], v[152:155], v[60:63]
	v_mfma_f32_16x16x32_bf16 v[52:55], v[140:143], v[156:159], v[52:55]
	v_mfma_f32_16x16x32_bf16 v[52:55], v[144:147], v[160:163], v[52:55]
	v_mfma_f32_16x16x32_bf16 v[44:47], v[140:143], v[182:185], v[44:47]
	v_mfma_f32_16x16x32_bf16 v[44:47], v[144:147], v[190:193], v[44:47]
	v_mfma_f32_16x16x32_bf16 v[36:39], v[140:143], v[194:197], v[36:39]
	v_mfma_f32_16x16x32_bf16 v[36:39], v[144:147], v[212:215], v[36:39]
	s_barrier
	s_setprio 0
	s_add_u32 s4, s4, 0x80080
	s_addc_u32 s5, s5, 0
	s_add_i32 s6, s6, s27
	v_lshl_add_u64 v[0:1], s[4:5], 0, v[172:173]
	s_mov_b32 m0, s6
	s_nop 0
	global_load_lds_dwordx4 v[0:1], off
	v_lshl_add_u64 v[0:1], s[4:5], 0, v[168:169]
	s_add_i32 m0, s6, 0x2000
	s_nop 0
	global_load_lds_dwordx4 v[0:1], off
	s_waitcnt vmcnt(6)
	s_barrier
	s_setprio 1
	v_mfma_f32_16x16x32_bf16 v[32:35], v[216:219], v[148:151], v[32:35]
	v_mfma_f32_16x16x32_bf16 v[32:35], v[220:223], v[152:155], v[32:35]
	v_mfma_f32_16x16x32_bf16 v[24:27], v[216:219], v[156:159], v[24:27]
	v_mfma_f32_16x16x32_bf16 v[24:27], v[220:223], v[160:163], v[24:27]
	v_mfma_f32_16x16x32_bf16 v[16:19], v[216:219], v[182:185], v[16:19]
	v_mfma_f32_16x16x32_bf16 v[16:19], v[220:223], v[190:193], v[16:19]
	v_mfma_f32_16x16x32_bf16 v[8:11], v[216:219], v[194:197], v[8:11]
	v_mfma_f32_16x16x32_bf16 v[8:11], v[220:223], v[212:215], v[8:11]
	v_mfma_f32_16x16x32_bf16 v[28:31], v[224:227], v[148:151], v[28:31]
	v_mfma_f32_16x16x32_bf16 v[28:31], v[228:231], v[152:155], v[28:31]
	v_mfma_f32_16x16x32_bf16 v[20:23], v[224:227], v[156:159], v[20:23]
	v_mfma_f32_16x16x32_bf16 v[20:23], v[228:231], v[160:163], v[20:23]
	v_mfma_f32_16x16x32_bf16 v[12:15], v[224:227], v[182:185], v[12:15]
	v_mfma_f32_16x16x32_bf16 v[12:15], v[228:231], v[190:193], v[12:15]
	v_mfma_f32_16x16x32_bf16 v[4:7], v[224:227], v[194:197], v[4:7]
	v_mfma_f32_16x16x32_bf16 v[4:7], v[228:231], v[212:215], v[4:7]
	s_add_i32 s42, s42, 2
	s_add_u32 s33, s33, 0x100
	s_addc_u32 s41, s41, 0
	s_add_u32 s2, s2, 0x100
	s_addc_u32 s3, s3, 0
	s_cmp_gt_u32 s42, 29
	s_barrier
	s_setprio 0
	s_cbranch_scc0 .LBB0_543
	s_cmp_gt_i32 s10, 1
	s_cselect_b64 s[6:7], -1, 0
	s_lshl_b32 s42, s10, 11
	s_add_i32 s2, s42, 0x4c00
	s_ashr_i32 s2, s2, 8
	s_add_i32 s2, s2, s11
	s_ashr_i32 s3, s2, 31
	s_min_i32 s1, s10, 1
	s_ashr_i32 s9, s8, 31
	s_lshl_b64 s[2:3], s[2:3], 23
	s_add_u32 s2, s34, s2
	s_addc_u32 s3, s35, s3
	s_lshl_b64 s[4:5], s[8:9], 17
	s_add_u32 s2, s2, s4
	s_addc_u32 s3, s3, s5
	s_lshl_b32 s1, s1, 11
	s_add_i32 s44, s1, 0x800
	s_addk_i32 s1, 0x5400
	s_ashr_i32 s1, s1, 8
	s_add_i32 s46, s1, s11
	s_ashr_i32 s47, s46, 31
	s_lshl_b64 s[46:47], s[46:47], 23
	s_add_u32 s1, s34, s46
	v_lshl_or_b32 v132, s11, 8, v187
	s_addc_u32 s11, s35, s47
	s_add_u32 s4, s1, s4
	s_addc_u32 s5, s11, s5
	s_ashr_i32 s43, s42, 31
	s_lshl_b64 s[8:9], s[8:9], 20
	s_ashr_i32 s45, s44, 31
	s_lshl_b64 s[42:43], s[42:43], 2
	s_add_u32 s42, s36, s42
	s_addc_u32 s43, s37, s43
	s_lshl_b64 s[44:45], s[44:45], 2
	s_add_u32 s44, s36, s44
	v_lshl_add_u64 v[0:1], v[176:177], 0, s[8:9]
	v_ashrrev_i32_e32 v133, 31, v132
	s_addc_u32 s45, s37, s45
	v_lshl_add_u64 v[0:1], v[132:133], 1, v[0:1]
	v_lshlrev_b64 v[132:133], 2, v[132:133]
	v_lshl_add_u64 v[182:183], s[42:43], 0, v[132:133]
	v_lshl_add_u64 v[184:185], s[44:45], 0, v[132:133]
	v_mov_b32_e32 v2, v186
	global_load_dwordx4 v[144:147], v[182:183], off
	global_load_dwordx4 v[136:139], v[182:183], off offset:16
	global_load_dwordx4 v[140:143], v[184:185], off
	global_load_dwordx4 v[132:135], v[184:185], off offset:16
	s_cmp_lt_i32 s10, 2
	v_lshlrev_b64 v[148:149], 1, v[2:3]
	v_lshl_add_u64 v[150:151], s[2:3], 0, v[148:149]
	v_lshl_add_u64 v[148:149], s[4:5], 0, v[148:149]
	flat_load_dwordx4 v[190:193], v[150:151]
	flat_load_dwordx4 v[160:163], v[148:149]
	v_add_u32_e32 v148, 0x1000, v2
	v_mov_b32_e32 v149, v3
	v_lshlrev_b64 v[148:149], 1, v[148:149]
	v_lshl_add_u64 v[150:151], s[2:3], 0, v[148:149]
	v_lshl_add_u64 v[148:149], s[4:5], 0, v[148:149]
	flat_load_dwordx4 v[194:197], v[150:151]
	flat_load_dwordx4 v[156:159], v[148:149]
	v_add_u32_e32 v148, 0x2000, v2
	v_mov_b32_e32 v149, v3
	v_lshlrev_b64 v[148:149], 1, v[148:149]
	v_lshl_add_u64 v[150:151], s[2:3], 0, v[148:149]
	v_lshl_add_u64 v[148:149], s[4:5], 0, v[148:149]
	v_add_u32_e32 v2, 0x3000, v2
	flat_load_dwordx4 v[234:237], v[150:151]
	flat_load_dwordx4 v[152:155], v[148:149]
	v_lshlrev_b64 v[148:149], 1, v[2:3]
	v_lshl_add_u64 v[150:151], s[2:3], 0, v[148:149]
	v_lshl_add_u64 v[148:149], s[4:5], 0, v[148:149]
	flat_load_dwordx4 v[238:241], v[150:151]
	s_nop 0
	flat_load_dwordx4 v[148:151], v[148:149]
	s_waitcnt vmcnt(0) lgkmcnt(0)
; __device__ __forceinline__ float sigmoidf_(float x) { return __builtin_amdgcn_rcpf(1.0f + __expf(-x)); }
;   __device__ __forceinline__ void operator()(EPI_ARGS) const {
;     ...
;         } else {
; #pragma unroll
;           for (int m = 0; m < 4; ++m) {
;             float xc[8], y[8];
;             unpack8(zc[m], xc);
; #pragma unroll
;             for (int k = 0; k < 8; ++k) y[k] = acc[ai][bj][m][k >> 2][k & 3] * sigmoidf_(fmaxf(xc[k] + gc[k], -40.f));
;             u32x4 o;
;             o.x = pack2(y[0], y[1]); o.y = pack2(y[2], y[3]); o.z = pack2(y[4], y[5]); o.w = pack2(y[6], y[7]);
;             *(u32x4*)(mrow + (size_t)(ai * HALF + m * 16) * DM + bj * HALF) = o;
;           }
	v_lshlrev_b32_e32 v2, 16, v190
	v_and_b32_e32 v189, 0xffff0000, v190
	v_lshlrev_b32_e32 v190, 16, v191
	v_and_b32_e32 v191, 0xffff0000, v191
	v_lshlrev_b32_e32 v212, 16, v192
	v_and_b32_e32 v192, 0xffff0000, v192
	v_lshlrev_b32_e32 v213, 16, v193
	v_and_b32_e32 v193, 0xffff0000, v193
	v_add_f32_e32 v2, v144, v2
	v_add_f32_e32 v189, v145, v189
	v_add_f32_e32 v190, v146, v190
	v_add_f32_e32 v191, v147, v191
	v_add_f32_e32 v212, v136, v212
	v_add_f32_e32 v192, v137, v192
	v_add_f32_e32 v213, v138, v213
	v_add_f32_e32 v193, v139, v193
	s_mov_b64 s[8:9], -1
	v_max_f32_e32 v233, 0xc2200000, v2
	v_max_f32_e32 v232, 0xc2200000, v189
	v_max_f32_e32 v231, 0xc2200000, v190
	v_max_f32_e32 v230, 0xc2200000, v191
	v_max_f32_e32 v229, 0xc2200000, v212
	v_max_f32_e32 v228, 0xc2200000, v192
	v_max_f32_e32 v227, 0xc2200000, v213
	v_max_f32_e32 v226, 0xc2200000, v193
	v_lshlrev_b32_e32 v225, 16, v194
	v_and_b32_e32 v224, 0xffff0000, v194
	v_lshlrev_b32_e32 v223, 16, v195
	v_and_b32_e32 v222, 0xffff0000, v195
	v_lshlrev_b32_e32 v221, 16, v196
	v_and_b32_e32 v220, 0xffff0000, v196
	v_lshlrev_b32_e32 v219, 16, v197
	v_and_b32_e32 v218, 0xffff0000, v197
	v_lshlrev_b32_e32 v217, 16, v234
	v_and_b32_e32 v216, 0xffff0000, v234
	v_lshlrev_b32_e32 v215, 16, v235
	v_and_b32_e32 v214, 0xffff0000, v235
	v_lshlrev_b32_e32 v213, 16, v236
	v_and_b32_e32 v212, 0xffff0000, v236
	v_lshlrev_b32_e32 v197, 16, v237
	v_and_b32_e32 v196, 0xffff0000, v237
	v_lshlrev_b32_e32 v195, 16, v238
	v_and_b32_e32 v194, 0xffff0000, v238
	v_lshlrev_b32_e32 v193, 16, v239
	v_and_b32_e32 v192, 0xffff0000, v239
	v_lshlrev_b32_e32 v191, 16, v240
	v_and_b32_e32 v190, 0xffff0000, v240
	v_lshlrev_b32_e32 v189, 16, v241
	v_and_b32_e32 v2, 0xffff0000, v241
	s_cbranch_scc1 .LBB0_546
	v_mul_f32_e32 v234, 0xbfb8aa3b, v233
	v_mul_f32_e32 v235, 0xbfb8aa3b, v232
	v_mul_f32_e32 v236, 0xbfb8aa3b, v231
	v_exp_f32_e32 v234, v234
	v_exp_f32_e32 v235, v235
	v_exp_f32_e32 v236, v236
	v_mul_f32_e32 v237, 0xbfb8aa3b, v230
	v_exp_f32_e32 v237, v237
	v_mul_f32_e32 v238, 0xbfb8aa3b, v229
	v_mul_f32_e32 v239, 0xbfb8aa3b, v228
	v_add_f32_e32 v234, 1.0, v234
	v_add_f32_e32 v235, 1.0, v235
	v_add_f32_e32 v236, 1.0, v236
	v_exp_f32_e32 v238, v238
	v_exp_f32_e32 v239, v239
	v_mul_f32_e32 v240, 0xbfb8aa3b, v227
	v_mul_f32_e32 v241, 0xbfb8aa3b, v226
	v_rcp_f32_e32 v234, v234
	v_rcp_f32_e32 v235, v235
	v_rcp_f32_e32 v236, v236
	v_add_f32_e32 v237, 1.0, v237
	v_exp_f32_e32 v240, v240
	v_exp_f32_e32 v241, v241
	v_rcp_f32_e32 v237, v237
	v_add_f32_e32 v238, 1.0, v238
	v_add_f32_e32 v239, 1.0, v239
	v_mul_f32_e32 v234, v128, v234
	v_mul_f32_e32 v235, v129, v235
	v_mul_f32_e32 v236, v130, v236
	v_rcp_f32_e32 v238, v238
	v_rcp_f32_e32 v239, v239
	v_add_f32_e32 v240, 1.0, v240
	v_add_f32_e32 v241, 1.0, v241
	v_mul_f32_e32 v237, v131, v237
	v_rcp_f32_e32 v240, v240
	v_rcp_f32_e32 v241, v241
	v_cvt_pk_bf16_f32 v234, v234, v235
	v_cvt_pk_bf16_f32 v235, v236, v237
	v_add_f32_e32 v236, v144, v225
	v_max_f32_e32 v236, 0xc2200000, v236
	v_mul_f32_e32 v236, 0xbfb8aa3b, v236
	v_mul_f32_e32 v238, v124, v238
	v_mul_f32_e32 v239, v125, v239
	v_exp_f32_e32 v242, v236
	v_cvt_pk_bf16_f32 v236, v238, v239
	v_mul_f32_e32 v240, v126, v240
	v_mul_f32_e32 v241, v127, v241
	v_cvt_pk_bf16_f32 v237, v240, v241
	flat_store_dwordx4 v[0:1], v[234:237]
	v_add_f32_e32 v238, v136, v221
	v_max_f32_e32 v238, 0xc2200000, v238
	v_add_f32_e32 v235, v145, v224
	v_add_f32_e32 v236, v146, v223
	v_max_f32_e32 v235, 0xc2200000, v235
	v_max_f32_e32 v236, 0xc2200000, v236
	v_add_f32_e32 v237, v147, v222
	v_add_f32_e32 v239, v137, v220
	v_mul_f32_e32 v235, 0xbfb8aa3b, v235
	v_mul_f32_e32 v236, 0xbfb8aa3b, v236
	v_max_f32_e32 v237, 0xc2200000, v237
	v_mul_f32_e32 v238, 0xbfb8aa3b, v238
	v_max_f32_e32 v239, 0xc2200000, v239
	v_exp_f32_e32 v235, v235
	v_exp_f32_e32 v236, v236
	v_mul_f32_e32 v237, 0xbfb8aa3b, v237
	v_exp_f32_e32 v238, v238
	v_mul_f32_e32 v239, 0xbfb8aa3b, v239
	v_add_f32_e32 v240, v138, v219
	v_exp_f32_e32 v237, v237
	v_exp_f32_e32 v239, v239
	v_max_f32_e32 v240, 0xc2200000, v240
	v_add_f32_e32 v241, v139, v218
	v_mul_f32_e32 v240, 0xbfb8aa3b, v240
	v_max_f32_e32 v241, 0xc2200000, v241
	v_exp_f32_e32 v240, v240
	v_mul_f32_e32 v241, 0xbfb8aa3b, v241
	v_add_f32_e32 v234, 1.0, v242
	v_add_f32_e32 v235, 1.0, v235
	v_add_f32_e32 v236, 1.0, v236
	v_add_f32_e32 v238, 1.0, v238
	v_exp_f32_e32 v241, v241
	v_rcp_f32_e32 v234, v234
	v_rcp_f32_e32 v235, v235
	v_rcp_f32_e32 v236, v236
	v_add_f32_e32 v237, 1.0, v237
	v_rcp_f32_e32 v238, v238
	v_add_f32_e32 v239, 1.0, v239
	v_rcp_f32_e32 v237, v237
	v_rcp_f32_e32 v239, v239
	v_add_f32_e32 v240, 1.0, v240
	v_rcp_f32_e32 v240, v240
	v_add_f32_e32 v241, 1.0, v241
	v_mul_f32_e32 v234, v120, v234
; __device__ __forceinline__ float sigmoidf_(float x) { return __builtin_amdgcn_rcpf(1.0f + __expf(-x)); }
;   __device__ __forceinline__ void operator()(EPI_ARGS) const {
;     ...
;           for (int m = 0; m < 4; ++m) {
;             float xc[8], y[8];
;             unpack8(zc[m], xc);
; #pragma unroll
;             for (int k = 0; k < 8; ++k) y[k] = acc[ai][bj][m][k >> 2][k & 3] * sigmoidf_(fmaxf(xc[k] + gc[k], -40.f));
;             u32x4 o;
;             o.x = pack2(y[0], y[1]); o.y = pack2(y[2], y[3]); o.z = pack2(y[4], y[5]); o.w = pack2(y[6], y[7]);
;             *(u32x4*)(mrow + (size_t)(ai * HALF + m * 16) * DM + bj * HALF) = o;
;           }
	v_mul_f32_e32 v235, v121, v235
	v_mul_f32_e32 v236, v122, v236
	v_rcp_f32_e32 v241, v241
	v_mul_f32_e32 v238, v116, v238
	v_mul_f32_e32 v237, v123, v237
	v_mul_f32_e32 v239, v117, v239
	v_cvt_pk_bf16_f32 v234, v234, v235
	v_cvt_pk_bf16_f32 v235, v236, v237
	v_cvt_pk_bf16_f32 v236, v238, v239
	v_add_f32_e32 v238, v144, v217
	v_max_f32_e32 v238, 0xc2200000, v238
	v_mul_f32_e32 v240, v118, v240
	v_mul_f32_e32 v238, 0xbfb8aa3b, v238
	v_mul_f32_e32 v241, v119, v241
	v_cvt_pk_bf16_f32 v237, v240, v241
	v_exp_f32_e32 v240, v238
	v_add_co_u32_e32 v238, vcc, s67, v0
	v_add_f32_e32 v241, v139, v196
	s_nop 0
	v_addc_co_u32_e32 v239, vcc, 0, v1, vcc
	flat_store_dwordx4 v[238:239], v[234:237]
	v_add_f32_e32 v238, v136, v213
	v_max_f32_e32 v238, 0xc2200000, v238
	v_add_f32_e32 v235, v145, v216
	v_add_f32_e32 v236, v146, v215
	v_max_f32_e32 v235, 0xc2200000, v235
	v_max_f32_e32 v236, 0xc2200000, v236
	v_add_f32_e32 v237, v147, v214
	v_add_f32_e32 v239, v137, v212
	v_mul_f32_e32 v235, 0xbfb8aa3b, v235
	v_mul_f32_e32 v236, 0xbfb8aa3b, v236
	v_max_f32_e32 v237, 0xc2200000, v237
	v_mul_f32_e32 v238, 0xbfb8aa3b, v238
	v_max_f32_e32 v239, 0xc2200000, v239
	v_add_f32_e32 v234, 1.0, v240
	v_exp_f32_e32 v235, v235
	v_exp_f32_e32 v236, v236
	v_mul_f32_e32 v237, 0xbfb8aa3b, v237
	v_exp_f32_e32 v238, v238
	v_mul_f32_e32 v239, 0xbfb8aa3b, v239
	v_add_f32_e32 v240, v138, v197
	v_exp_f32_e32 v237, v237
	v_exp_f32_e32 v239, v239
	v_max_f32_e32 v240, 0xc2200000, v240
	v_mul_f32_e32 v240, 0xbfb8aa3b, v240
	v_max_f32_e32 v241, 0xc2200000, v241
	v_exp_f32_e32 v240, v240
	v_mul_f32_e32 v241, 0xbfb8aa3b, v241
	v_add_f32_e32 v235, 1.0, v235
	v_add_f32_e32 v236, 1.0, v236
	v_add_f32_e32 v238, 1.0, v238
	v_exp_f32_e32 v241, v241
	v_rcp_f32_e32 v234, v234
	v_rcp_f32_e32 v235, v235
	v_rcp_f32_e32 v236, v236
	v_add_f32_e32 v237, 1.0, v237
	v_rcp_f32_e32 v238, v238
	v_add_f32_e32 v239, 1.0, v239
	v_rcp_f32_e32 v237, v237
	v_rcp_f32_e32 v239, v239
	v_add_f32_e32 v240, 1.0, v240
	v_rcp_f32_e32 v240, v240
	v_add_f32_e32 v241, 1.0, v241
	v_mul_f32_e32 v234, v112, v234
	v_mul_f32_e32 v235, v113, v235
	v_mul_f32_e32 v236, v114, v236
	v_rcp_f32_e32 v241, v241
	v_mul_f32_e32 v238, v108, v238
	v_mul_f32_e32 v237, v115, v237
	v_mul_f32_e32 v239, v109, v239
	v_cvt_pk_bf16_f32 v234, v234, v235
	v_cvt_pk_bf16_f32 v235, v236, v237
	v_cvt_pk_bf16_f32 v236, v238, v239
	v_add_f32_e32 v238, v144, v195
	v_max_f32_e32 v238, 0xc2200000, v238
	v_mul_f32_e32 v240, v110, v240
	v_mul_f32_e32 v238, 0xbfb8aa3b, v238
	s_mov_b32 s1, 0x20000
	v_mul_f32_e32 v241, v111, v241
	v_cvt_pk_bf16_f32 v237, v240, v241
	v_exp_f32_e32 v240, v238
	v_add_co_u32_e32 v238, vcc, s1, v0
	v_add_f32_e32 v241, v139, v2
	s_nop 0
	v_addc_co_u32_e32 v239, vcc, 0, v1, vcc
	flat_store_dwordx4 v[238:239], v[234:237]
	v_add_f32_e32 v238, v136, v191
	v_max_f32_e32 v238, 0xc2200000, v238
	v_add_f32_e32 v235, v145, v194
	v_add_f32_e32 v236, v146, v193
	v_max_f32_e32 v235, 0xc2200000, v235
	v_max_f32_e32 v236, 0xc2200000, v236
	v_add_f32_e32 v237, v147, v192
	v_add_f32_e32 v239, v137, v190
	v_mul_f32_e32 v235, 0xbfb8aa3b, v235
	v_mul_f32_e32 v236, 0xbfb8aa3b, v236
	v_max_f32_e32 v237, 0xc2200000, v237
	v_mul_f32_e32 v238, 0xbfb8aa3b, v238
	v_max_f32_e32 v239, 0xc2200000, v239
	v_add_f32_e32 v234, 1.0, v240
	v_exp_f32_e32 v235, v235
	v_exp_f32_e32 v236, v236
	v_mul_f32_e32 v237, 0xbfb8aa3b, v237
	v_exp_f32_e32 v238, v238
	v_mul_f32_e32 v239, 0xbfb8aa3b, v239
	v_add_f32_e32 v240, v138, v189
	v_exp_f32_e32 v237, v237
	v_exp_f32_e32 v239, v239
	v_max_f32_e32 v240, 0xc2200000, v240
	v_max_f32_e32 v241, 0xc2200000, v241
	v_mul_f32_e32 v240, 0xbfb8aa3b, v240
	v_mul_f32_e32 v241, 0xbfb8aa3b, v241
	v_exp_f32_e32 v240, v240
	v_exp_f32_e32 v241, v241
	v_add_f32_e32 v235, 1.0, v235
	v_add_f32_e32 v236, 1.0, v236
	v_add_f32_e32 v238, 1.0, v238
	v_rcp_f32_e32 v234, v234
	v_rcp_f32_e32 v235, v235
	v_rcp_f32_e32 v236, v236
	v_add_f32_e32 v237, 1.0, v237
	v_rcp_f32_e32 v238, v238
	v_add_f32_e32 v239, 1.0, v239
	v_rcp_f32_e32 v237, v237
	v_rcp_f32_e32 v239, v239
	v_add_f32_e32 v240, 1.0, v240
	v_add_f32_e32 v241, 1.0, v241
	v_rcp_f32_e32 v240, v240
	v_rcp_f32_e32 v241, v241
	v_mul_f32_e32 v234, v104, v234
	v_mul_f32_e32 v235, v105, v235
	v_mul_f32_e32 v236, v106, v236
	v_mul_f32_e32 v238, v100, v238
	v_mul_f32_e32 v237, v107, v237
	v_mul_f32_e32 v239, v101, v239
	v_cvt_pk_bf16_f32 v234, v234, v235
	v_cvt_pk_bf16_f32 v235, v236, v237
	v_cvt_pk_bf16_f32 v236, v238, v239
	v_add_co_u32_e32 v238, vcc, 0x30000, v0
	s_mov_b64 s[8:9], 0
	s_nop 0
	v_addc_co_u32_e32 v239, vcc, 0, v1, vcc
	v_mul_f32_e32 v240, v102, v240
	v_mul_f32_e32 v241, v103, v241
	v_cvt_pk_bf16_f32 v237, v240, v241
	flat_store_dwordx4 v[238:239], v[234:237]

; #define PG8_WAIT_V(n) asm volatile("s_waitcnt vmcnt(" #n ")" ::: "memory")
; #define PG8_WAIT_L(n) asm volatile("s_waitcnt lgkmcnt(" #n ")" ::: "memory")
; #define PG8_BAR __builtin_amdgcn_s_barrier()
; #define PG8_SCHED __builtin_amdgcn_sched_barrier(0)
; template <class Epi, class AddrA, class AddrB>
; __device__ __forceinline__ void gemm_phase(const Sched S, const int lda, const int ldb, const int K, const AddrA addrA,
;                                            const AddrB addrB, const Epi E) {
;     ...
;     const bool has_next = S.next(ui + 1, nxt);
;     const char* nA = has_next ? addrA(nxt) : cA;
;     const char* nB = has_next ? addrB(nxt) : cB;
;     for (int t = 0; t < nt; t += 2) {
;       const bool last = (t == nt - 2);
;       const char* a1 = cA + (size_t)(t + 1) * kstep;
;       const char* a2 = last ? nA : cA + (size_t)(t + 2) * kstep;
;       const char* b2 = last ? nB : cB + (size_t)(t + 2) * kstep;
;       const char* a3 = a2 + kstep;
;       const char* b3 = b2 + kstep;
;       PG8_LDB(B0, 0, 0); PG8_SCHED; PG8_LDA(At, 0, 0); PG8_STAGE(PG8_SA(1, 1), a1 + hstepA, voffA);
;       PG8_WAIT_L(8); PG8_BAR; PG8_WAIT_L(0); PG8_MMA(0, 0, At, B0); PG8_BAR; PG8_SCHED;
;       PG8_LDB(B1, 0, 1); PG8_STAGE(PG8_SB(0, 0), b2, voffB);
;       PG8_BAR; PG8_WAIT_L(0); PG8_MMA(0, 1, At, B1); PG8_BAR;
;       PG8_LDA(At, 0, 1); PG8_STAGE(PG8_SA(0, 0), a2, voffA);
;       PG8_BAR; PG8_WAIT_L(0); PG8_MMA(1, 0, At, B0); PG8_BAR; PG8_SCHED;
;       PG8_STAGE(PG8_SB(0, 1), b2 + hstepB, voffB);
;       PG8_WAIT_V(6); PG8_BAR; PG8_MMA(1, 1, At, B1); PG8_BAR;
.LBB0_618:
	s_ashr_i32 s3, s2, 31
	s_lshl_b64 s[8:9], s[2:3], 20
	s_add_u32 s8, s23, s8
	s_addc_u32 s9, s24, s9
	s_and_b64 s[10:11], s[18:19], exec
	s_cselect_b32 s3, s9, s17
	s_cselect_b32 s13, s8, s16
	s_ashr_i32 s5, s4, 31
	s_lshl_b64 s[10:11], s[4:5], 20
	s_add_u32 s10, s21, s10
	s_addc_u32 s11, s22, s11
	s_and_b64 s[18:19], s[18:19], exec
	s_cselect_b32 s5, s11, s15
	s_cselect_b32 s35, s10, s14
	s_add_u32 s36, s14, 0x100
	s_addc_u32 s37, s15, 0
	s_add_u32 s14, s16, 0x80080
	s_addc_u32 s15, s17, 0
	s_mov_b32 s38, -2
	s_add_u32 s16, s14, 0xfff80080
	s_addc_u32 s17, s15, -1
	s_add_i32 s39, 0, 0x10000
	v_add_u32_e32 v142, s39, v144
	ds_read_b128 v[148:151], v142
	ds_read_b128 v[152:155], v142 offset:1024
	ds_read_b128 v[156:159], v142 offset:2048
	ds_read_b128 v[160:163], v142 offset:3072
	s_cmp_eq_u32 s38, 28
	s_cselect_b32 s19, s3, s17
	s_cselect_b32 s18, s13, s16
	s_cselect_b32 s17, s5, s37
	s_cselect_b32 s16, s35, s36
	v_lshl_add_u64 v[142:143], s[14:15], 0, v[140:141]
	s_add_i32 m0, s26, 0xc000
	ds_read_b128 v[168:171], v146
	ds_read_b128 v[172:175], v146 offset:1024
	ds_read_b128 v[176:179], v146 offset:2048
	ds_read_b128 v[180:183], v146 offset:3072
	ds_read_b128 v[184:187], v146 offset:4096
	ds_read_b128 v[188:191], v146 offset:5120
	ds_read_b128 v[192:195], v146 offset:6144
	ds_read_b128 v[212:215], v146 offset:7168
	global_load_lds_dwordx4 v[142:143], off
	v_lshl_add_u64 v[142:143], s[14:15], 0, v[138:139]
	s_add_i32 m0, s26, 0xe000
	s_nop 0
	global_load_lds_dwordx4 v[142:143], off
	s_waitcnt lgkmcnt(8)
	s_barrier
	s_waitcnt lgkmcnt(0)
	s_setprio 1
	v_mfma_f32_16x16x32_bf16 v[128:131], v[148:151], v[168:171], 0
	v_mfma_f32_16x16x32_bf16 v[128:131], v[152:155], v[172:175], v[128:131]
	v_mfma_f32_16x16x32_bf16 v[120:123], v[148:151], v[176:179], 0
	v_mfma_f32_16x16x32_bf16 v[120:123], v[152:155], v[180:183], v[120:123]
	v_mfma_f32_16x16x32_bf16 v[112:115], v[148:151], v[184:187], 0
	v_mfma_f32_16x16x32_bf16 v[112:115], v[152:155], v[188:191], v[112:115]
	v_mfma_f32_16x16x32_bf16 v[104:107], v[148:151], v[192:195], 0
	v_mfma_f32_16x16x32_bf16 v[104:107], v[152:155], v[212:215], v[104:107]
	v_mfma_f32_16x16x32_bf16 v[124:127], v[156:159], v[168:171], 0
	v_mfma_f32_16x16x32_bf16 v[124:127], v[160:163], v[172:175], v[124:127]
	v_mfma_f32_16x16x32_bf16 v[116:119], v[156:159], v[176:179], 0
	v_mfma_f32_16x16x32_bf16 v[116:119], v[160:163], v[180:183], v[116:119]
	v_mfma_f32_16x16x32_bf16 v[108:111], v[156:159], v[184:187], 0
	v_mfma_f32_16x16x32_bf16 v[108:111], v[160:163], v[188:191], v[108:111]
	v_mfma_f32_16x16x32_bf16 v[100:103], v[156:159], v[192:195], 0
	v_mfma_f32_16x16x32_bf16 v[100:103], v[160:163], v[212:215], v[100:103]
	s_barrier
	s_setprio 0
	s_add_i32 s42, 0, 0x14000
	v_add_u32_e32 v142, s42, v144
	s_add_i32 s39, s39, s25
	ds_read_b128 v[216:219], v142
	ds_read_b128 v[220:223], v142 offset:1024
	ds_read_b128 v[224:227], v142 offset:2048
	ds_read_b128 v[228:231], v142 offset:3072
	v_lshl_add_u64 v[142:143], s[16:17], 0, v[2:3]
	s_mov_b32 m0, s39
	v_lshl_add_u64 v[196:197], s[16:17], 0, v[0:1]
	global_load_lds_dwordx4 v[142:143], off
	s_add_i32 m0, s39, 0x2000
	s_nop 0
	global_load_lds_dwordx4 v[196:197], off
	s_barrier
	s_waitcnt lgkmcnt(0)
	s_setprio 1
	v_mfma_f32_16x16x32_bf16 v[96:99], v[216:219], v[168:171], 0
	v_mfma_f32_16x16x32_bf16 v[96:99], v[220:223], v[172:175], v[96:99]
	v_mfma_f32_16x16x32_bf16 v[88:91], v[216:219], v[176:179], 0
	v_mfma_f32_16x16x32_bf16 v[88:91], v[220:223], v[180:183], v[88:91]
	v_mfma_f32_16x16x32_bf16 v[80:83], v[216:219], v[184:187], 0
	v_mfma_f32_16x16x32_bf16 v[80:83], v[220:223], v[188:191], v[80:83]
	v_mfma_f32_16x16x32_bf16 v[72:75], v[216:219], v[192:195], 0
	v_mfma_f32_16x16x32_bf16 v[72:75], v[220:223], v[212:215], v[72:75]
	v_mfma_f32_16x16x32_bf16 v[92:95], v[224:227], v[168:171], 0
	v_mfma_f32_16x16x32_bf16 v[92:95], v[228:231], v[172:175], v[92:95]
	v_mfma_f32_16x16x32_bf16 v[84:87], v[224:227], v[176:179], 0
	v_mfma_f32_16x16x32_bf16 v[84:87], v[228:231], v[180:183], v[84:87]
	v_mfma_f32_16x16x32_bf16 v[76:79], v[224:227], v[184:187], 0
	v_mfma_f32_16x16x32_bf16 v[76:79], v[228:231], v[188:191], v[76:79]
	v_mfma_f32_16x16x32_bf16 v[68:71], v[224:227], v[192:195], 0
	v_mfma_f32_16x16x32_bf16 v[68:71], v[228:231], v[212:215], v[68:71]
	s_mov_b32 m0, s26
	v_lshl_add_u64 v[232:233], s[18:19], 0, v[134:135]
	s_barrier
	s_setprio 0
	ds_read_b128 v[168:171], v146 offset:16384
	ds_read_b128 v[172:175], v146 offset:17408
	ds_read_b128 v[176:179], v146 offset:18432
	ds_read_b128 v[180:183], v146 offset:19456
	ds_read_b128 v[184:187], v146 offset:20480
	ds_read_b128 v[188:191], v146 offset:21504
	ds_read_b128 v[192:195], v146 offset:22528
	ds_read_b128 v[212:215], v146 offset:23552
	global_load_lds_dwordx4 v[232:233], off
	v_lshl_add_u64 v[234:235], s[18:19], 0, v[132:133]
	s_mov_b32 m0, s27
	s_nop 0
	global_load_lds_dwordx4 v[234:235], off
	s_barrier
	s_waitcnt lgkmcnt(0)
	s_setprio 1
	v_mfma_f32_16x16x32_bf16 v[64:67], v[148:151], v[168:171], 0
	v_mfma_f32_16x16x32_bf16 v[64:67], v[152:155], v[172:175], v[64:67]
	v_mfma_f32_16x16x32_bf16 v[56:59], v[148:151], v[176:179], 0
	v_mfma_f32_16x16x32_bf16 v[56:59], v[152:155], v[180:183], v[56:59]
	v_mfma_f32_16x16x32_bf16 v[48:51], v[148:151], v[184:187], 0
	v_mfma_f32_16x16x32_bf16 v[48:51], v[152:155], v[188:191], v[48:51]
	v_mfma_f32_16x16x32_bf16 v[40:43], v[148:151], v[192:195], 0
	v_mfma_f32_16x16x32_bf16 v[40:43], v[152:155], v[212:215], v[40:43]
	v_mfma_f32_16x16x32_bf16 v[60:63], v[156:159], v[168:171], 0
	v_mfma_f32_16x16x32_bf16 v[60:63], v[160:163], v[172:175], v[60:63]
	v_mfma_f32_16x16x32_bf16 v[52:55], v[156:159], v[176:179], 0
	v_mfma_f32_16x16x32_bf16 v[52:55], v[160:163], v[180:183], v[52:55]
	v_mfma_f32_16x16x32_bf16 v[44:47], v[156:159], v[184:187], 0
	v_mfma_f32_16x16x32_bf16 v[44:47], v[160:163], v[188:191], v[44:47]
	v_mfma_f32_16x16x32_bf16 v[36:39], v[156:159], v[192:195], 0
	v_mfma_f32_16x16x32_bf16 v[36:39], v[160:163], v[212:215], v[36:39]
	s_barrier
; #define PG8_WAIT_V(n) asm volatile("s_waitcnt vmcnt(" #n ")" ::: "memory")
; #define PG8_WAIT_L(n) asm volatile("s_waitcnt lgkmcnt(" #n ")" ::: "memory")
; #define PG8_BAR __builtin_amdgcn_s_barrier()
; #define PG8_SCHED __builtin_amdgcn_sched_barrier(0)
; template <class Epi, class AddrA, class AddrB>
; __device__ __forceinline__ void gemm_phase(const Sched S, const int lda, const int ldb, const int K, const AddrA addrA,
;                                            const AddrB addrB, const Epi E) {
;     ...
;       PG8_BAR; PG8_WAIT_L(0); PG8_MMA(1, 0, At, B0); PG8_BAR; PG8_SCHED;
;       PG8_STAGE(PG8_SB(0, 1), b2 + hstepB, voffB);
;       PG8_WAIT_V(6); PG8_BAR; PG8_MMA(1, 1, At, B1); PG8_BAR;
;       PG8_LDB(B0, 1, 0); PG8_SCHED; PG8_LDA(At, 1, 0); PG8_STAGE(PG8_SA(0, 1), a2 + hstepA, voffA);
;       PG8_WAIT_L(8); PG8_BAR; PG8_WAIT_L(0); PG8_MMA(0, 0, At, B0); PG8_BAR; PG8_SCHED;
;       PG8_LDB(B1, 1, 1); PG8_STAGE(PG8_SB(1, 0), b3, voffB);
;       PG8_BAR; PG8_WAIT_L(0); PG8_MMA(0, 1, At, B1); PG8_BAR;
;       PG8_LDA(At, 1, 1); PG8_STAGE(PG8_SA(1, 0), a3, voffA);
;       PG8_BAR; PG8_WAIT_L(0); PG8_MMA(1, 0, At, B0); PG8_BAR; PG8_SCHED;
;       PG8_STAGE(PG8_SB(1, 1), b3 + hstepB, voffB);
;       PG8_WAIT_V(6); PG8_BAR; PG8_MMA(1, 1, At, B1); PG8_BAR;
	s_setprio 0
	s_add_u32 s40, s16, 0x80000
	s_addc_u32 s41, s17, 0
	s_add_i32 s39, s42, s25
	v_lshl_add_u64 v[148:149], s[40:41], 0, v[2:3]
	s_mov_b32 m0, s39
	s_nop 0
	global_load_lds_dwordx4 v[148:149], off
	v_lshl_add_u64 v[148:149], s[40:41], 0, v[0:1]
	s_add_i32 m0, s39, 0x2000
	s_nop 0
	global_load_lds_dwordx4 v[148:149], off
	s_waitcnt vmcnt(6)
	s_barrier
	s_setprio 1
	v_mfma_f32_16x16x32_bf16 v[32:35], v[216:219], v[168:171], 0
	v_mfma_f32_16x16x32_bf16 v[32:35], v[220:223], v[172:175], v[32:35]
	v_mfma_f32_16x16x32_bf16 v[24:27], v[216:219], v[176:179], 0
	v_mfma_f32_16x16x32_bf16 v[24:27], v[220:223], v[180:183], v[24:27]
	v_mfma_f32_16x16x32_bf16 v[16:19], v[216:219], v[184:187], 0
	v_mfma_f32_16x16x32_bf16 v[16:19], v[220:223], v[188:191], v[16:19]
	v_mfma_f32_16x16x32_bf16 v[8:11], v[216:219], v[192:195], 0
	v_mfma_f32_16x16x32_bf16 v[8:11], v[220:223], v[212:215], v[8:11]
	v_mfma_f32_16x16x32_bf16 v[28:31], v[224:227], v[168:171], 0
	v_mfma_f32_16x16x32_bf16 v[28:31], v[228:231], v[172:175], v[28:31]
	v_mfma_f32_16x16x32_bf16 v[20:23], v[224:227], v[176:179], 0
	v_mfma_f32_16x16x32_bf16 v[20:23], v[228:231], v[180:183], v[20:23]
	v_mfma_f32_16x16x32_bf16 v[12:15], v[224:227], v[184:187], 0
	v_mfma_f32_16x16x32_bf16 v[12:15], v[228:231], v[188:191], v[12:15]
	v_mfma_f32_16x16x32_bf16 v[4:7], v[224:227], v[192:195], 0
	v_mfma_f32_16x16x32_bf16 v[4:7], v[228:231], v[212:215], v[4:7]
	s_add_i32 s39, 0, 0x18000
	v_add_u32_e32 v147, s39, v144
	s_barrier
	s_setprio 0
	ds_read_b128 v[148:151], v147
	ds_read_b128 v[152:155], v147 offset:1024
	ds_read_b128 v[156:159], v147 offset:2048
	ds_read_b128 v[160:163], v147 offset:3072
	s_add_u32 s18, s18, 0x80000
	s_addc_u32 s19, s19, 0
	s_mov_b32 m0, s28
	v_lshl_add_u64 v[216:217], s[18:19], 0, v[134:135]
	ds_read_b128 v[168:171], v146 offset:32768
	ds_read_b128 v[172:175], v146 offset:33792
	ds_read_b128 v[176:179], v146 offset:34816
	ds_read_b128 v[180:183], v146 offset:35840
	ds_read_b128 v[184:187], v146 offset:36864
	ds_read_b128 v[188:191], v146 offset:37888
	ds_read_b128 v[192:195], v146 offset:38912
	ds_read_b128 v[212:215], v146 offset:39936
	global_load_lds_dwordx4 v[216:217], off
	v_lshl_add_u64 v[216:217], s[18:19], 0, v[132:133]
	s_mov_b32 m0, s29
	s_nop 0
	global_load_lds_dwordx4 v[216:217], off
	s_waitcnt lgkmcnt(8)
	s_barrier
	s_waitcnt lgkmcnt(0)
	s_setprio 1
	v_mfma_f32_16x16x32_bf16 v[128:131], v[148:151], v[168:171], v[128:131]
	v_mfma_f32_16x16x32_bf16 v[128:131], v[152:155], v[172:175], v[128:131]
	v_mfma_f32_16x16x32_bf16 v[120:123], v[148:151], v[176:179], v[120:123]
	v_mfma_f32_16x16x32_bf16 v[120:123], v[152:155], v[180:183], v[120:123]
	v_mfma_f32_16x16x32_bf16 v[112:115], v[148:151], v[184:187], v[112:115]
	v_mfma_f32_16x16x32_bf16 v[112:115], v[152:155], v[188:191], v[112:115]
	v_mfma_f32_16x16x32_bf16 v[104:107], v[148:151], v[192:195], v[104:107]
	v_mfma_f32_16x16x32_bf16 v[104:107], v[152:155], v[212:215], v[104:107]
	v_mfma_f32_16x16x32_bf16 v[124:127], v[156:159], v[168:171], v[124:127]
	v_mfma_f32_16x16x32_bf16 v[124:127], v[160:163], v[172:175], v[124:127]
	v_mfma_f32_16x16x32_bf16 v[116:119], v[156:159], v[176:179], v[116:119]
	v_mfma_f32_16x16x32_bf16 v[116:119], v[160:163], v[180:183], v[116:119]
	v_mfma_f32_16x16x32_bf16 v[108:111], v[156:159], v[184:187], v[108:111]
	v_mfma_f32_16x16x32_bf16 v[108:111], v[160:163], v[188:191], v[108:111]
	v_mfma_f32_16x16x32_bf16 v[100:103], v[156:159], v[192:195], v[100:103]
	v_mfma_f32_16x16x32_bf16 v[100:103], v[160:163], v[212:215], v[100:103]
	s_barrier
	s_setprio 0
	s_add_i32 s18, 0, 0x1c000
	s_add_i32 s19, s39, s25
	v_add_u32_e32 v147, s18, v144
	v_lshl_add_u64 v[142:143], v[142:143], 0, s[52:53]
	s_mov_b32 m0, s19
	ds_read_b128 v[216:219], v147
	ds_read_b128 v[220:223], v147 offset:1024
	ds_read_b128 v[224:227], v147 offset:2048
	ds_read_b128 v[228:231], v147 offset:3072
	global_load_lds_dwordx4 v[142:143], off
	v_lshl_add_u64 v[142:143], v[196:197], 0, s[52:53]
	s_add_i32 m0, s19, 0x2000
	s_nop 0
	global_load_lds_dwordx4 v[142:143], off
	s_barrier
	s_waitcnt lgkmcnt(0)
	s_setprio 1
	v_mfma_f32_16x16x32_bf16 v[96:99], v[216:219], v[168:171], v[96:99]
	v_mfma_f32_16x16x32_bf16 v[96:99], v[220:223], v[172:175], v[96:99]
	v_mfma_f32_16x16x32_bf16 v[88:91], v[216:219], v[176:179], v[88:91]
	v_mfma_f32_16x16x32_bf16 v[88:91], v[220:223], v[180:183], v[88:91]
	v_mfma_f32_16x16x32_bf16 v[80:83], v[216:219], v[184:187], v[80:83]
	v_mfma_f32_16x16x32_bf16 v[80:83], v[220:223], v[188:191], v[80:83]
	v_mfma_f32_16x16x32_bf16 v[72:75], v[216:219], v[192:195], v[72:75]
	v_mfma_f32_16x16x32_bf16 v[72:75], v[220:223], v[212:215], v[72:75]
	v_mfma_f32_16x16x32_bf16 v[92:95], v[224:227], v[168:171], v[92:95]
	v_mfma_f32_16x16x32_bf16 v[92:95], v[228:231], v[172:175], v[92:95]
	v_mfma_f32_16x16x32_bf16 v[84:87], v[224:227], v[176:179], v[84:87]
	v_mfma_f32_16x16x32_bf16 v[84:87], v[228:231], v[180:183], v[84:87]
	v_mfma_f32_16x16x32_bf16 v[76:79], v[224:227], v[184:187], v[76:79]
	v_mfma_f32_16x16x32_bf16 v[76:79], v[228:231], v[188:191], v[76:79]
	v_mfma_f32_16x16x32_bf16 v[68:71], v[224:227], v[192:195], v[68:71]
	v_mfma_f32_16x16x32_bf16 v[68:71], v[228:231], v[212:215], v[68:71]
	s_mov_b32 m0, s30
	v_lshl_add_u64 v[142:143], v[232:233], 0, s[52:53]
	s_barrier
	s_setprio 0
	ds_read_b128 v[168:171], v146 offset:49152
	ds_read_b128 v[172:175], v146 offset:50176
	ds_read_b128 v[176:179], v146 offset:51200
	ds_read_b128 v[180:183], v146 offset:52224
	ds_read_b128 v[184:187], v146 offset:53248
	ds_read_b128 v[188:191], v146 offset:54272
	ds_read_b128 v[192:195], v146 offset:55296
	ds_read_b128 v[212:215], v146 offset:56320
	global_load_lds_dwordx4 v[142:143], off
	v_lshl_add_u64 v[142:143], v[234:235], 0, s[52:53]
	s_mov_b32 m0, s31
	s_nop 0
	global_load_lds_dwordx4 v[142:143], off
	s_barrier
; #define PG8_WAIT_V(n) asm volatile("s_waitcnt vmcnt(" #n ")" ::: "memory")
; #define PG8_WAIT_L(n) asm volatile("s_waitcnt lgkmcnt(" #n ")" ::: "memory")
; #define PG8_BAR __builtin_amdgcn_s_barrier()
; #define PG8_SCHED __builtin_amdgcn_sched_barrier(0)
; template <class Epi, class AddrA, class AddrB>
; __device__ __forceinline__ void gemm_phase(const Sched S, const int lda, const int ldb, const int K, const AddrA addrA,
;                                            const AddrB addrB, const Epi E) {
;     ...
;     for (int t = 0; t < nt; t += 2) {
;       const bool last = (t == nt - 2);
;       const char* a1 = cA + (size_t)(t + 1) * kstep;
;       const char* a2 = last ? nA : cA + (size_t)(t + 2) * kstep;
;       const char* b2 = last ? nB : cB + (size_t)(t + 2) * kstep;
;       const char* a3 = a2 + kstep;
;       const char* b3 = b2 + kstep;
;       PG8_LDB(B0, 0, 0); PG8_SCHED; PG8_LDA(At, 0, 0); PG8_STAGE(PG8_SA(1, 1), a1 + hstepA, voffA);
;       PG8_WAIT_L(8); PG8_BAR; PG8_WAIT_L(0); PG8_MMA(0, 0, At, B0); PG8_BAR; PG8_SCHED;
;       PG8_LDB(B1, 0, 1); PG8_STAGE(PG8_SB(0, 0), b2, voffB);
;       PG8_BAR; PG8_WAIT_L(0); PG8_MMA(0, 1, At, B1); PG8_BAR;
;     ...
;       PG8_BAR; PG8_WAIT_L(0); PG8_MMA(1, 0, At, B0); PG8_BAR; PG8_SCHED;
;       PG8_STAGE(PG8_SB(1, 1), b3 + hstepB, voffB);
;       PG8_WAIT_V(6); PG8_BAR; PG8_MMA(1, 1, At, B1); PG8_BAR;
	s_waitcnt lgkmcnt(0)
	s_setprio 1
	v_mfma_f32_16x16x32_bf16 v[64:67], v[148:151], v[168:171], v[64:67]
	v_mfma_f32_16x16x32_bf16 v[64:67], v[152:155], v[172:175], v[64:67]
	v_mfma_f32_16x16x32_bf16 v[56:59], v[148:151], v[176:179], v[56:59]
	v_mfma_f32_16x16x32_bf16 v[56:59], v[152:155], v[180:183], v[56:59]
	v_mfma_f32_16x16x32_bf16 v[48:51], v[148:151], v[184:187], v[48:51]
	v_mfma_f32_16x16x32_bf16 v[48:51], v[152:155], v[188:191], v[48:51]
	v_mfma_f32_16x16x32_bf16 v[40:43], v[148:151], v[192:195], v[40:43]
	v_mfma_f32_16x16x32_bf16 v[40:43], v[152:155], v[212:215], v[40:43]
	v_mfma_f32_16x16x32_bf16 v[60:63], v[156:159], v[168:171], v[60:63]
	v_mfma_f32_16x16x32_bf16 v[60:63], v[160:163], v[172:175], v[60:63]
	v_mfma_f32_16x16x32_bf16 v[52:55], v[156:159], v[176:179], v[52:55]
	v_mfma_f32_16x16x32_bf16 v[52:55], v[160:163], v[180:183], v[52:55]
	v_mfma_f32_16x16x32_bf16 v[44:47], v[156:159], v[184:187], v[44:47]
	v_mfma_f32_16x16x32_bf16 v[44:47], v[160:163], v[188:191], v[44:47]
	v_mfma_f32_16x16x32_bf16 v[36:39], v[156:159], v[192:195], v[36:39]
	v_mfma_f32_16x16x32_bf16 v[36:39], v[160:163], v[212:215], v[36:39]
	s_barrier
	s_setprio 0
	s_add_u32 s16, s16, 0x80080
	s_addc_u32 s17, s17, 0
	s_add_i32 s18, s18, s25
	v_lshl_add_u64 v[142:143], s[16:17], 0, v[2:3]
	s_mov_b32 m0, s18
	s_nop 0
	global_load_lds_dwordx4 v[142:143], off
	v_lshl_add_u64 v[142:143], s[16:17], 0, v[0:1]
	s_add_i32 m0, s18, 0x2000
	s_nop 0
	global_load_lds_dwordx4 v[142:143], off
	s_waitcnt vmcnt(6)
	s_barrier
	s_setprio 1
	v_mfma_f32_16x16x32_bf16 v[32:35], v[216:219], v[168:171], v[32:35]
	v_mfma_f32_16x16x32_bf16 v[32:35], v[220:223], v[172:175], v[32:35]
	v_mfma_f32_16x16x32_bf16 v[24:27], v[216:219], v[176:179], v[24:27]
	v_mfma_f32_16x16x32_bf16 v[24:27], v[220:223], v[180:183], v[24:27]
	v_mfma_f32_16x16x32_bf16 v[16:19], v[216:219], v[184:187], v[16:19]
	v_mfma_f32_16x16x32_bf16 v[16:19], v[220:223], v[188:191], v[16:19]
	v_mfma_f32_16x16x32_bf16 v[8:11], v[216:219], v[192:195], v[8:11]
	v_mfma_f32_16x16x32_bf16 v[8:11], v[220:223], v[212:215], v[8:11]
	v_mfma_f32_16x16x32_bf16 v[28:31], v[224:227], v[168:171], v[28:31]
	v_mfma_f32_16x16x32_bf16 v[28:31], v[228:231], v[172:175], v[28:31]
	v_mfma_f32_16x16x32_bf16 v[20:23], v[224:227], v[176:179], v[20:23]
	v_mfma_f32_16x16x32_bf16 v[20:23], v[228:231], v[180:183], v[20:23]
	v_mfma_f32_16x16x32_bf16 v[12:15], v[224:227], v[184:187], v[12:15]
	v_mfma_f32_16x16x32_bf16 v[12:15], v[228:231], v[188:191], v[12:15]
	v_mfma_f32_16x16x32_bf16 v[4:7], v[224:227], v[192:195], v[4:7]
	v_mfma_f32_16x16x32_bf16 v[4:7], v[228:231], v[212:215], v[4:7]
	s_add_i32 s38, s38, 2
	s_add_u32 s36, s36, 0x100
	s_addc_u32 s37, s37, 0
	s_add_u32 s14, s14, 0x100
	s_addc_u32 s15, s15, 0
	s_cmp_gt_u32 s38, 29
	s_barrier
	s_setprio 0
.LBB0_619:
	s_add_u32 s16, s14, 0xfff80080
	s_addc_u32 s17, s15, -1
	s_add_i32 s39, 0, 0x10000
	v_add_u32_e32 v142, s39, v144
	ds_read_b128 v[148:151], v142
	ds_read_b128 v[152:155], v142 offset:1024
	ds_read_b128 v[156:159], v142 offset:2048
	ds_read_b128 v[160:163], v142 offset:3072
	s_cmp_eq_u32 s38, 28
	s_cselect_b32 s19, s3, s17
	s_cselect_b32 s18, s13, s16
	s_cselect_b32 s17, s5, s37
	s_cselect_b32 s16, s35, s36
	v_lshl_add_u64 v[142:143], s[14:15], 0, v[140:141]
	s_add_i32 m0, s26, 0xc000
	ds_read_b128 v[168:171], v146
	ds_read_b128 v[172:175], v146 offset:1024
	ds_read_b128 v[176:179], v146 offset:2048
	ds_read_b128 v[180:183], v146 offset:3072
	ds_read_b128 v[184:187], v146 offset:4096
	ds_read_b128 v[188:191], v146 offset:5120
	ds_read_b128 v[192:195], v146 offset:6144
	ds_read_b128 v[212:215], v146 offset:7168
	global_load_lds_dwordx4 v[142:143], off
	v_lshl_add_u64 v[142:143], s[14:15], 0, v[138:139]
	s_add_i32 m0, s26, 0xe000
	s_nop 0
	global_load_lds_dwordx4 v[142:143], off
	s_waitcnt lgkmcnt(8)
	s_barrier
	s_waitcnt lgkmcnt(0)
	s_setprio 1
	v_mfma_f32_16x16x32_bf16 v[128:131], v[148:151], v[168:171], v[128:131]
	v_mfma_f32_16x16x32_bf16 v[128:131], v[152:155], v[172:175], v[128:131]
	v_mfma_f32_16x16x32_bf16 v[120:123], v[148:151], v[176:179], v[120:123]
	v_mfma_f32_16x16x32_bf16 v[120:123], v[152:155], v[180:183], v[120:123]
	v_mfma_f32_16x16x32_bf16 v[112:115], v[148:151], v[184:187], v[112:115]
	v_mfma_f32_16x16x32_bf16 v[112:115], v[152:155], v[188:191], v[112:115]
	v_mfma_f32_16x16x32_bf16 v[104:107], v[148:151], v[192:195], v[104:107]
	v_mfma_f32_16x16x32_bf16 v[104:107], v[152:155], v[212:215], v[104:107]
	v_mfma_f32_16x16x32_bf16 v[124:127], v[156:159], v[168:171], v[124:127]
	v_mfma_f32_16x16x32_bf16 v[124:127], v[160:163], v[172:175], v[124:127]
	v_mfma_f32_16x16x32_bf16 v[116:119], v[156:159], v[176:179], v[116:119]
	v_mfma_f32_16x16x32_bf16 v[116:119], v[160:163], v[180:183], v[116:119]
	v_mfma_f32_16x16x32_bf16 v[108:111], v[156:159], v[184:187], v[108:111]
	v_mfma_f32_16x16x32_bf16 v[108:111], v[160:163], v[188:191], v[108:111]
	v_mfma_f32_16x16x32_bf16 v[100:103], v[156:159], v[192:195], v[100:103]
	v_mfma_f32_16x16x32_bf16 v[100:103], v[160:163], v[212:215], v[100:103]
	s_barrier
	s_setprio 0
	s_add_i32 s42, 0, 0x14000
	v_add_u32_e32 v142, s42, v144
	s_add_i32 s39, s39, s25
	ds_read_b128 v[216:219], v142
	ds_read_b128 v[220:223], v142 offset:1024
	ds_read_b128 v[224:227], v142 offset:2048
	ds_read_b128 v[228:231], v142 offset:3072
	v_lshl_add_u64 v[142:143], s[16:17], 0, v[2:3]
	s_mov_b32 m0, s39
	v_lshl_add_u64 v[196:197], s[16:17], 0, v[0:1]
	global_load_lds_dwordx4 v[142:143], off
	s_add_i32 m0, s39, 0x2000
	s_nop 0
	global_load_lds_dwordx4 v[196:197], off
	s_barrier
; #define PG8_WAIT_V(n) asm volatile("s_waitcnt vmcnt(" #n ")" ::: "memory")
; #define PG8_WAIT_L(n) asm volatile("s_waitcnt lgkmcnt(" #n ")" ::: "memory")
; #define PG8_BAR __builtin_amdgcn_s_barrier()
; #define PG8_SCHED __builtin_amdgcn_sched_barrier(0)
; template <class Epi, class AddrA, class AddrB>
; __device__ __forceinline__ void gemm_phase(const Sched S, const int lda, const int ldb, const int K, const AddrA addrA,
;                                            const AddrB addrB, const Epi E) {
;     ...
;       PG8_WAIT_L(8); PG8_BAR; PG8_WAIT_L(0); PG8_MMA(0, 0, At, B0); PG8_BAR; PG8_SCHED;
;       PG8_LDB(B1, 0, 1); PG8_STAGE(PG8_SB(0, 0), b2, voffB);
;       PG8_BAR; PG8_WAIT_L(0); PG8_MMA(0, 1, At, B1); PG8_BAR;
;       PG8_LDA(At, 0, 1); PG8_STAGE(PG8_SA(0, 0), a2, voffA);
;       PG8_BAR; PG8_WAIT_L(0); PG8_MMA(1, 0, At, B0); PG8_BAR; PG8_SCHED;
;       PG8_STAGE(PG8_SB(0, 1), b2 + hstepB, voffB);
;       PG8_WAIT_V(6); PG8_BAR; PG8_MMA(1, 1, At, B1); PG8_BAR;
;       PG8_LDB(B0, 1, 0); PG8_SCHED; PG8_LDA(At, 1, 0); PG8_STAGE(PG8_SA(0, 1), a2 + hstepA, voffA);
;       PG8_WAIT_L(8); PG8_BAR; PG8_WAIT_L(0); PG8_MMA(0, 0, At, B0); PG8_BAR; PG8_SCHED;
	s_waitcnt lgkmcnt(0)
	s_setprio 1
	v_mfma_f32_16x16x32_bf16 v[96:99], v[216:219], v[168:171], v[96:99]
	v_mfma_f32_16x16x32_bf16 v[96:99], v[220:223], v[172:175], v[96:99]
	v_mfma_f32_16x16x32_bf16 v[88:91], v[216:219], v[176:179], v[88:91]
	v_mfma_f32_16x16x32_bf16 v[88:91], v[220:223], v[180:183], v[88:91]
	v_mfma_f32_16x16x32_bf16 v[80:83], v[216:219], v[184:187], v[80:83]
	v_mfma_f32_16x16x32_bf16 v[80:83], v[220:223], v[188:191], v[80:83]
	v_mfma_f32_16x16x32_bf16 v[72:75], v[216:219], v[192:195], v[72:75]
	v_mfma_f32_16x16x32_bf16 v[72:75], v[220:223], v[212:215], v[72:75]
	v_mfma_f32_16x16x32_bf16 v[92:95], v[224:227], v[168:171], v[92:95]
	v_mfma_f32_16x16x32_bf16 v[92:95], v[228:231], v[172:175], v[92:95]
	v_mfma_f32_16x16x32_bf16 v[84:87], v[224:227], v[176:179], v[84:87]
	v_mfma_f32_16x16x32_bf16 v[84:87], v[228:231], v[180:183], v[84:87]
	v_mfma_f32_16x16x32_bf16 v[76:79], v[224:227], v[184:187], v[76:79]
	v_mfma_f32_16x16x32_bf16 v[76:79], v[228:231], v[188:191], v[76:79]
	v_mfma_f32_16x16x32_bf16 v[68:71], v[224:227], v[192:195], v[68:71]
	v_mfma_f32_16x16x32_bf16 v[68:71], v[228:231], v[212:215], v[68:71]
	s_mov_b32 m0, s26
	v_lshl_add_u64 v[232:233], s[18:19], 0, v[134:135]
	s_barrier
	s_setprio 0
	ds_read_b128 v[168:171], v146 offset:16384
	ds_read_b128 v[172:175], v146 offset:17408
	ds_read_b128 v[176:179], v146 offset:18432
	ds_read_b128 v[180:183], v146 offset:19456
	ds_read_b128 v[184:187], v146 offset:20480
	ds_read_b128 v[188:191], v146 offset:21504
	ds_read_b128 v[192:195], v146 offset:22528
	ds_read_b128 v[212:215], v146 offset:23552
	global_load_lds_dwordx4 v[232:233], off
	v_lshl_add_u64 v[234:235], s[18:19], 0, v[132:133]
	s_mov_b32 m0, s27
	s_nop 0
	global_load_lds_dwordx4 v[234:235], off
	s_barrier
	s_waitcnt lgkmcnt(0)
	s_setprio 1
	v_mfma_f32_16x16x32_bf16 v[64:67], v[148:151], v[168:171], v[64:67]
	v_mfma_f32_16x16x32_bf16 v[64:67], v[152:155], v[172:175], v[64:67]
	v_mfma_f32_16x16x32_bf16 v[56:59], v[148:151], v[176:179], v[56:59]
	v_mfma_f32_16x16x32_bf16 v[56:59], v[152:155], v[180:183], v[56:59]
	v_mfma_f32_16x16x32_bf16 v[48:51], v[148:151], v[184:187], v[48:51]
	v_mfma_f32_16x16x32_bf16 v[48:51], v[152:155], v[188:191], v[48:51]
	v_mfma_f32_16x16x32_bf16 v[40:43], v[148:151], v[192:195], v[40:43]
	v_mfma_f32_16x16x32_bf16 v[40:43], v[152:155], v[212:215], v[40:43]
	v_mfma_f32_16x16x32_bf16 v[60:63], v[156:159], v[168:171], v[60:63]
	v_mfma_f32_16x16x32_bf16 v[60:63], v[160:163], v[172:175], v[60:63]
	v_mfma_f32_16x16x32_bf16 v[52:55], v[156:159], v[176:179], v[52:55]
	v_mfma_f32_16x16x32_bf16 v[52:55], v[160:163], v[180:183], v[52:55]
	v_mfma_f32_16x16x32_bf16 v[44:47], v[156:159], v[184:187], v[44:47]
	v_mfma_f32_16x16x32_bf16 v[44:47], v[160:163], v[188:191], v[44:47]
	v_mfma_f32_16x16x32_bf16 v[36:39], v[156:159], v[192:195], v[36:39]
	v_mfma_f32_16x16x32_bf16 v[36:39], v[160:163], v[212:215], v[36:39]
	s_barrier
	s_setprio 0
	s_add_u32 s40, s16, 0x80000
	s_addc_u32 s41, s17, 0
	s_add_i32 s39, s42, s25
	v_lshl_add_u64 v[148:149], s[40:41], 0, v[2:3]
	s_mov_b32 m0, s39
	s_nop 0
	global_load_lds_dwordx4 v[148:149], off
	v_lshl_add_u64 v[148:149], s[40:41], 0, v[0:1]
	s_add_i32 m0, s39, 0x2000
	s_nop 0
	global_load_lds_dwordx4 v[148:149], off
	s_waitcnt vmcnt(6)
	s_barrier
	s_setprio 1
	v_mfma_f32_16x16x32_bf16 v[32:35], v[216:219], v[168:171], v[32:35]
	v_mfma_f32_16x16x32_bf16 v[32:35], v[220:223], v[172:175], v[32:35]
	v_mfma_f32_16x16x32_bf16 v[24:27], v[216:219], v[176:179], v[24:27]
	v_mfma_f32_16x16x32_bf16 v[24:27], v[220:223], v[180:183], v[24:27]
	v_mfma_f32_16x16x32_bf16 v[16:19], v[216:219], v[184:187], v[16:19]
	v_mfma_f32_16x16x32_bf16 v[16:19], v[220:223], v[188:191], v[16:19]
	v_mfma_f32_16x16x32_bf16 v[8:11], v[216:219], v[192:195], v[8:11]
	v_mfma_f32_16x16x32_bf16 v[8:11], v[220:223], v[212:215], v[8:11]
	v_mfma_f32_16x16x32_bf16 v[28:31], v[224:227], v[168:171], v[28:31]
	v_mfma_f32_16x16x32_bf16 v[28:31], v[228:231], v[172:175], v[28:31]
	v_mfma_f32_16x16x32_bf16 v[20:23], v[224:227], v[176:179], v[20:23]
	v_mfma_f32_16x16x32_bf16 v[20:23], v[228:231], v[180:183], v[20:23]
	v_mfma_f32_16x16x32_bf16 v[12:15], v[224:227], v[184:187], v[12:15]
	v_mfma_f32_16x16x32_bf16 v[12:15], v[228:231], v[188:191], v[12:15]
	v_mfma_f32_16x16x32_bf16 v[4:7], v[224:227], v[192:195], v[4:7]
	v_mfma_f32_16x16x32_bf16 v[4:7], v[228:231], v[212:215], v[4:7]
	s_add_i32 s39, 0, 0x18000
	v_add_u32_e32 v147, s39, v144
	s_barrier
	s_setprio 0
	ds_read_b128 v[148:151], v147
	ds_read_b128 v[152:155], v147 offset:1024
	ds_read_b128 v[156:159], v147 offset:2048
	ds_read_b128 v[160:163], v147 offset:3072
	s_add_u32 s18, s18, 0x80000
	s_addc_u32 s19, s19, 0
	s_mov_b32 m0, s28
	v_lshl_add_u64 v[216:217], s[18:19], 0, v[134:135]
	ds_read_b128 v[168:171], v146 offset:32768
	ds_read_b128 v[172:175], v146 offset:33792
	ds_read_b128 v[176:179], v146 offset:34816
	ds_read_b128 v[180:183], v146 offset:35840
	ds_read_b128 v[184:187], v146 offset:36864
	ds_read_b128 v[188:191], v146 offset:37888
	ds_read_b128 v[192:195], v146 offset:38912
	ds_read_b128 v[212:215], v146 offset:39936
	global_load_lds_dwordx4 v[216:217], off
	v_lshl_add_u64 v[216:217], s[18:19], 0, v[132:133]
	s_mov_b32 m0, s29
	s_nop 0
	global_load_lds_dwordx4 v[216:217], off
	s_waitcnt lgkmcnt(8)
	s_barrier
; #define PG8_WAIT_V(n) asm volatile("s_waitcnt vmcnt(" #n ")" ::: "memory")
; #define PG8_WAIT_L(n) asm volatile("s_waitcnt lgkmcnt(" #n ")" ::: "memory")
; #define PG8_BAR __builtin_amdgcn_s_barrier()
; #define PG8_SCHED __builtin_amdgcn_sched_barrier(0)
; template <class Epi, class AddrA, class AddrB>
; __device__ __forceinline__ void gemm_phase(const Sched S, const int lda, const int ldb, const int K, const AddrA addrA,
;                                            const AddrB addrB, const Epi E) {
;     ...
;       PG8_WAIT_V(6); PG8_BAR; PG8_MMA(1, 1, At, B1); PG8_BAR;
;       PG8_LDB(B0, 1, 0); PG8_SCHED; PG8_LDA(At, 1, 0); PG8_STAGE(PG8_SA(0, 1), a2 + hstepA, voffA);
;       PG8_WAIT_L(8); PG8_BAR; PG8_WAIT_L(0); PG8_MMA(0, 0, At, B0); PG8_BAR; PG8_SCHED;
;       PG8_LDB(B1, 1, 1); PG8_STAGE(PG8_SB(1, 0), b3, voffB);
;       PG8_BAR; PG8_WAIT_L(0); PG8_MMA(0, 1, At, B1); PG8_BAR;
;       PG8_LDA(At, 1, 1); PG8_STAGE(PG8_SA(1, 0), a3, voffA);
;       PG8_BAR; PG8_WAIT_L(0); PG8_MMA(1, 0, At, B0); PG8_BAR; PG8_SCHED;
;       PG8_STAGE(PG8_SB(1, 1), b3 + hstepB, voffB);
;       PG8_WAIT_V(6); PG8_BAR; PG8_MMA(1, 1, At, B1); PG8_BAR;
	s_waitcnt lgkmcnt(0)
	s_setprio 1
	v_mfma_f32_16x16x32_bf16 v[128:131], v[148:151], v[168:171], v[128:131]
	v_mfma_f32_16x16x32_bf16 v[128:131], v[152:155], v[172:175], v[128:131]
	v_mfma_f32_16x16x32_bf16 v[120:123], v[148:151], v[176:179], v[120:123]
	v_mfma_f32_16x16x32_bf16 v[120:123], v[152:155], v[180:183], v[120:123]
	v_mfma_f32_16x16x32_bf16 v[112:115], v[148:151], v[184:187], v[112:115]
	v_mfma_f32_16x16x32_bf16 v[112:115], v[152:155], v[188:191], v[112:115]
	v_mfma_f32_16x16x32_bf16 v[104:107], v[148:151], v[192:195], v[104:107]
	v_mfma_f32_16x16x32_bf16 v[104:107], v[152:155], v[212:215], v[104:107]
	v_mfma_f32_16x16x32_bf16 v[124:127], v[156:159], v[168:171], v[124:127]
	v_mfma_f32_16x16x32_bf16 v[124:127], v[160:163], v[172:175], v[124:127]
	v_mfma_f32_16x16x32_bf16 v[116:119], v[156:159], v[176:179], v[116:119]
	v_mfma_f32_16x16x32_bf16 v[116:119], v[160:163], v[180:183], v[116:119]
	v_mfma_f32_16x16x32_bf16 v[108:111], v[156:159], v[184:187], v[108:111]
	v_mfma_f32_16x16x32_bf16 v[108:111], v[160:163], v[188:191], v[108:111]
	v_mfma_f32_16x16x32_bf16 v[100:103], v[156:159], v[192:195], v[100:103]
	v_mfma_f32_16x16x32_bf16 v[100:103], v[160:163], v[212:215], v[100:103]
	s_barrier
	s_setprio 0
	s_add_i32 s18, 0, 0x1c000
	s_add_i32 s19, s39, s25
	v_add_u32_e32 v147, s18, v144
	v_lshl_add_u64 v[142:143], v[142:143], 0, s[52:53]
	s_mov_b32 m0, s19
	ds_read_b128 v[216:219], v147
	ds_read_b128 v[220:223], v147 offset:1024
	ds_read_b128 v[224:227], v147 offset:2048
	ds_read_b128 v[228:231], v147 offset:3072
	global_load_lds_dwordx4 v[142:143], off
	v_lshl_add_u64 v[142:143], v[196:197], 0, s[52:53]
	s_add_i32 m0, s19, 0x2000
	s_nop 0
	global_load_lds_dwordx4 v[142:143], off
	s_barrier
	s_waitcnt lgkmcnt(0)
	s_setprio 1
	v_mfma_f32_16x16x32_bf16 v[96:99], v[216:219], v[168:171], v[96:99]
	v_mfma_f32_16x16x32_bf16 v[96:99], v[220:223], v[172:175], v[96:99]
	v_mfma_f32_16x16x32_bf16 v[88:91], v[216:219], v[176:179], v[88:91]
	v_mfma_f32_16x16x32_bf16 v[88:91], v[220:223], v[180:183], v[88:91]
	v_mfma_f32_16x16x32_bf16 v[80:83], v[216:219], v[184:187], v[80:83]
	v_mfma_f32_16x16x32_bf16 v[80:83], v[220:223], v[188:191], v[80:83]
	v_mfma_f32_16x16x32_bf16 v[72:75], v[216:219], v[192:195], v[72:75]
	v_mfma_f32_16x16x32_bf16 v[72:75], v[220:223], v[212:215], v[72:75]
	v_mfma_f32_16x16x32_bf16 v[92:95], v[224:227], v[168:171], v[92:95]
	v_mfma_f32_16x16x32_bf16 v[92:95], v[228:231], v[172:175], v[92:95]
	v_mfma_f32_16x16x32_bf16 v[84:87], v[224:227], v[176:179], v[84:87]
	v_mfma_f32_16x16x32_bf16 v[84:87], v[228:231], v[180:183], v[84:87]
	v_mfma_f32_16x16x32_bf16 v[76:79], v[224:227], v[184:187], v[76:79]
	v_mfma_f32_16x16x32_bf16 v[76:79], v[228:231], v[188:191], v[76:79]
	v_mfma_f32_16x16x32_bf16 v[68:71], v[224:227], v[192:195], v[68:71]
	v_mfma_f32_16x16x32_bf16 v[68:71], v[228:231], v[212:215], v[68:71]
	s_mov_b32 m0, s30
	v_lshl_add_u64 v[142:143], v[232:233], 0, s[52:53]
	s_barrier
	s_setprio 0
	ds_read_b128 v[168:171], v146 offset:49152
	ds_read_b128 v[172:175], v146 offset:50176
	ds_read_b128 v[176:179], v146 offset:51200
	ds_read_b128 v[180:183], v146 offset:52224
	ds_read_b128 v[184:187], v146 offset:53248
	ds_read_b128 v[188:191], v146 offset:54272
	ds_read_b128 v[192:195], v146 offset:55296
	ds_read_b128 v[212:215], v146 offset:56320
	global_load_lds_dwordx4 v[142:143], off
	v_lshl_add_u64 v[142:143], v[234:235], 0, s[52:53]
	s_mov_b32 m0, s31
	s_nop 0
	global_load_lds_dwordx4 v[142:143], off
	s_barrier
	s_waitcnt lgkmcnt(0)
	s_setprio 1
	v_mfma_f32_16x16x32_bf16 v[64:67], v[148:151], v[168:171], v[64:67]
	v_mfma_f32_16x16x32_bf16 v[64:67], v[152:155], v[172:175], v[64:67]
	v_mfma_f32_16x16x32_bf16 v[56:59], v[148:151], v[176:179], v[56:59]
	v_mfma_f32_16x16x32_bf16 v[56:59], v[152:155], v[180:183], v[56:59]
	v_mfma_f32_16x16x32_bf16 v[48:51], v[148:151], v[184:187], v[48:51]
	v_mfma_f32_16x16x32_bf16 v[48:51], v[152:155], v[188:191], v[48:51]
	v_mfma_f32_16x16x32_bf16 v[40:43], v[148:151], v[192:195], v[40:43]
	v_mfma_f32_16x16x32_bf16 v[40:43], v[152:155], v[212:215], v[40:43]
	v_mfma_f32_16x16x32_bf16 v[60:63], v[156:159], v[168:171], v[60:63]
	v_mfma_f32_16x16x32_bf16 v[60:63], v[160:163], v[172:175], v[60:63]
	v_mfma_f32_16x16x32_bf16 v[52:55], v[156:159], v[176:179], v[52:55]
	v_mfma_f32_16x16x32_bf16 v[52:55], v[160:163], v[180:183], v[52:55]
	v_mfma_f32_16x16x32_bf16 v[44:47], v[156:159], v[184:187], v[44:47]
	v_mfma_f32_16x16x32_bf16 v[44:47], v[160:163], v[188:191], v[44:47]
	v_mfma_f32_16x16x32_bf16 v[36:39], v[156:159], v[192:195], v[36:39]
	v_mfma_f32_16x16x32_bf16 v[36:39], v[160:163], v[212:215], v[36:39]
	s_barrier
	s_setprio 0
	s_add_u32 s16, s16, 0x80080
	s_addc_u32 s17, s17, 0
	s_add_i32 s18, s18, s25
	v_lshl_add_u64 v[142:143], s[16:17], 0, v[2:3]
	s_mov_b32 m0, s18
	s_nop 0
	global_load_lds_dwordx4 v[142:143], off
	v_lshl_add_u64 v[142:143], s[16:17], 0, v[0:1]
	s_add_i32 m0, s18, 0x2000
	s_nop 0
	global_load_lds_dwordx4 v[142:143], off
	s_waitcnt vmcnt(6)
	s_barrier
	s_setprio 1
	v_mfma_f32_16x16x32_bf16 v[32:35], v[216:219], v[168:171], v[32:35]
	v_mfma_f32_16x16x32_bf16 v[32:35], v[220:223], v[172:175], v[32:35]
	v_mfma_f32_16x16x32_bf16 v[24:27], v[216:219], v[176:179], v[24:27]
	v_mfma_f32_16x16x32_bf16 v[24:27], v[220:223], v[180:183], v[24:27]
	v_mfma_f32_16x16x32_bf16 v[16:19], v[216:219], v[184:187], v[16:19]
	v_mfma_f32_16x16x32_bf16 v[16:19], v[220:223], v[188:191], v[16:19]
	v_mfma_f32_16x16x32_bf16 v[8:11], v[216:219], v[192:195], v[8:11]
	v_mfma_f32_16x16x32_bf16 v[8:11], v[220:223], v[212:215], v[8:11]
	v_mfma_f32_16x16x32_bf16 v[28:31], v[224:227], v[168:171], v[28:31]
	v_mfma_f32_16x16x32_bf16 v[28:31], v[228:231], v[172:175], v[28:31]
	v_mfma_f32_16x16x32_bf16 v[20:23], v[224:227], v[176:179], v[20:23]
	v_mfma_f32_16x16x32_bf16 v[20:23], v[228:231], v[180:183], v[20:23]
	v_mfma_f32_16x16x32_bf16 v[12:15], v[224:227], v[184:187], v[12:15]
	v_mfma_f32_16x16x32_bf16 v[12:15], v[228:231], v[188:191], v[12:15]
	v_mfma_f32_16x16x32_bf16 v[4:7], v[224:227], v[192:195], v[4:7]
	v_mfma_f32_16x16x32_bf16 v[4:7], v[228:231], v[212:215], v[4:7]
	s_add_i32 s38, s38, 2
	s_add_u32 s36, s36, 0x100
	s_addc_u32 s37, s37, 0
	s_add_u32 s14, s14, 0x100
	s_addc_u32 s15, s15, 0
	s_cmp_gt_u32 s38, 29
	s_barrier
;   __device__ __forceinline__ void operator()(EPI_ARGS) const {
;     const size_t row0 = (size_t)u.pm * 256 + wr * 64 + fr;
;     const int col0 = u.pn * 256 + wc * 32 + 8 * fq;
; #pragma unroll
;     for (int ai = 0; ai < 2; ++ai)
; #pragma unroll
;       for (int bj = 0; bj < 2; ++bj) {
;         f32x4 x0[4], x1[4];
; #pragma unroll
;         for (int m = 0; m < 4; ++m) {
;           const size_t o = (row0 + ai * HALF + m * 16) * DM + col0 + bj * HALF;
;           x0[m] = *(const f32x4*)(xres + o);
;           x1[m] = *(const f32x4*)(xres + o + 4);
;         }
;         __builtin_amdgcn_sched_barrier(0);
; #pragma unroll
;         for (int m = 0; m < 4; ++m) {
;           const size_t o = (row0 + ai * HALF + m * 16) * DM + col0 + bj * HALF;
;           *(f32x4*)(hbuf + o) = acc[ai][bj][m][0] + x0[m] * ALPHA;
;           *(f32x4*)(hbuf + o + 4) = acc[ai][bj][m][1] + x1[m] * ALPHA;
;         }
	s_setprio 0
	s_cbranch_scc0 .LBB0_619
	s_ashr_i32 s13, s12, 31
	v_lshl_or_b32 v142, s34, 8, v145
	v_ashrrev_i32_e32 v143, 31, v142
	s_lshl_b64 s[12:13], s[12:13], 21
	v_lshlrev_b64 v[184:185], 2, v[142:143]
	v_lshl_add_u64 v[188:189], s[12:13], 0, v[136:137]
	v_lshl_add_u64 v[186:187], s[0:1], 0, v[184:185]
	v_or_b32_e32 v190, 0x20000, v188
	v_mov_b32_e32 v191, v189
	v_or_b32_e32 v192, 0x40000, v188
	v_mov_b32_e32 v193, v189
	v_or_b32_e32 v194, 0x60000, v188
	v_mov_b32_e32 v195, v189
	v_lshl_add_u64 v[142:143], v[186:187], 0, v[188:189]
	v_lshl_add_u64 v[160:161], v[186:187], 0, v[190:191]
	v_lshl_add_u64 v[172:173], v[186:187], 0, v[192:193]
	v_lshl_add_u64 v[180:181], v[186:187], 0, v[194:195]
	flat_load_dwordx4 v[148:151], v[142:143]
	flat_load_dwordx4 v[152:155], v[142:143] offset:16
	flat_load_dwordx4 v[156:159], v[160:161]
	s_nop 0
	flat_load_dwordx4 v[160:163], v[160:161] offset:16
	s_nop 0
	flat_load_dwordx4 v[168:171], v[172:173]
	s_nop 0
	flat_load_dwordx4 v[172:175], v[172:173] offset:16
	s_nop 0
	flat_load_dwordx4 v[176:179], v[180:181]
	s_nop 0
	flat_load_dwordx4 v[180:183], v[180:181] offset:16
	v_lshl_add_u64 v[184:185], s[48:49], 0, v[184:185]
	s_mov_b32 s14, 0x3fb504f3
	s_waitcnt vmcnt(0) lgkmcnt(0)
	v_pk_fma_f32 v[148:149], v[148:149], s[14:15], v[128:129] op_sel_hi:[1,0,1]
	v_lshl_add_u64 v[128:129], v[184:185], 0, v[188:189]
	v_pk_fma_f32 v[126:127], v[154:155], s[14:15], v[126:127] op_sel_hi:[1,0,1]
	v_pk_fma_f32 v[124:125], v[152:153], s[14:15], v[124:125] op_sel_hi:[1,0,1]
	global_store_dwordx4 v[128:129], v[124:127], off offset:16
	v_pk_fma_f32 v[118:119], v[162:163], s[14:15], v[118:119] op_sel_hi:[1,0,1]
	v_pk_fma_f32 v[116:117], v[160:161], s[14:15], v[116:117] op_sel_hi:[1,0,1]
	v_lshl_add_u64 v[124:125], v[184:185], 0, v[190:191]
	v_pk_fma_f32 v[122:123], v[158:159], s[14:15], v[122:123] op_sel_hi:[1,0,1]
	v_pk_fma_f32 v[120:121], v[156:157], s[14:15], v[120:121] op_sel_hi:[1,0,1]
	global_store_dwordx4 v[124:125], v[116:119], off offset:16
	v_pk_fma_f32 v[110:111], v[174:175], s[14:15], v[110:111] op_sel_hi:[1,0,1]
	v_pk_fma_f32 v[108:109], v[172:173], s[14:15], v[108:109] op_sel_hi:[1,0,1]
	v_lshl_add_u64 v[116:117], v[184:185], 0, v[192:193]
	s_mov_b64 s[12:13], 0x200
	v_pk_fma_f32 v[150:151], v[150:151], s[14:15], v[130:131] op_sel_hi:[1,0,1]
	global_store_dwordx4 v[124:125], v[120:123], off
	v_pk_fma_f32 v[114:115], v[170:171], s[14:15], v[114:115] op_sel_hi:[1,0,1]
	v_pk_fma_f32 v[112:113], v[168:169], s[14:15], v[112:113] op_sel_hi:[1,0,1]
	global_store_dwordx4 v[116:117], v[108:111], off offset:16
	v_pk_fma_f32 v[106:107], v[178:179], s[14:15], v[106:107] op_sel_hi:[1,0,1]
	v_pk_fma_f32 v[104:105], v[176:177], s[14:15], v[104:105] op_sel_hi:[1,0,1]
	v_lshl_add_u64 v[108:109], v[184:185], 0, v[194:195]
	v_pk_fma_f32 v[102:103], v[182:183], s[14:15], v[102:103] op_sel_hi:[1,0,1]
	v_pk_fma_f32 v[100:101], v[180:181], s[14:15], v[100:101] op_sel_hi:[1,0,1]
	v_lshl_add_u64 v[124:125], v[186:187], 0, s[12:13]
	global_store_dwordx4 v[128:129], v[148:151], off
	global_store_dwordx4 v[116:117], v[112:115], off
	global_store_dwordx4 v[108:109], v[104:107], off
	global_store_dwordx4 v[108:109], v[100:103], off offset:16
	v_lshl_add_u64 v[112:113], v[124:125], 0, v[190:191]
	v_lshl_add_u64 v[120:121], v[124:125], 0, v[192:193]
	v_lshl_add_u64 v[130:131], v[124:125], 0, v[194:195]
	flat_load_dwordx4 v[100:103], v[142:143] offset:512
	flat_load_dwordx4 v[104:107], v[142:143] offset:528
	flat_load_dwordx4 v[108:111], v[112:113]
	s_nop 0
	flat_load_dwordx4 v[112:115], v[112:113] offset:16
	s_nop 0
	flat_load_dwordx4 v[116:119], v[120:121]
	s_nop 0
	flat_load_dwordx4 v[120:123], v[120:121] offset:16
	s_nop 0
	flat_load_dwordx4 v[124:127], v[130:131]
	flat_load_dwordx4 v[148:151], v[130:131] offset:16
	s_mov_b32 s3, 0x100000
	s_waitcnt vmcnt(0) lgkmcnt(0)
	v_pk_fma_f32 v[96:97], v[100:101], s[14:15], v[96:97] op_sel_hi:[1,0,1]
	v_add_co_u32_e32 v100, vcc, s3, v142
	s_mov_b32 s5, 0x120000
	s_nop 0
	v_addc_co_u32_e32 v101, vcc, 0, v143, vcc
	v_pk_fma_f32 v[98:99], v[102:103], s[14:15], v[98:99] op_sel_hi:[1,0,1]
	v_add_co_u32_e32 v102, vcc, s5, v142
	v_lshl_add_u64 v[130:131], v[184:185], 0, s[12:13]
	v_pk_fma_f32 v[94:95], v[106:107], s[14:15], v[94:95] op_sel_hi:[1,0,1]
	v_pk_fma_f32 v[92:93], v[104:105], s[14:15], v[92:93] op_sel_hi:[1,0,1]
	v_addc_co_u32_e32 v103, vcc, 0, v143, vcc
	s_mov_b32 s12, 0x140000
	global_store_dwordx4 v[128:129], v[92:95], off offset:528
	v_pk_fma_f32 v[86:87], v[114:115], s[14:15], v[86:87] op_sel_hi:[1,0,1]
	v_pk_fma_f32 v[84:85], v[112:113], s[14:15], v[84:85] op_sel_hi:[1,0,1]
	v_lshl_add_u64 v[92:93], v[130:131], 0, v[190:191]
	v_add_co_u32_e32 v104, vcc, s12, v142
	global_store_dwordx4 v[92:93], v[84:87], off offset:16
	v_pk_fma_f32 v[78:79], v[122:123], s[14:15], v[78:79] op_sel_hi:[1,0,1]
	v_pk_fma_f32 v[76:77], v[120:121], s[14:15], v[76:77] op_sel_hi:[1,0,1]
	v_lshl_add_u64 v[84:85], v[130:131], 0, v[192:193]
	v_addc_co_u32_e32 v105, vcc, 0, v143, vcc
	s_mov_b32 s13, 0x160000
	v_pk_fma_f32 v[90:91], v[110:111], s[14:15], v[90:91] op_sel_hi:[1,0,1]
	v_pk_fma_f32 v[88:89], v[108:109], s[14:15], v[88:89] op_sel_hi:[1,0,1]
	v_pk_fma_f32 v[82:83], v[118:119], s[14:15], v[82:83] op_sel_hi:[1,0,1]
	v_pk_fma_f32 v[80:81], v[116:117], s[14:15], v[80:81] op_sel_hi:[1,0,1]
	global_store_dwordx4 v[84:85], v[76:79], off offset:16
	v_pk_fma_f32 v[74:75], v[126:127], s[14:15], v[74:75] op_sel_hi:[1,0,1]
	v_pk_fma_f32 v[72:73], v[124:125], s[14:15], v[72:73] op_sel_hi:[1,0,1]
	v_lshl_add_u64 v[76:77], v[130:131], 0, v[194:195]
	v_pk_fma_f32 v[70:71], v[150:151], s[14:15], v[70:71] op_sel_hi:[1,0,1]
	v_pk_fma_f32 v[68:69], v[148:149], s[14:15], v[68:69] op_sel_hi:[1,0,1]
	s_mov_b64 s[16:17], 0x100000
	s_mov_b64 s[18:19], 0x120000
	s_mov_b64 s[34:35], 0x140000
	s_mov_b64 s[36:37], 0x160000
	v_add_co_u32_e32 v106, vcc, s13, v142
	global_store_dwordx4 v[128:129], v[96:99], off offset:512
	global_store_dwordx4 v[92:93], v[88:91], off
	global_store_dwordx4 v[84:85], v[80:83], off
	global_store_dwordx4 v[76:77], v[72:75], off
	global_store_dwordx4 v[76:77], v[68:71], off offset:16
	v_lshl_add_u64 v[80:81], v[142:143], 0, s[18:19]
	v_lshl_add_u64 v[72:73], v[142:143], 0, s[16:17]
	v_lshl_add_u64 v[88:89], v[142:143], 0, s[34:35]
	v_lshl_add_u64 v[96:97], v[142:143], 0, s[36:37]
	v_addc_co_u32_e32 v107, vcc, 0, v143, vcc
	flat_load_dwordx4 v[68:71], v[100:101]
	s_nop 0
	flat_load_dwordx4 v[72:75], v[72:73] offset:16
	s_nop 0
	flat_load_dwordx4 v[76:79], v[102:103]
	s_nop 0
	flat_load_dwordx4 v[80:83], v[80:81] offset:16
	s_nop 0
	flat_load_dwordx4 v[84:87], v[104:105]
	s_nop 0
	flat_load_dwordx4 v[88:91], v[88:89] offset:16
	s_nop 0
	flat_load_dwordx4 v[92:95], v[106:107]
	s_nop 0
	flat_load_dwordx4 v[96:99], v[96:97] offset:16
	s_waitcnt vmcnt(0) lgkmcnt(0)
; template <class Epi, class AddrA, class AddrB>
; __device__ __forceinline__ void gemm_phase(const Sched S, const int lda, const int ldb, const int K, const AddrA addrA,
;                                            const AddrB addrB, const Epi E) {
;     ...
;     E(acc, cur, wr, wc, fr, fq);
;     if (!has_next) break;
;   __device__ __forceinline__ void operator()(EPI_ARGS) const {
;     ...
; #pragma unroll
;         for (int m = 0; m < 4; ++m) {
;           const size_t o = (row0 + ai * HALF + m * 16) * DM + col0 + bj * HALF;
;           x0[m] = *(const f32x4*)(xres + o);
;           x1[m] = *(const f32x4*)(xres + o + 4);
;         }
;         __builtin_amdgcn_sched_barrier(0);
; #pragma unroll
;         for (int m = 0; m < 4; ++m) {
;           const size_t o = (row0 + ai * HALF + m * 16) * DM + col0 + bj * HALF;
;           *(f32x4*)(hbuf + o) = acc[ai][bj][m][0] + x0[m] * ALPHA;
;           *(f32x4*)(hbuf + o + 4) = acc[ai][bj][m][1] + x1[m] * ALPHA;
;         }
;       }
	v_pk_fma_f32 v[66:67], v[70:71], s[14:15], v[66:67] op_sel_hi:[1,0,1]
	v_add_co_u32_e32 v70, vcc, s3, v128
	v_pk_fma_f32 v[64:65], v[68:69], s[14:15], v[64:65] op_sel_hi:[1,0,1]
	v_lshl_add_u64 v[68:69], v[128:129], 0, s[16:17]
	v_addc_co_u32_e32 v71, vcc, 0, v129, vcc
	v_pk_fma_f32 v[62:63], v[74:75], s[14:15], v[62:63] op_sel_hi:[1,0,1]
	v_pk_fma_f32 v[60:61], v[72:73], s[14:15], v[60:61] op_sel_hi:[1,0,1]
	global_store_dwordx4 v[68:69], v[60:63], off offset:16
	v_add_co_u32_e32 v68, vcc, s5, v128
	s_nop 0
	v_lshl_add_u64 v[60:61], v[128:129], 0, s[18:19]
	v_addc_co_u32_e32 v69, vcc, 0, v129, vcc
	v_add_co_u32_e32 v72, vcc, s12, v128
	v_pk_fma_f32 v[54:55], v[82:83], s[14:15], v[54:55] op_sel_hi:[1,0,1]
	v_pk_fma_f32 v[52:53], v[80:81], s[14:15], v[52:53] op_sel_hi:[1,0,1]
	v_addc_co_u32_e32 v73, vcc, 0, v129, vcc
	global_store_dwordx4 v[60:61], v[52:55], off offset:16
	v_pk_fma_f32 v[46:47], v[90:91], s[14:15], v[46:47] op_sel_hi:[1,0,1]
	v_pk_fma_f32 v[44:45], v[88:89], s[14:15], v[44:45] op_sel_hi:[1,0,1]
	v_lshl_add_u64 v[52:53], v[128:129], 0, s[34:35]
	v_add_co_u32_e32 v74, vcc, s13, v128
	v_pk_fma_f32 v[58:59], v[78:79], s[14:15], v[58:59] op_sel_hi:[1,0,1]
	v_pk_fma_f32 v[56:57], v[76:77], s[14:15], v[56:57] op_sel_hi:[1,0,1]
	v_pk_fma_f32 v[50:51], v[86:87], s[14:15], v[50:51] op_sel_hi:[1,0,1]
	v_pk_fma_f32 v[48:49], v[84:85], s[14:15], v[48:49] op_sel_hi:[1,0,1]
	global_store_dwordx4 v[52:53], v[44:47], off offset:16
	v_pk_fma_f32 v[42:43], v[94:95], s[14:15], v[42:43] op_sel_hi:[1,0,1]
	v_pk_fma_f32 v[40:41], v[92:93], s[14:15], v[40:41] op_sel_hi:[1,0,1]
	v_lshl_add_u64 v[44:45], v[128:129], 0, s[36:37]
	v_addc_co_u32_e32 v75, vcc, 0, v129, vcc
	v_pk_fma_f32 v[38:39], v[98:99], s[14:15], v[38:39] op_sel_hi:[1,0,1]
	v_pk_fma_f32 v[36:37], v[96:97], s[14:15], v[36:37] op_sel_hi:[1,0,1]
	s_mov_b64 s[12:13], 0x100200
	s_mov_b64 s[16:17], 0x120200
	s_mov_b64 s[18:19], 0x140200
	s_mov_b64 s[34:35], 0x160200
	global_store_dwordx4 v[70:71], v[64:67], off
	global_store_dwordx4 v[68:69], v[56:59], off
	global_store_dwordx4 v[72:73], v[48:51], off
	global_store_dwordx4 v[74:75], v[40:43], off
	global_store_dwordx4 v[44:45], v[36:39], off offset:16
	v_lshl_add_u64 v[44:45], v[142:143], 0, s[12:13]
	v_lshl_add_u64 v[48:49], v[142:143], 0, s[16:17]
	v_lshl_add_u64 v[60:61], v[142:143], 0, s[18:19]
	v_lshl_add_u64 v[64:65], v[142:143], 0, s[34:35]
	flat_load_dwordx4 v[36:39], v[100:101] offset:512
	flat_load_dwordx4 v[40:43], v[102:103] offset:512
	s_nop 0
	flat_load_dwordx4 v[44:47], v[44:45] offset:16
	s_nop 0
	flat_load_dwordx4 v[48:51], v[48:49] offset:16
	s_nop 0
	flat_load_dwordx4 v[52:55], v[104:105] offset:512
	flat_load_dwordx4 v[56:59], v[106:107] offset:512
	s_nop 0
	flat_load_dwordx4 v[60:63], v[60:61] offset:16
	s_nop 0
	flat_load_dwordx4 v[64:67], v[64:65] offset:16
	s_waitcnt vmcnt(0) lgkmcnt(0)
	v_pk_fma_f32 v[32:33], v[36:37], s[14:15], v[32:33] op_sel_hi:[1,0,1]
	v_lshl_add_u64 v[36:37], v[128:129], 0, s[12:13]
	v_pk_fma_f32 v[30:31], v[46:47], s[14:15], v[30:31] op_sel_hi:[1,0,1]
	v_pk_fma_f32 v[28:29], v[44:45], s[14:15], v[28:29] op_sel_hi:[1,0,1]
	global_store_dwordx4 v[36:37], v[28:31], off offset:16
	v_pk_fma_f32 v[22:23], v[50:51], s[14:15], v[22:23] op_sel_hi:[1,0,1]
	v_pk_fma_f32 v[20:21], v[48:49], s[14:15], v[20:21] op_sel_hi:[1,0,1]
	v_lshl_add_u64 v[28:29], v[128:129], 0, s[16:17]
	global_store_dwordx4 v[28:29], v[20:23], off offset:16
	v_pk_fma_f32 v[14:15], v[62:63], s[14:15], v[14:15] op_sel_hi:[1,0,1]
	v_pk_fma_f32 v[12:13], v[60:61], s[14:15], v[12:13] op_sel_hi:[1,0,1]
	v_lshl_add_u64 v[20:21], v[128:129], 0, s[18:19]
	v_pk_fma_f32 v[34:35], v[38:39], s[14:15], v[34:35] op_sel_hi:[1,0,1]
	v_pk_fma_f32 v[26:27], v[42:43], s[14:15], v[26:27] op_sel_hi:[1,0,1]
	v_pk_fma_f32 v[24:25], v[40:41], s[14:15], v[24:25] op_sel_hi:[1,0,1]
	v_pk_fma_f32 v[18:19], v[54:55], s[14:15], v[18:19] op_sel_hi:[1,0,1]
	v_pk_fma_f32 v[16:17], v[52:53], s[14:15], v[16:17] op_sel_hi:[1,0,1]
	global_store_dwordx4 v[20:21], v[12:15], off offset:16
	v_pk_fma_f32 v[10:11], v[58:59], s[14:15], v[10:11] op_sel_hi:[1,0,1]
	v_pk_fma_f32 v[8:9], v[56:57], s[14:15], v[8:9] op_sel_hi:[1,0,1]
	v_lshl_add_u64 v[12:13], v[128:129], 0, s[34:35]
	v_pk_fma_f32 v[6:7], v[66:67], s[14:15], v[6:7] op_sel_hi:[1,0,1]
	v_pk_fma_f32 v[4:5], v[64:65], s[14:15], v[4:5] op_sel_hi:[1,0,1]
	s_and_b64 vcc, exec, s[6:7]
	s_mov_b32 s34, s4
	s_mov_b32 s12, s2
	s_mov_b64 s[14:15], s[10:11]
	s_mov_b64 s[16:17], s[8:9]
	global_store_dwordx4 v[70:71], v[32:35], off offset:512
	global_store_dwordx4 v[68:69], v[24:27], off offset:512
	global_store_dwordx4 v[72:73], v[16:19], off offset:512
	global_store_dwordx4 v[74:75], v[8:11], off offset:512
	global_store_dwordx4 v[12:13], v[4:7], off offset:16
	s_cbranch_vccz .LBB0_616
	s_waitcnt vmcnt(0)
	s_cmpk_gt_u32 s20, 0xff
	s_cbranch_scc1 .LBB0_623
	s_barrier
